# v81 + write-through (sc1) policy on the plain 16-byte epilogue stores of the GEMM phases P1 P3 P4 P5 P7 P8 P9, so the grid barrier L2 write-back has little to flush
# speedup vs baseline: 1.0098x; 1.0098x over previous
.LBB0_160:
	v_lshlrev_b64 v[172:173], 10, v[148:149]
	v_cvt_pk_bf16_f32 v126, v126, v127
	v_cvt_pk_bf16_f32 v127, v128, v129
	v_cvt_pk_bf16_f32 v128, v122, v123
	v_cvt_pk_bf16_f32 v129, v124, v125
	v_mov_b32_e32 v124, v152
	v_mov_b32_e32 v125, v152
	v_mov_b32_e32 v153, v152
	v_lshl_add_u64 v[172:173], s[94:95], 0, v[172:173]
	v_lshlrev_b32_e32 v138, 1, v162
	v_pk_mul_f32 v[120:121], v[120:121], v[124:125]
	v_pk_mul_f32 v[116:117], v[116:117], v[124:125]
	v_cndmask_b32_e64 v124, 0, 1, s[8:9]
	v_lshl_add_u64 v[122:123], v[172:173], 0, v[138:139]
	v_pk_mul_f32 v[118:119], v[118:119], v[152:153]
	v_pk_mul_f32 v[114:115], v[114:115], v[152:153]
	v_cmp_ne_u32_e64 s[12:13], 1, v124
	s_andn2_b64 vcc, exec, s[8:9]
	s_mov_b64 s[8:9], -1
	global_store_dwordx4 v[122:123], v[126:129], off sc1
	s_cbranch_vccnz .LBB0_164
	s_and_b64 vcc, exec, s[6:7]
	s_cbranch_vccnz .LBB0_163
	v_lshlrev_b32_e32 v124, 2, v162
	v_mov_b32_e32 v125, v139
	v_lshl_add_u64 v[124:125], v[150:151], 0, v[124:125]
	global_store_dwordx4 v[124:125], v[118:121], off offset:512 nt
	global_store_dwordx4 v[124:125], v[114:117], off offset:528 nt

.LBB0_167:
	s_and_b64 vcc, exec, s[8:9]
	v_cvt_pk_bf16_f32 v118, v118, v119
	v_cvt_pk_bf16_f32 v119, v120, v121
	v_cvt_pk_bf16_f32 v120, v114, v115
	v_cvt_pk_bf16_f32 v121, v116, v117
	global_store_dwordx4 v[122:123], v[118:121], off offset:256 sc1
	s_cbranch_vccnz .LBB0_171
	v_and_b32_e32 v115, 64, v161
	v_xor_b32_e32 v114, 16, v161
	v_add_u32_e32 v115, 64, v115
	v_cmp_lt_i32_e32 vcc, v114, v115
	v_xor_b32_e32 v116, 32, v161
	s_nop 0
	v_cndmask_b32_e32 v114, v161, v114, vcc
	v_lshlrev_b32_e32 v114, 2, v114
	ds_bpermute_b32 v114, v114, v171
	v_cmp_lt_i32_e32 vcc, v116, v115
	s_waitcnt lgkmcnt(0)
	v_add_f32_e32 v114, v171, v114
	v_cndmask_b32_e32 v115, v161, v116, vcc
	v_lshlrev_b32_e32 v115, 2, v115
	ds_bpermute_b32 v115, v115, v114
	s_and_saveexec_b64 vcc, s[0:1]
	s_cbranch_execz .LBB0_170
	s_waitcnt lgkmcnt(0)
	v_add_f32_e32 v114, v114, v115
	v_fma_f32 v114, v114, s57, 0.5
	v_trunc_f32_e32 v114, v114
	v_mul_f32_e32 v115, 0x2f800000, v114
	v_floor_f32_e32 v115, v115
	v_fmac_f32_e32 v114, 0xcf800000, v115
	v_cvt_u32_f32_e32 v114, v114
	v_cvt_u32_f32_e32 v115, v115
	v_lshl_add_u64 v[116:117], v[148:149], 3, s[62:63]
	global_atomic_add_x2 v[116:117], v[114:115], off

.LBB0_177:
	v_ashrrev_i32_e32 v115, 31, v114
	v_lshlrev_b64 v[122:123], 10, v[114:115]
	v_mov_b32_e32 v119, v118
	v_lshl_add_u64 v[122:123], s[94:95], 0, v[122:123]
	v_cvt_pk_bf16_f32 v110, v110, v111
	v_cvt_pk_bf16_f32 v111, v112, v113
	v_cvt_pk_bf16_f32 v112, v106, v107
	v_cvt_pk_bf16_f32 v113, v108, v109
	v_mov_b32_e32 v108, v118
	v_mov_b32_e32 v109, v118
	v_lshl_add_u64 v[106:107], v[122:123], 0, v[138:139]
	v_pk_mul_f32 v[104:105], v[104:105], v[108:109]
	v_pk_mul_f32 v[102:103], v[102:103], v[118:119]
	v_pk_mul_f32 v[100:101], v[100:101], v[108:109]
	v_pk_mul_f32 v[98:99], v[98:99], v[118:119]
	s_and_b64 vcc, exec, s[12:13]
	s_mov_b64 s[20:21], -1
	global_store_dwordx4 v[106:107], v[110:113], off sc1
	s_cbranch_vccnz .LBB0_181
	s_and_b64 vcc, exec, s[6:7]
	s_cbranch_vccnz .LBB0_180
	v_lshlrev_b32_e32 v108, 2, v162
	v_mov_b32_e32 v109, v139
	v_lshl_add_u64 v[108:109], v[116:117], 0, v[108:109]
	global_store_dwordx4 v[108:109], v[102:105], off offset:512 nt
	global_store_dwordx4 v[108:109], v[98:101], off offset:528 nt

.LBB0_184:
	s_and_b64 vcc, exec, s[8:9]
	v_cvt_pk_bf16_f32 v102, v102, v103
	v_cvt_pk_bf16_f32 v103, v104, v105
	v_cvt_pk_bf16_f32 v104, v98, v99
	v_cvt_pk_bf16_f32 v105, v100, v101
	global_store_dwordx4 v[106:107], v[102:105], off offset:256 sc1
	s_cbranch_vccnz .LBB0_188
	v_and_b32_e32 v99, 64, v161
	v_xor_b32_e32 v98, 16, v161
	v_add_u32_e32 v99, 64, v99
	v_cmp_lt_i32_e32 vcc, v98, v99
	v_xor_b32_e32 v100, 32, v161
	s_nop 0
	v_cndmask_b32_e32 v98, v161, v98, vcc
	v_lshlrev_b32_e32 v98, 2, v98
	ds_bpermute_b32 v98, v98, v120
	v_cmp_lt_i32_e32 vcc, v100, v99
	s_waitcnt lgkmcnt(0)
	v_add_f32_e32 v98, v120, v98
	v_cndmask_b32_e32 v99, v161, v100, vcc
	v_lshlrev_b32_e32 v99, 2, v99
	ds_bpermute_b32 v99, v99, v98
	s_and_saveexec_b64 vcc, s[0:1]
	s_cbranch_execz .LBB0_187
	s_waitcnt lgkmcnt(0)
	v_add_f32_e32 v98, v98, v99
	v_fma_f32 v98, v98, s57, 0.5
	v_trunc_f32_e32 v98, v98
	v_mul_f32_e32 v99, 0x2f800000, v98
	v_floor_f32_e32 v99, v99
	v_fmac_f32_e32 v98, 0xcf800000, v99
	v_cvt_u32_f32_e32 v98, v98
	v_cvt_u32_f32_e32 v99, v99
	v_lshl_add_u64 v[100:101], v[114:115], 3, s[62:63]
	global_atomic_add_x2 v[100:101], v[98:99], off

.LBB0_194:
	v_ashrrev_i32_e32 v99, 31, v98
	v_lshlrev_b64 v[106:107], 10, v[98:99]
	v_mov_b32_e32 v103, v102
	v_lshl_add_u64 v[106:107], s[94:95], 0, v[106:107]
	v_cvt_pk_bf16_f32 v94, v94, v95
	v_cvt_pk_bf16_f32 v95, v96, v97
	v_cvt_pk_bf16_f32 v96, v90, v91
	v_cvt_pk_bf16_f32 v97, v92, v93
	v_mov_b32_e32 v92, v102
	v_mov_b32_e32 v93, v102
	v_lshl_add_u64 v[90:91], v[106:107], 0, v[138:139]
	v_pk_mul_f32 v[88:89], v[88:89], v[92:93]
	v_pk_mul_f32 v[86:87], v[86:87], v[102:103]
	v_pk_mul_f32 v[84:85], v[84:85], v[92:93]
	v_pk_mul_f32 v[82:83], v[82:83], v[102:103]
	s_and_b64 vcc, exec, s[12:13]
	s_mov_b64 s[20:21], -1
	global_store_dwordx4 v[90:91], v[94:97], off sc1
	s_cbranch_vccnz .LBB0_198
	s_and_b64 vcc, exec, s[6:7]
	s_cbranch_vccnz .LBB0_197
	v_lshlrev_b32_e32 v92, 2, v162
	v_mov_b32_e32 v93, v139
	v_lshl_add_u64 v[92:93], v[100:101], 0, v[92:93]
	global_store_dwordx4 v[92:93], v[86:89], off offset:512 nt
	global_store_dwordx4 v[92:93], v[82:85], off offset:528 nt

.LBB0_201:
	s_and_b64 vcc, exec, s[8:9]
	v_cvt_pk_bf16_f32 v86, v86, v87
	v_cvt_pk_bf16_f32 v87, v88, v89
	v_cvt_pk_bf16_f32 v88, v82, v83
	v_cvt_pk_bf16_f32 v89, v84, v85
	global_store_dwordx4 v[90:91], v[86:89], off offset:256 sc1
	s_cbranch_vccnz .LBB0_205
	v_and_b32_e32 v83, 64, v161
	v_xor_b32_e32 v82, 16, v161
	v_add_u32_e32 v83, 64, v83
	v_cmp_lt_i32_e32 vcc, v82, v83
	v_xor_b32_e32 v84, 32, v161
	s_nop 0
	v_cndmask_b32_e32 v82, v161, v82, vcc
	v_lshlrev_b32_e32 v82, 2, v82
	ds_bpermute_b32 v82, v82, v104
	v_cmp_lt_i32_e32 vcc, v84, v83
	s_waitcnt lgkmcnt(0)
	v_add_f32_e32 v82, v104, v82
	v_cndmask_b32_e32 v83, v161, v84, vcc
	v_lshlrev_b32_e32 v83, 2, v83
	ds_bpermute_b32 v83, v83, v82
	s_and_saveexec_b64 vcc, s[0:1]
	s_cbranch_execz .LBB0_204
	s_waitcnt lgkmcnt(0)
	v_add_f32_e32 v82, v82, v83
	v_fma_f32 v82, v82, s57, 0.5
	v_trunc_f32_e32 v82, v82
	v_mul_f32_e32 v83, 0x2f800000, v82
	v_floor_f32_e32 v83, v83
	v_fmac_f32_e32 v82, 0xcf800000, v83
	v_cvt_u32_f32_e32 v82, v82
	v_cvt_u32_f32_e32 v83, v83
	v_lshl_add_u64 v[84:85], v[98:99], 3, s[62:63]
	global_atomic_add_x2 v[84:85], v[82:83], off

.LBB0_211:
	v_ashrrev_i32_e32 v83, 31, v82
	v_lshlrev_b64 v[90:91], 10, v[82:83]
	v_mov_b32_e32 v87, v86
	v_lshl_add_u64 v[90:91], s[94:95], 0, v[90:91]
	v_cvt_pk_bf16_f32 v78, v78, v79
	v_cvt_pk_bf16_f32 v79, v80, v81
	v_cvt_pk_bf16_f32 v80, v74, v75
	v_cvt_pk_bf16_f32 v81, v76, v77
	v_mov_b32_e32 v76, v86
	v_mov_b32_e32 v77, v86
	v_lshl_add_u64 v[74:75], v[90:91], 0, v[138:139]
	v_pk_mul_f32 v[72:73], v[72:73], v[76:77]
	v_pk_mul_f32 v[70:71], v[70:71], v[86:87]
	v_pk_mul_f32 v[68:69], v[68:69], v[76:77]
	v_pk_mul_f32 v[66:67], v[66:67], v[86:87]
	s_and_b64 vcc, exec, s[12:13]
	s_mov_b64 s[20:21], -1
	global_store_dwordx4 v[74:75], v[78:81], off sc1
	s_cbranch_vccnz .LBB0_215
	s_and_b64 vcc, exec, s[6:7]
	s_cbranch_vccnz .LBB0_214
	v_lshlrev_b32_e32 v76, 2, v162
	v_mov_b32_e32 v77, v139
	v_lshl_add_u64 v[76:77], v[84:85], 0, v[76:77]
	global_store_dwordx4 v[76:77], v[70:73], off offset:512 nt
	global_store_dwordx4 v[76:77], v[66:69], off offset:528 nt

.LBB0_218:
	s_and_b64 vcc, exec, s[8:9]
	v_cvt_pk_bf16_f32 v70, v70, v71
	v_cvt_pk_bf16_f32 v71, v72, v73
	v_cvt_pk_bf16_f32 v72, v66, v67
	v_cvt_pk_bf16_f32 v73, v68, v69
	global_store_dwordx4 v[74:75], v[70:73], off offset:256 sc1
	s_cbranch_vccnz .LBB0_222
	v_and_b32_e32 v67, 64, v161
	v_xor_b32_e32 v66, 16, v161
	v_add_u32_e32 v67, 64, v67
	v_cmp_lt_i32_e32 vcc, v66, v67
	v_xor_b32_e32 v68, 32, v161
	s_nop 0
	v_cndmask_b32_e32 v66, v161, v66, vcc
	v_lshlrev_b32_e32 v66, 2, v66
	ds_bpermute_b32 v66, v66, v88
	v_cmp_lt_i32_e32 vcc, v68, v67
	s_waitcnt lgkmcnt(0)
	v_add_f32_e32 v66, v88, v66
	v_cndmask_b32_e32 v67, v161, v68, vcc
	v_lshlrev_b32_e32 v67, 2, v67
	ds_bpermute_b32 v67, v67, v66
	s_and_saveexec_b64 vcc, s[0:1]
	s_cbranch_execz .LBB0_221
	s_waitcnt lgkmcnt(0)
	v_add_f32_e32 v66, v66, v67
	v_fma_f32 v66, v66, s57, 0.5
	v_trunc_f32_e32 v66, v66
	v_mul_f32_e32 v67, 0x2f800000, v66
	v_floor_f32_e32 v67, v67
	v_fmac_f32_e32 v66, 0xcf800000, v67
	v_cvt_u32_f32_e32 v66, v66
	v_cvt_u32_f32_e32 v67, v67
	v_lshl_add_u64 v[68:69], v[82:83], 3, s[62:63]
	global_atomic_add_x2 v[68:69], v[66:67], off

.LBB0_228:
	v_ashrrev_i32_e32 v67, 31, v66
	v_lshlrev_b64 v[74:75], 10, v[66:67]
	v_mov_b32_e32 v71, v70
	v_lshl_add_u64 v[74:75], s[94:95], 0, v[74:75]
	v_cvt_pk_bf16_f32 v62, v62, v63
	v_cvt_pk_bf16_f32 v63, v64, v65
	v_cvt_pk_bf16_f32 v64, v58, v59
	v_cvt_pk_bf16_f32 v65, v60, v61
	v_mov_b32_e32 v60, v70
	v_mov_b32_e32 v61, v70
	v_lshl_add_u64 v[58:59], v[74:75], 0, v[138:139]
	v_pk_mul_f32 v[56:57], v[56:57], v[60:61]
	v_pk_mul_f32 v[54:55], v[54:55], v[70:71]
	v_pk_mul_f32 v[52:53], v[52:53], v[60:61]
	v_pk_mul_f32 v[50:51], v[50:51], v[70:71]
	s_and_b64 vcc, exec, s[12:13]
	s_mov_b64 s[20:21], -1
	global_store_dwordx4 v[58:59], v[62:65], off sc1
	s_cbranch_vccnz .LBB0_232
	s_and_b64 vcc, exec, s[6:7]
	s_cbranch_vccnz .LBB0_231
	v_lshlrev_b32_e32 v60, 2, v162
	v_mov_b32_e32 v61, v139
	v_lshl_add_u64 v[60:61], v[68:69], 0, v[60:61]
	global_store_dwordx4 v[60:61], v[54:57], off offset:512 nt
	global_store_dwordx4 v[60:61], v[50:53], off offset:528 nt

.LBB0_235:
	s_and_b64 vcc, exec, s[8:9]
	v_cvt_pk_bf16_f32 v54, v54, v55
	v_cvt_pk_bf16_f32 v55, v56, v57
	v_cvt_pk_bf16_f32 v56, v50, v51
	v_cvt_pk_bf16_f32 v57, v52, v53
	global_store_dwordx4 v[58:59], v[54:57], off offset:256 sc1
	s_cbranch_vccnz .LBB0_239
	v_and_b32_e32 v51, 64, v161
	v_xor_b32_e32 v50, 16, v161
	v_add_u32_e32 v51, 64, v51
	v_cmp_lt_i32_e32 vcc, v50, v51
	v_xor_b32_e32 v52, 32, v161
	s_nop 0
	v_cndmask_b32_e32 v50, v161, v50, vcc
	v_lshlrev_b32_e32 v50, 2, v50
	ds_bpermute_b32 v50, v50, v72
	v_cmp_lt_i32_e32 vcc, v52, v51
	s_waitcnt lgkmcnt(0)
	v_add_f32_e32 v50, v72, v50
	v_cndmask_b32_e32 v51, v161, v52, vcc
	v_lshlrev_b32_e32 v51, 2, v51
	ds_bpermute_b32 v51, v51, v50
	s_and_saveexec_b64 vcc, s[0:1]
	s_cbranch_execz .LBB0_238
	s_waitcnt lgkmcnt(0)
	v_add_f32_e32 v50, v50, v51
	v_fma_f32 v50, v50, s57, 0.5
	v_trunc_f32_e32 v50, v50
	v_mul_f32_e32 v51, 0x2f800000, v50
	v_floor_f32_e32 v51, v51
	v_fmac_f32_e32 v50, 0xcf800000, v51
	v_cvt_u32_f32_e32 v50, v50
	v_cvt_u32_f32_e32 v51, v51
	v_lshl_add_u64 v[52:53], v[66:67], 3, s[62:63]
	global_atomic_add_x2 v[52:53], v[50:51], off

.LBB0_245:
	v_ashrrev_i32_e32 v51, 31, v50
	v_lshlrev_b64 v[58:59], 10, v[50:51]
	v_mov_b32_e32 v55, v54
	v_lshl_add_u64 v[58:59], s[94:95], 0, v[58:59]
	v_cvt_pk_bf16_f32 v46, v46, v47
	v_cvt_pk_bf16_f32 v47, v48, v49
	v_cvt_pk_bf16_f32 v48, v42, v43
	v_cvt_pk_bf16_f32 v49, v44, v45
	v_mov_b32_e32 v44, v54
	v_mov_b32_e32 v45, v54
	v_lshl_add_u64 v[42:43], v[58:59], 0, v[138:139]
	v_pk_mul_f32 v[40:41], v[40:41], v[44:45]
	v_pk_mul_f32 v[38:39], v[38:39], v[54:55]
	v_pk_mul_f32 v[36:37], v[36:37], v[44:45]
	v_pk_mul_f32 v[34:35], v[34:35], v[54:55]
	s_and_b64 vcc, exec, s[12:13]
	s_mov_b64 s[20:21], -1
	global_store_dwordx4 v[42:43], v[46:49], off sc1
	s_cbranch_vccnz .LBB0_249
	s_and_b64 vcc, exec, s[6:7]
	s_cbranch_vccnz .LBB0_248
	v_lshlrev_b32_e32 v44, 2, v162
	v_mov_b32_e32 v45, v139
	v_lshl_add_u64 v[44:45], v[52:53], 0, v[44:45]
	global_store_dwordx4 v[44:45], v[38:41], off offset:512 nt
	global_store_dwordx4 v[44:45], v[34:37], off offset:528 nt

.LBB0_252:
	s_and_b64 vcc, exec, s[8:9]
	v_cvt_pk_bf16_f32 v38, v38, v39
	v_cvt_pk_bf16_f32 v39, v40, v41
	v_cvt_pk_bf16_f32 v40, v34, v35
	v_cvt_pk_bf16_f32 v41, v36, v37
	global_store_dwordx4 v[42:43], v[38:41], off offset:256 sc1
	s_cbranch_vccnz .LBB0_256
	v_and_b32_e32 v35, 64, v161
	v_xor_b32_e32 v34, 16, v161
	v_add_u32_e32 v35, 64, v35
	v_cmp_lt_i32_e32 vcc, v34, v35
	v_xor_b32_e32 v36, 32, v161
	s_nop 0
	v_cndmask_b32_e32 v34, v161, v34, vcc
	v_lshlrev_b32_e32 v34, 2, v34
	ds_bpermute_b32 v34, v34, v56
	v_cmp_lt_i32_e32 vcc, v36, v35
	s_waitcnt lgkmcnt(0)
	v_add_f32_e32 v34, v56, v34
	v_cndmask_b32_e32 v35, v161, v36, vcc
	v_lshlrev_b32_e32 v35, 2, v35
	ds_bpermute_b32 v35, v35, v34
	s_and_saveexec_b64 vcc, s[0:1]
	s_cbranch_execz .LBB0_255
	s_waitcnt lgkmcnt(0)
	v_add_f32_e32 v34, v34, v35
	v_fma_f32 v34, v34, s57, 0.5
	v_trunc_f32_e32 v34, v34
	v_mul_f32_e32 v35, 0x2f800000, v34
	v_floor_f32_e32 v35, v35
	v_fmac_f32_e32 v34, 0xcf800000, v35
	v_cvt_u32_f32_e32 v34, v34
	v_cvt_u32_f32_e32 v35, v35
	v_lshl_add_u64 v[36:37], v[50:51], 3, s[62:63]
	global_atomic_add_x2 v[36:37], v[34:35], off

.LBB0_262:
	v_ashrrev_i32_e32 v35, 31, v34
	v_lshlrev_b64 v[42:43], 10, v[34:35]
	v_mov_b32_e32 v39, v38
	v_lshl_add_u64 v[42:43], s[94:95], 0, v[42:43]
	v_cvt_pk_bf16_f32 v30, v30, v31
	v_cvt_pk_bf16_f32 v31, v32, v33
	v_cvt_pk_bf16_f32 v32, v26, v27
	v_cvt_pk_bf16_f32 v33, v28, v29
	v_mov_b32_e32 v28, v38
	v_mov_b32_e32 v29, v38
	v_lshl_add_u64 v[26:27], v[42:43], 0, v[138:139]
	v_pk_mul_f32 v[24:25], v[24:25], v[28:29]
	v_pk_mul_f32 v[22:23], v[22:23], v[38:39]
	v_pk_mul_f32 v[20:21], v[20:21], v[28:29]
	v_pk_mul_f32 v[18:19], v[18:19], v[38:39]
	s_and_b64 vcc, exec, s[12:13]
	s_mov_b64 s[20:21], -1
	global_store_dwordx4 v[26:27], v[30:33], off sc1
	s_cbranch_vccnz .LBB0_266
	s_and_b64 vcc, exec, s[6:7]
	s_cbranch_vccnz .LBB0_265
	v_lshlrev_b32_e32 v28, 2, v162
	v_mov_b32_e32 v29, v139
	v_lshl_add_u64 v[28:29], v[36:37], 0, v[28:29]
	global_store_dwordx4 v[28:29], v[22:25], off offset:512 nt
	global_store_dwordx4 v[28:29], v[18:21], off offset:528 nt

.LBB0_269:
	s_and_b64 vcc, exec, s[8:9]
	v_cvt_pk_bf16_f32 v22, v22, v23
	v_cvt_pk_bf16_f32 v23, v24, v25
	v_cvt_pk_bf16_f32 v24, v18, v19
	v_cvt_pk_bf16_f32 v25, v20, v21
	global_store_dwordx4 v[26:27], v[22:25], off offset:256 sc1
	s_cbranch_vccnz .LBB0_273
	v_and_b32_e32 v19, 64, v161
	v_xor_b32_e32 v18, 16, v161
	v_add_u32_e32 v19, 64, v19
	v_cmp_lt_i32_e32 vcc, v18, v19
	v_xor_b32_e32 v20, 32, v161
	s_nop 0
	v_cndmask_b32_e32 v18, v161, v18, vcc
	v_lshlrev_b32_e32 v18, 2, v18
	ds_bpermute_b32 v18, v18, v40
	v_cmp_lt_i32_e32 vcc, v20, v19
	s_waitcnt lgkmcnt(0)
	v_add_f32_e32 v18, v40, v18
	v_cndmask_b32_e32 v19, v161, v20, vcc
	v_lshlrev_b32_e32 v19, 2, v19
	ds_bpermute_b32 v19, v19, v18
	s_and_saveexec_b64 vcc, s[0:1]
	s_cbranch_execz .LBB0_272
	s_waitcnt lgkmcnt(0)
	v_add_f32_e32 v18, v18, v19
	v_fma_f32 v18, v18, s57, 0.5
	v_trunc_f32_e32 v18, v18
	v_mul_f32_e32 v19, 0x2f800000, v18
	v_floor_f32_e32 v19, v19
	v_fmac_f32_e32 v18, 0xcf800000, v19
	v_cvt_u32_f32_e32 v18, v18
	v_cvt_u32_f32_e32 v19, v19
	v_lshl_add_u64 v[20:21], v[34:35], 3, s[62:63]
	global_atomic_add_x2 v[20:21], v[18:19], off

.LBB0_279:
	v_ashrrev_i32_e32 v19, 31, v18
	v_lshlrev_b64 v[26:27], 10, v[18:19]
	v_mov_b32_e32 v23, v22
	v_lshl_add_u64 v[26:27], s[94:95], 0, v[26:27]
	v_cvt_pk_bf16_f32 v14, v14, v15
	v_cvt_pk_bf16_f32 v15, v16, v17
	v_cvt_pk_bf16_f32 v16, v10, v11
	v_cvt_pk_bf16_f32 v17, v12, v13
	v_mov_b32_e32 v12, v22
	v_mov_b32_e32 v13, v22
	v_lshl_add_u64 v[10:11], v[26:27], 0, v[138:139]
	v_pk_mul_f32 v[8:9], v[8:9], v[12:13]
	v_pk_mul_f32 v[6:7], v[6:7], v[22:23]
	v_pk_mul_f32 v[4:5], v[4:5], v[12:13]
	v_pk_mul_f32 v[2:3], v[2:3], v[22:23]
	s_and_b64 vcc, exec, s[12:13]
	s_mov_b64 s[10:11], -1
	global_store_dwordx4 v[10:11], v[14:17], off sc1
	s_cbranch_vccnz .LBB0_283
	s_and_b64 vcc, exec, s[6:7]
	s_cbranch_vccnz .LBB0_282
	v_lshlrev_b32_e32 v138, 2, v162
	v_lshl_add_u64 v[12:13], v[20:21], 0, v[138:139]
	global_store_dwordx4 v[12:13], v[6:9], off offset:512 nt
	global_store_dwordx4 v[12:13], v[2:5], off offset:528 nt

.LBB0_286:
	s_and_b64 vcc, exec, s[8:9]
	v_cvt_pk_bf16_f32 v6, v6, v7
	v_cvt_pk_bf16_f32 v7, v8, v9
	v_cvt_pk_bf16_f32 v8, v2, v3
	v_cvt_pk_bf16_f32 v9, v4, v5
	global_store_dwordx4 v[10:11], v[6:9], off offset:256 sc1
	s_cbranch_vccnz .LBB0_290
	v_and_b32_e32 v3, 64, v161
	v_xor_b32_e32 v2, 16, v161
	v_add_u32_e32 v3, 64, v3
	v_cmp_lt_i32_e32 vcc, v2, v3
	v_xor_b32_e32 v4, 32, v161
	s_nop 0
	v_cndmask_b32_e32 v2, v161, v2, vcc
	v_lshlrev_b32_e32 v2, 2, v2
	ds_bpermute_b32 v2, v2, v24
	v_cmp_lt_i32_e32 vcc, v4, v3
	s_waitcnt lgkmcnt(0)
	v_add_f32_e32 v2, v24, v2
	v_cndmask_b32_e32 v3, v161, v4, vcc
	v_lshlrev_b32_e32 v3, 2, v3
	ds_bpermute_b32 v3, v3, v2
	s_and_saveexec_b64 s[6:7], s[0:1]
	s_cbranch_execz .LBB0_289
	s_waitcnt lgkmcnt(0)
	v_add_f32_e32 v2, v2, v3
	v_fma_f32 v2, v2, s57, 0.5
	v_trunc_f32_e32 v2, v2
	v_mul_f32_e32 v3, 0x2f800000, v2
	v_floor_f32_e32 v3, v3
	v_fmac_f32_e32 v2, 0xcf800000, v3
	v_cvt_u32_f32_e32 v2, v2
	v_cvt_u32_f32_e32 v3, v3
	v_lshl_add_u64 v[4:5], v[18:19], 3, s[62:63]
	global_atomic_add_x2 v[4:5], v[2:3], off

.LBB0_333:
	s_or_b64 exec, exec, s[6:7]
	s_lshl_b64 s[4:5], s[4:5], 2
	v_readlane_b32 s6, v254, 57
	v_readlane_b32 s7, v254, 58
	s_add_u32 s4, s6, s4
	s_addc_u32 s5, s7, s5
	v_lshlrev_b32_e32 v6, 5, v10
	s_waitcnt lgkmcnt(0)
	s_barrier
	global_load_dwordx4 v[2:5], v6, s[4:5] offset:16
	s_nop 0
	global_load_dwordx4 v[6:9], v6, s[4:5]
	v_lshlrev_b32_e32 v10, 5, v12
	v_add_u32_e32 v14, 0, v10
	ds_read_b128 v[16:19], v14 offset:25088
	s_waitcnt vmcnt(2)
	ds_read_b128 v[32:35], v14 offset:25104
	s_lshl_b64 s[4:5], s[34:35], 13
	v_readlane_b32 s6, v254, 59
	s_add_u32 s4, s6, s4
	v_readlane_b32 s6, v254, 61
	s_addc_u32 s5, s6, s5
	v_readlane_b32 s6, v254, 63
	s_waitcnt vmcnt(1) lgkmcnt(0)
	v_pk_mul_f32 v[20:21], v[4:5], v[34:35]
	s_waitcnt vmcnt(0)
	v_pk_mul_f32 v[18:19], v[8:9], v[18:19]
	v_mov_b32_e32 v15, v8
	v_pk_mul_f32 v[16:17], v[6:7], v[16:17]
	v_mov_b32_e32 v8, v7
	v_mov_b32_e32 v7, v4
	v_pk_mul_f32 v[32:33], v[2:3], v[32:33]
	v_mov_b32_e32 v4, v3
	v_bfe_u32 v3, v19, 16, 1
	v_mov_b32_e32 v14, v6
	v_mov_b32_e32 v6, v2
	v_bfe_u32 v2, v21, 16, 1
	v_bfe_u32 v34, v17, 16, 1
	v_add3_u32 v3, v19, v3, s85
	v_bfe_u32 v19, v20, 16, 1
	v_bfe_u32 v31, v33, 16, 1
	v_add3_u32 v2, v21, v2, s85
	v_add3_u32 v21, v17, v34, s85
	v_bfe_u32 v17, v18, 16, 1
	v_add3_u32 v19, v20, v19, s85
	v_add3_u32 v31, v33, v31, s85
	v_bfe_u32 v33, v16, 16, 1
	v_bfe_u32 v34, v32, 16, 1
	v_add3_u32 v17, v18, v17, s85
	v_lshrrev_b32_e32 v19, 16, v19
	v_add3_u32 v18, v32, v34, s85
	v_add3_u32 v16, v16, v33, s85
	v_lshrrev_b32_e32 v17, 16, v17
	v_and_or_b32 v19, v2, s86, v19
	v_lshlrev_b32_e32 v2, 3, v12
	v_lshrrev_b32_e32 v16, 16, v16
	v_lshrrev_b32_e32 v18, 16, v18
	v_and_or_b32 v17, v3, s86, v17
	v_ashrrev_i32_e32 v3, 31, v2
	v_and_or_b32 v18, v31, s86, v18
	v_and_or_b32 v16, v21, s86, v16
	v_lshl_add_u64 v[20:21], v[2:3], 1, s[4:5]
	global_store_dwordx4 v[20:21], v[16:19], off sc1
	s_lshl_b64 s[4:5], s[34:35], 16
	s_add_u32 s18, s6, s4
	v_lshlrev_b32_e32 v18, 6, v12
	v_readlane_b32 s6, v255, 1
	v_and_b32_e32 v16, 31, v12
	v_and_b32_e32 v3, 0x3c0, v10
	v_and_b32_e32 v10, 64, v18
	s_addc_u32 s19, s6, s5
	v_readlane_b32 s6, v255, 3
	v_add_u32_e32 v20, 0, v10
	v_lshlrev_b32_e32 v10, 4, v16
	s_add_u32 s6, s6, s4
	v_readlane_b32 s4, v255, 5
	v_lshl_add_u64 v[16:17], s[18:19], 0, v[10:11]
	v_and_b32_e32 v10, 15, v12
	s_addc_u32 s7, s4, s5
	v_and_b32_e32 v18, 0x1c0, v18
	v_cmp_gt_u32_e64 s[4:5], 8, v10
	v_lshlrev_b32_e32 v10, 4, v10
	v_add_u32_e32 v21, 0, v18
	v_lshl_add_u64 v[18:19], s[6:7], 0, v[10:11]
	s_mov_b32 s18, 0

.LBB0_335:
	v_cndmask_b32_e64 v10, 0, 1, s[6:7]
	v_cmp_ne_u32_e32 vcc, 1, v10
	v_add_u32_e32 v10, s35, v12
	v_ashrrev_i32_e32 v10, 5, v10
	v_add_u32_e32 v48, s19, v10
	v_and_b32_e32 v10, 63, v48
	s_movk_i32 s6, 0x3c0
	v_bitop3_b32 v31, v10, s6, v3 bitop3:0x36
	v_lshl_add_u32 v31, v31, 3, 0
	ds_read_b64 v[50:51], v31
	v_lshl_add_u32 v10, v10, 7, v20
	ds_read_b128 v[32:35], v10 offset:8704
	ds_read_b128 v[36:39], v10 offset:8720
	ds_read_b128 v[40:43], v10 offset:8736
	ds_read_b128 v[44:47], v10 offset:8752
	v_cmp_gt_u32_e64 s[6:7], 64, v48
	s_waitcnt lgkmcnt(3)
	v_mov_b32_e32 v54, v33
	s_waitcnt lgkmcnt(2)
	v_mov_b32_e32 v55, v37
	v_mov_b32_e32 v52, v32
	v_mov_b32_e32 v53, v36
	v_pk_mul_f32 v[54:55], v[50:51], v[54:55] op_sel:[1,0]
	v_ashrrev_i32_e32 v49, 31, v48
	v_pk_fma_f32 v[52:53], v[50:51], v[52:53], v[54:55] op_sel_hi:[0,1,1] neg_lo:[0,0,1] neg_hi:[0,0,1]
	v_mov_b32_e32 v54, v32
	v_pk_mov_b32 v[32:33], v[32:33], v[36:37] op_sel:[1,0]
	v_mov_b32_e32 v55, v37
	v_pk_mul_f32 v[32:33], v[50:51], v[32:33]
	v_mov_b32_e32 v36, v34
	v_pk_fma_f32 v[32:33], v[50:51], v[54:55], v[32:33] op_sel:[1,0,0] op_sel_hi:[0,1,1]
	v_cndmask_b32_e64 v33, v33, v53, s[6:7]
	v_cndmask_b32_e64 v32, v32, v52, s[6:7]
	v_mov_b32_e32 v52, v35
	v_mov_b32_e32 v53, v39
	v_mov_b32_e32 v37, v38
	v_pk_mul_f32 v[52:53], v[50:51], v[52:53] op_sel:[1,0]
	v_pk_mul_f32 v[32:33], v[14:15], v[32:33]
	v_pk_fma_f32 v[36:37], v[50:51], v[36:37], v[52:53] op_sel_hi:[0,1,1] neg_lo:[0,0,1] neg_hi:[0,0,1]
	v_mov_b32_e32 v52, v34
	v_pk_mov_b32 v[34:35], v[34:35], v[38:39] op_sel:[1,0]
	v_mov_b32_e32 v53, v39
	v_pk_mul_f32 v[34:35], v[50:51], v[34:35]
	s_waitcnt lgkmcnt(1)
	v_mov_b32_e32 v38, v41
	v_pk_fma_f32 v[34:35], v[50:51], v[52:53], v[34:35] op_sel:[1,0,0] op_sel_hi:[0,1,1]
	s_waitcnt lgkmcnt(0)
	v_mov_b32_e32 v39, v45
	v_cndmask_b32_e64 v35, v35, v37, s[6:7]
	v_cndmask_b32_e64 v34, v34, v36, s[6:7]
	v_mov_b32_e32 v36, v40
	v_mov_b32_e32 v37, v44
	v_pk_mul_f32 v[38:39], v[50:51], v[38:39] op_sel:[1,0]
	v_pk_mul_f32 v[34:35], v[8:9], v[34:35]
	v_pk_fma_f32 v[36:37], v[50:51], v[36:37], v[38:39] op_sel_hi:[0,1,1] neg_lo:[0,0,1] neg_hi:[0,0,1]
	v_mov_b32_e32 v38, v40
	v_pk_mov_b32 v[40:41], v[40:41], v[44:45] op_sel:[1,0]
	v_mov_b32_e32 v39, v45
	v_pk_mul_f32 v[40:41], v[50:51], v[40:41]
	s_movk_i32 s35, 0x200
	v_pk_fma_f32 v[38:39], v[50:51], v[38:39], v[40:41] op_sel:[1,0,0] op_sel_hi:[0,1,1]
	v_mov_b32_e32 v40, v43
	v_mov_b32_e32 v41, v47
	v_cndmask_b32_e64 v37, v39, v37, s[6:7]
	v_cndmask_b32_e64 v36, v38, v36, s[6:7]
	v_mov_b32_e32 v38, v42
	v_mov_b32_e32 v39, v46
	v_pk_mul_f32 v[40:41], v[50:51], v[40:41] op_sel:[1,0]
	v_pk_mul_f32 v[36:37], v[6:7], v[36:37]
	v_pk_fma_f32 v[38:39], v[50:51], v[38:39], v[40:41] op_sel_hi:[0,1,1] neg_lo:[0,0,1] neg_hi:[0,0,1]
	v_mov_b32_e32 v40, v42
	v_pk_mov_b32 v[42:43], v[42:43], v[46:47] op_sel:[1,0]
	v_mov_b32_e32 v41, v47
	v_pk_mul_f32 v[42:43], v[50:51], v[42:43]
	s_and_b64 vcc, exec, vcc
	v_pk_fma_f32 v[40:41], v[50:51], v[40:41], v[42:43] op_sel:[1,0,0] op_sel_hi:[0,1,1]
	v_cndmask_b32_e64 v39, v41, v39, s[6:7]
	v_cndmask_b32_e64 v38, v40, v38, s[6:7]
	v_pk_mul_f32 v[38:39], v[4:5], v[38:39]
	v_bfe_u32 v40, v35, 16, 1
	v_bfe_u32 v10, v39, 16, 1
	v_bfe_u32 v31, v38, 16, 1
	v_bfe_u32 v41, v34, 16, 1
	v_add3_u32 v41, v34, v41, s85
	v_add3_u32 v40, v35, v40, s85
	v_add3_u32 v31, v38, v31, s85
	v_add3_u32 v10, v39, v10, s85
	v_bfe_u32 v34, v32, 16, 1
	v_bfe_u32 v35, v33, 16, 1
	v_bfe_u32 v38, v36, 16, 1
	v_bfe_u32 v39, v37, 16, 1
	v_add3_u32 v37, v37, v39, s85
	v_add3_u32 v36, v36, v38, s85
	v_add3_u32 v33, v33, v35, s85
	v_add3_u32 v32, v32, v34, s85
	v_lshrrev_b32_e32 v32, 16, v32
	v_lshrrev_b32_e32 v33, 16, v33
	v_lshrrev_b32_e32 v34, 16, v36
	v_lshrrev_b32_e32 v35, 16, v37
	v_lshlrev_b64 v[36:37], 9, v[48:49]
	v_and_or_b32 v35, v10, s86, v35
	v_and_or_b32 v34, v31, s86, v34
	v_and_or_b32 v33, v40, s86, v33
	v_and_or_b32 v32, v41, s86, v32
	v_lshl_add_u64 v[36:37], v[16:17], 0, v[36:37]
	s_mov_b64 s[6:7], 0
	global_store_dwordx4 v[36:37], v[32:35], off sc1
	s_cbranch_vccz .LBB0_335
	s_lshl_b32 s19, s18, 6
	s_mov_b32 s35, 0
	s_mov_b64 s[6:7], -1
.LBB0_337:
	v_cndmask_b32_e64 v10, 0, 1, s[6:7]
	v_cmp_ne_u32_e32 vcc, 1, v10
	v_add_u32_e32 v10, s35, v12
	v_ashrrev_i32_e32 v10, 4, v10
	v_add_u32_e32 v64, s19, v10
	v_lshlrev_b32_e32 v31, 5, v64
	v_and_b32_e32 v31, 0xfffffe00, v31
	v_lshlrev_b32_e32 v10, 9, v10
	v_add_u32_e32 v31, v21, v31
	v_and_b32_e32 v10, 0x1e00, v10
	v_add_u32_e32 v10, v21, v10
	ds_read_b128 v[32:35], v31 offset:512
	ds_read_b128 v[36:39], v31 offset:528
	ds_read_b128 v[40:43], v31 offset:544
	ds_read_b128 v[44:47], v31 offset:560
	ds_read_b128 v[48:51], v10 offset:16896
	ds_read_b128 v[52:55], v10 offset:16912
	ds_read_b128 v[56:59], v10 offset:16928
	ds_read_b128 v[60:63], v10 offset:16944
	s_waitcnt lgkmcnt(7)
	v_mov_b32_e32 v66, v32
	s_waitcnt lgkmcnt(6)
	v_mov_b32_e32 v67, v36
	s_waitcnt lgkmcnt(2)
	v_mov_b32_e32 v69, v52
	v_mov_b32_e32 v36, v33
	v_mov_b32_e32 v52, v49
	v_mov_b32_e32 v68, v48
	v_pk_mul_f32 v[32:33], v[36:37], v[52:53]
	v_pk_mul_f32 v[48:49], v[66:67], v[52:53]
	v_pk_fma_f32 v[32:33], v[66:67], v[68:69], v[32:33] neg_lo:[0,0,1] neg_hi:[0,0,1]
	v_pk_fma_f32 v[36:37], v[36:37], v[68:69], v[48:49]
	v_ashrrev_i32_e32 v65, 31, v64
	v_cndmask_b32_e64 v10, -v37, v33, s[4:5]
	v_mov_b32_e32 v33, v38
	v_mov_b32_e32 v37, v54
	v_mov_b32_e32 v38, v35
	v_mov_b32_e32 v54, v51
	v_cndmask_b32_e64 v31, -v36, v32, s[4:5]
	v_mov_b32_e32 v32, v34
	v_mov_b32_e32 v36, v50
	v_pk_mul_f32 v[34:35], v[38:39], v[54:55]
	s_movk_i32 s35, 0x200
	v_pk_fma_f32 v[34:35], v[32:33], v[36:37], v[34:35] neg_lo:[0,0,1] neg_hi:[0,0,1]
	v_pk_mul_f32 v[32:33], v[32:33], v[54:55]
	s_mov_b64 s[6:7], 0
	v_pk_fma_f32 v[32:33], v[38:39], v[36:37], v[32:33]
	s_and_b64 vcc, exec, vcc
	v_cndmask_b32_e64 v39, -v33, v35, s[4:5]
	v_mov_b32_e32 v33, v44
	s_waitcnt lgkmcnt(0)
	v_mov_b32_e32 v35, v60
	v_mov_b32_e32 v44, v41
	v_mov_b32_e32 v60, v57
	v_cndmask_b32_e64 v38, -v32, v34, s[4:5]
	v_mov_b32_e32 v32, v40
	v_mov_b32_e32 v34, v56
	v_pk_mul_f32 v[36:37], v[44:45], v[60:61]
	s_nop 0
	v_pk_fma_f32 v[36:37], v[32:33], v[34:35], v[36:37] neg_lo:[0,0,1] neg_hi:[0,0,1]
	v_pk_mul_f32 v[32:33], v[32:33], v[60:61]
	s_nop 0
	v_pk_fma_f32 v[32:33], v[44:45], v[34:35], v[32:33]
	v_mov_b32_e32 v35, v62
	v_cndmask_b32_e64 v40, -v33, v37, s[4:5]
	v_mov_b32_e32 v33, v46
	v_mov_b32_e32 v46, v43
	v_mov_b32_e32 v62, v59
	v_cndmask_b32_e64 v41, -v32, v36, s[4:5]
	v_mov_b32_e32 v32, v42
	v_mov_b32_e32 v34, v58
	v_pk_mul_f32 v[36:37], v[46:47], v[62:63]
	s_nop 0
	v_pk_fma_f32 v[36:37], v[32:33], v[34:35], v[36:37] neg_lo:[0,0,1] neg_hi:[0,0,1]
	v_pk_mul_f32 v[32:33], v[32:33], v[62:63]
	s_nop 0
	v_pk_fma_f32 v[32:33], v[46:47], v[34:35], v[32:33]
	s_nop 0
	v_cndmask_b32_e64 v32, -v32, v36, s[4:5]
	v_cndmask_b32_e64 v33, -v33, v37, s[4:5]
	v_bfe_u32 v34, v33, 16, 1
	v_bfe_u32 v35, v32, 16, 1
	v_bfe_u32 v36, v39, 16, 1
	v_bfe_u32 v37, v38, 16, 1
	v_add3_u32 v37, v38, v37, s85
	v_add3_u32 v36, v39, v36, s85
	v_add3_u32 v32, v32, v35, s85
	v_add3_u32 v33, v33, v34, s85
	v_bfe_u32 v34, v31, 16, 1
	v_bfe_u32 v35, v10, 16, 1
	v_bfe_u32 v38, v41, 16, 1
	v_bfe_u32 v39, v40, 16, 1
	v_add3_u32 v39, v40, v39, s85
	v_add3_u32 v38, v41, v38, s85
	v_add3_u32 v10, v10, v35, s85
	v_add3_u32 v31, v31, v34, s85
	v_lshrrev_b32_e32 v31, 16, v31
	v_lshrrev_b32_e32 v10, 16, v10
	v_lshrrev_b32_e32 v34, 16, v38
	v_lshrrev_b32_e32 v35, 16, v39
	v_and_or_b32 v35, v33, s86, v35
	v_and_or_b32 v34, v32, s86, v34
	v_and_or_b32 v33, v36, s86, v10
	v_and_or_b32 v32, v37, s86, v31
	v_lshlrev_b64 v[36:37], 8, v[64:65]
	v_lshl_add_u64 v[36:37], v[18:19], 0, v[36:37]
	global_store_dwordx4 v[36:37], v[32:35], off sc1
	s_cbranch_vccz .LBB0_337
	s_add_i32 s18, s18, 1
	s_cmp_eq_u32 s18, 4
	s_cbranch_scc0 .LBB0_334
	v_cmp_gt_i32_e32 vcc, 64, v12
	s_and_saveexec_b64 s[4:5], vcc
	s_cbranch_execz .LBB0_341
	v_readlane_b32 s6, v254, 47
	v_readlane_b32 s7, v254, 48
	s_lshl_b64 s[6:7], s[6:7], 3
	v_readlane_b32 s18, v255, 6
	v_lshl_add_u32 v3, v12, 3, 0
	v_readlane_b32 s19, v255, 7
	s_add_u32 s18, s18, s6
	ds_read2st64_b64 v[4:7], v3 offset0:1 offset1:16
	s_addc_u32 s19, s19, s7
	v_readlane_b32 s82, v255, 8
	v_readlane_b32 s83, v255, 9
	s_add_u32 s6, s82, s6
	s_addc_u32 s7, s83, s7
	v_lshlrev_b64 v[8:9], 3, v[12:13]
	v_lshl_add_u64 v[14:15], s[6:7], 0, v[8:9]
	s_waitcnt lgkmcnt(0)
	global_store_dwordx2 v[14:15], v[4:5], off
	v_lshl_add_u64 v[4:5], s[18:19], 0, v[8:9]
	global_store_dwordx2 v[4:5], v[6:7], off

.LBB0_380:
	s_waitcnt vmcnt(15)
	v_pk_mul_f32 v[2:3], v[2:3], v[78:79] op_sel_hi:[1,0]
	v_add_u32_e32 v99, v77, v79
	ds_write2_b32 v99, v2, v3 offset1:1
	v_pk_mul_f32 v[2:3], v[4:5], v[78:79] op_sel_hi:[1,0]
	ds_write2_b32 v99, v2, v3 offset0:2 offset1:3
	s_waitcnt vmcnt(14)
	v_pk_mul_f32 v[2:3], v[6:7], v[74:75] op_sel_hi:[1,0]
	v_add_u32_e32 v4, 0x410, v99
	ds_write2_b32 v4, v2, v3 offset1:1
	v_pk_mul_f32 v[2:3], v[8:9], v[74:75] op_sel_hi:[1,0]
	v_add_u32_e32 v4, 0x418, v99
	ds_write2_b32 v4, v2, v3 offset1:1
	s_waitcnt vmcnt(13)
	v_pk_mul_f32 v[2:3], v[10:11], v[82:83] op_sel_hi:[1,0]
	v_add_u32_e32 v4, 0x820, v99
	ds_write2_b32 v4, v2, v3 offset1:1
	v_pk_mul_f32 v[2:3], v[12:13], v[82:83] op_sel_hi:[1,0]
	v_add_u32_e32 v4, 0x828, v99
	ds_write2_b32 v4, v2, v3 offset1:1
	s_waitcnt vmcnt(12)
	v_pk_mul_f32 v[2:3], v[14:15], v[76:77] op_sel_hi:[1,0]
	v_add_u32_e32 v4, 0xc30, v99
	ds_write2_b32 v4, v2, v3 offset1:1
	v_pk_mul_f32 v[2:3], v[16:17], v[76:77] op_sel_hi:[1,0]
	v_add_u32_e32 v4, 0xc38, v99
	ds_write2_b32 v4, v2, v3 offset1:1
	s_waitcnt vmcnt(11)
	v_pk_mul_f32 v[2:3], v[18:19], v[86:87] op_sel_hi:[1,0]
	v_add_u32_e32 v4, 0x1040, v99
	ds_write2_b32 v4, v2, v3 offset1:1
	v_pk_mul_f32 v[2:3], v[20:21], v[86:87] op_sel_hi:[1,0]
	v_add_u32_e32 v4, 0x1048, v99
	ds_write2_b32 v4, v2, v3 offset1:1
	s_waitcnt vmcnt(10)
	v_pk_mul_f32 v[2:3], v[22:23], v[80:81] op_sel_hi:[1,0]
	v_add_u32_e32 v4, 0x1450, v99
	ds_write2_b32 v4, v2, v3 offset1:1
	v_pk_mul_f32 v[2:3], v[24:25], v[80:81] op_sel_hi:[1,0]
	v_add_u32_e32 v4, 0x1458, v99
	ds_write2_b32 v4, v2, v3 offset1:1
	s_waitcnt vmcnt(9)
	v_pk_mul_f32 v[2:3], v[26:27], v[90:91] op_sel_hi:[1,0]
	v_add_u32_e32 v4, 0x1860, v99
	ds_write2_b32 v4, v2, v3 offset1:1
	v_pk_mul_f32 v[2:3], v[28:29], v[90:91] op_sel_hi:[1,0]
	v_add_u32_e32 v4, 0x1868, v99
	ds_write2_b32 v4, v2, v3 offset1:1
	s_waitcnt vmcnt(8)
	v_pk_mul_f32 v[2:3], v[30:31], v[84:85] op_sel_hi:[1,0]
	v_add_u32_e32 v4, 0x1c70, v99
	ds_write2_b32 v4, v2, v3 offset1:1
	v_pk_mul_f32 v[2:3], v[32:33], v[84:85] op_sel_hi:[1,0]
	v_add_u32_e32 v4, 0x1c78, v99
	ds_write2_b32 v4, v2, v3 offset1:1
	s_waitcnt vmcnt(7)
	v_pk_mul_f32 v[2:3], v[34:35], v[94:95] op_sel_hi:[1,0]
	v_add_u32_e32 v4, 0x2080, v99
	ds_write2_b32 v4, v2, v3 offset1:1
	v_pk_mul_f32 v[2:3], v[36:37], v[94:95] op_sel_hi:[1,0]
	v_add_u32_e32 v4, 0x2088, v99
	ds_write2_b32 v4, v2, v3 offset1:1
	s_waitcnt vmcnt(6)
	v_pk_mul_f32 v[2:3], v[38:39], v[88:89] op_sel_hi:[1,0]
	v_add_u32_e32 v4, 0x2490, v99
	ds_write2_b32 v4, v2, v3 offset1:1
	v_pk_mul_f32 v[2:3], v[40:41], v[88:89] op_sel_hi:[1,0]
	v_add_u32_e32 v4, 0x2498, v99
	ds_write2_b32 v4, v2, v3 offset1:1
	s_waitcnt vmcnt(5)
	v_pk_mul_f32 v[2:3], v[42:43], v[98:99] op_sel_hi:[1,0]
	v_add_u32_e32 v4, 0x28a0, v99
	ds_write2_b32 v4, v2, v3 offset1:1
	v_pk_mul_f32 v[2:3], v[44:45], v[98:99] op_sel_hi:[1,0]
	v_add_u32_e32 v4, 0x28a8, v99
	ds_write2_b32 v4, v2, v3 offset1:1
	s_waitcnt vmcnt(4)
	v_pk_mul_f32 v[2:3], v[46:47], v[92:93] op_sel_hi:[1,0]
	v_add_u32_e32 v4, 0x2cb0, v99
	ds_write2_b32 v4, v2, v3 offset1:1
	v_pk_mul_f32 v[2:3], v[48:49], v[92:93] op_sel_hi:[1,0]
	v_add_u32_e32 v4, 0x2cb8, v99
	ds_write2_b32 v4, v2, v3 offset1:1
	s_waitcnt vmcnt(3)
	v_pk_mul_f32 v[2:3], v[50:51], v[102:103] op_sel_hi:[1,0]
	v_add_u32_e32 v4, 0x30c0, v99
	ds_write2_b32 v4, v2, v3 offset1:1
	v_pk_mul_f32 v[2:3], v[52:53], v[102:103] op_sel_hi:[1,0]
	v_add_u32_e32 v4, 0x30c8, v99
	ds_write2_b32 v4, v2, v3 offset1:1
	s_waitcnt vmcnt(2)
	v_pk_mul_f32 v[2:3], v[54:55], v[96:97] op_sel_hi:[1,0]
	v_add_u32_e32 v4, 0x34d0, v99
	ds_write2_b32 v4, v2, v3 offset1:1
	v_pk_mul_f32 v[2:3], v[56:57], v[96:97] op_sel_hi:[1,0]
	v_add_u32_e32 v4, 0x34d8, v99
	ds_write2_b32 v4, v2, v3 offset1:1
	s_waitcnt vmcnt(1)
	v_pk_mul_f32 v[2:3], v[58:59], v[104:105] op_sel_hi:[1,0]
	v_add_u32_e32 v4, 0x38e0, v99
	ds_write2_b32 v4, v2, v3 offset1:1
	v_pk_mul_f32 v[2:3], v[60:61], v[104:105] op_sel_hi:[1,0]
	v_add_u32_e32 v4, 0x38e8, v99
	s_and_b32 s4, 0xffff, s4
	ds_write2_b32 v4, v2, v3 offset1:1
	s_waitcnt vmcnt(0)
	v_pk_mul_f32 v[2:3], v[62:63], v[100:101] op_sel_hi:[1,0]
	v_add_u32_e32 v4, 0x3cf0, v99
	s_and_b32 s7, 0xffff, s7
	ds_write2_b32 v4, v2, v3 offset1:1
	v_pk_mul_f32 v[2:3], v[64:65], v[100:101] op_sel_hi:[1,0]
	v_add_u32_e32 v4, 0x3cf8, v99
	s_cmp_lt_u32 s7, 44
	ds_write2_b32 v4, v2, v3 offset1:1
	s_cselect_b32 s7, 0, 0xfffff500
	s_waitcnt lgkmcnt(0)
	s_cselect_b32 s10, 0, 0x80
	s_add_i32 s7, s7, s4
	s_lshl_b32 s7, s7, 1
	s_and_b32 s4, s4, 64
	v_add_u32_e32 v26, 0x400, v83
	s_and_b32 s7, s7, 0xffffff00
	s_or_b32 s4, s4, s10
	ds_read2_b32 v[6:7], v83 offset0:65 offset1:73
	ds_read2_b32 v[8:9], v83 offset1:8
	ds_read2_b32 v[10:11], v83 offset0:130 offset1:138
	ds_read2_b32 v[12:13], v83 offset0:195 offset1:203
	ds_read2_b32 v[14:15], v26 offset0:4 offset1:12
	ds_read2_b32 v[16:17], v26 offset0:69 offset1:77
	ds_read2_b32 v[18:19], v26 offset0:134 offset1:142
	ds_read2_b32 v[20:21], v26 offset0:199 offset1:207
	s_or_b32 s7, s4, s7
	s_and_b32 s4, 0xffff, s6
	v_or_b32_e32 v24, s7, v81
	s_lshl_b32 s4, s4, 1
	v_ashrrev_i32_e32 v25, 31, v24
	v_lshl_add_u64 v[22:23], v[70:71], 0, s[4:5]
	v_lshlrev_b64 v[24:25], 11, v[24:25]
	s_waitcnt lgkmcnt(6)
	v_cvt_pk_bf16_f32 v2, v8, v6
	s_waitcnt lgkmcnt(4)
	v_cvt_pk_bf16_f32 v3, v10, v12
	s_waitcnt lgkmcnt(2)
	v_cvt_pk_bf16_f32 v4, v14, v16
	s_waitcnt lgkmcnt(0)
	v_cvt_pk_bf16_f32 v5, v18, v20
	v_lshl_add_u64 v[24:25], v[22:23], 0, v[24:25]
	v_or_b32_e32 v6, s7, v85
	global_store_dwordx4 v[24:25], v[2:5], off sc1
	s_nop 1
	v_cvt_pk_bf16_f32 v2, v9, v7
	v_ashrrev_i32_e32 v7, 31, v6
	v_cvt_pk_bf16_f32 v3, v11, v13
	v_cvt_pk_bf16_f32 v4, v15, v17
	v_cvt_pk_bf16_f32 v5, v19, v21
	v_lshlrev_b64 v[6:7], 11, v[6:7]
	ds_read2_b32 v[8:9], v83 offset0:81 offset1:89
	ds_read2_b32 v[10:11], v83 offset0:16 offset1:24
	ds_read2_b32 v[12:13], v83 offset0:146 offset1:154
	ds_read2_b32 v[14:15], v83 offset0:211 offset1:219
	ds_read2_b32 v[16:17], v26 offset0:20 offset1:28
	ds_read2_b32 v[18:19], v26 offset0:85 offset1:93
	ds_read2_b32 v[20:21], v26 offset0:150 offset1:158
	ds_read2_b32 v[24:25], v26 offset0:215 offset1:223
	v_lshl_add_u64 v[6:7], v[22:23], 0, v[6:7]
	global_store_dwordx4 v[6:7], v[2:5], off sc1
	v_or_b32_e32 v6, s7, v87
	v_ashrrev_i32_e32 v7, 31, v6
	v_lshlrev_b64 v[6:7], 11, v[6:7]
	s_waitcnt lgkmcnt(6)
	v_cvt_pk_bf16_f32 v2, v10, v8
	s_waitcnt lgkmcnt(4)
	v_cvt_pk_bf16_f32 v3, v12, v14
	s_waitcnt lgkmcnt(2)
	v_cvt_pk_bf16_f32 v4, v16, v18
	s_waitcnt lgkmcnt(0)
	v_cvt_pk_bf16_f32 v5, v20, v24
	v_lshl_add_u64 v[6:7], v[22:23], 0, v[6:7]
	global_store_dwordx4 v[6:7], v[2:5], off sc1
	v_or_b32_e32 v6, s7, v89
	v_ashrrev_i32_e32 v7, 31, v6
	v_cvt_pk_bf16_f32 v2, v11, v9
	v_cvt_pk_bf16_f32 v3, v13, v15
	v_cvt_pk_bf16_f32 v4, v17, v19
	v_cvt_pk_bf16_f32 v5, v21, v25
	v_lshlrev_b64 v[6:7], 11, v[6:7]
	ds_read2_b32 v[8:9], v83 offset0:32 offset1:40
	ds_read2_b32 v[10:11], v83 offset0:97 offset1:105
	ds_read2_b32 v[12:13], v83 offset0:162 offset1:170
	ds_read2_b32 v[14:15], v83 offset0:227 offset1:235
	ds_read2_b32 v[16:17], v26 offset0:36 offset1:44
	ds_read2_b32 v[18:19], v26 offset0:101 offset1:109
	ds_read2_b32 v[20:21], v26 offset0:166 offset1:174
	ds_read2_b32 v[24:25], v26 offset0:231 offset1:239
	v_lshl_add_u64 v[6:7], v[22:23], 0, v[6:7]
	global_store_dwordx4 v[6:7], v[2:5], off sc1
	v_or_b32_e32 v6, s7, v91
	v_ashrrev_i32_e32 v7, 31, v6
	v_lshlrev_b64 v[6:7], 11, v[6:7]
	s_waitcnt lgkmcnt(6)
	v_cvt_pk_bf16_f32 v2, v8, v10
	s_waitcnt lgkmcnt(4)
	v_cvt_pk_bf16_f32 v3, v12, v14
	s_waitcnt lgkmcnt(2)
	v_cvt_pk_bf16_f32 v4, v16, v18
	s_waitcnt lgkmcnt(0)
	v_cvt_pk_bf16_f32 v5, v20, v24
	v_lshl_add_u64 v[6:7], v[22:23], 0, v[6:7]
	global_store_dwordx4 v[6:7], v[2:5], off sc1
	v_or_b32_e32 v6, s7, v93
	v_ashrrev_i32_e32 v7, 31, v6
	v_cvt_pk_bf16_f32 v2, v9, v11
	v_cvt_pk_bf16_f32 v3, v13, v15
	v_cvt_pk_bf16_f32 v4, v17, v19
	v_cvt_pk_bf16_f32 v5, v21, v25
	v_lshlrev_b64 v[6:7], 11, v[6:7]
	ds_read2_b32 v[8:9], v83 offset0:48 offset1:56
	ds_read2_b32 v[10:11], v83 offset0:113 offset1:121
	ds_read2_b32 v[12:13], v83 offset0:178 offset1:186
	ds_read2_b32 v[14:15], v83 offset0:243 offset1:251
	ds_read2_b32 v[16:17], v26 offset0:52 offset1:60
	ds_read2_b32 v[18:19], v26 offset0:117 offset1:125
	ds_read2_b32 v[20:21], v26 offset0:182 offset1:190
	ds_read2_b32 v[24:25], v26 offset0:247 offset1:255
	v_lshl_add_u64 v[6:7], v[22:23], 0, v[6:7]
	global_store_dwordx4 v[6:7], v[2:5], off sc1
	v_or_b32_e32 v6, s7, v95
	v_ashrrev_i32_e32 v7, 31, v6
	v_lshlrev_b64 v[6:7], 11, v[6:7]
	s_waitcnt lgkmcnt(6)
	v_cvt_pk_bf16_f32 v2, v8, v10
	s_waitcnt lgkmcnt(4)
	v_cvt_pk_bf16_f32 v3, v12, v14
	s_waitcnt lgkmcnt(2)
	v_cvt_pk_bf16_f32 v4, v16, v18
	s_waitcnt lgkmcnt(0)
	v_cvt_pk_bf16_f32 v5, v20, v24
	v_lshl_add_u64 v[6:7], v[22:23], 0, v[6:7]
	global_store_dwordx4 v[6:7], v[2:5], off sc1
	v_or_b32_e32 v6, s7, v97
	v_ashrrev_i32_e32 v7, 31, v6
	v_lshlrev_b64 v[6:7], 11, v[6:7]
	v_cvt_pk_bf16_f32 v2, v9, v11
	v_cvt_pk_bf16_f32 v3, v13, v15
	v_cvt_pk_bf16_f32 v4, v17, v19
	v_cvt_pk_bf16_f32 v5, v21, v25
	v_lshl_add_u64 v[6:7], v[22:23], 0, v[6:7]
	global_store_dwordx4 v[6:7], v[2:5], off sc1
	s_waitcnt lgkmcnt(0)
	s_branch .LBB0_346
.LBB0_381:
	s_and_b64 vcc, exec, s[6:7]
	s_cbranch_vccz .LBB0_346
	s_ashr_i32 s4, s8, 31
	s_lshr_b32 s4, s4, 28
	s_add_i32 s4, s8, s4
	s_ashr_i32 s4, s4, 4
	s_lshl_b32 s10, s4, 6
	s_lshl_b32 s4, s4, 10
	v_or_b32_e32 v62, s10, v75
	s_sub_i32 s6, s12, s4
	v_or_b32_e32 v4, 4, v62
	s_ashr_i32 s7, s6, 31
	v_ashrrev_i32_e32 v63, 31, v62
	v_ashrrev_i32_e32 v5, 31, v4
	v_lshl_add_u64 v[64:65], s[6:7], 2, v[68:69]
	v_lshlrev_b64 v[2:3], 12, v[62:63]
	v_lshlrev_b64 v[4:5], 12, v[4:5]
	v_lshl_add_u64 v[2:3], v[64:65], 0, v[2:3]
	v_lshl_add_u64 v[6:7], v[64:65], 0, v[4:5]
	v_or_b32_e32 v10, 8, v62
	v_or_b32_e32 v12, 12, v62
	global_load_dwordx4 v[2:5], v[2:3], off nt
	s_nop 0
	global_load_dwordx4 v[6:9], v[6:7], off nt
	v_ashrrev_i32_e32 v11, 31, v10
	v_ashrrev_i32_e32 v13, 31, v12
	v_lshlrev_b64 v[10:11], 12, v[10:11]
	v_lshlrev_b64 v[12:13], 12, v[12:13]
	v_lshl_add_u64 v[10:11], v[64:65], 0, v[10:11]
	v_lshl_add_u64 v[14:15], v[64:65], 0, v[12:13]
	global_load_dwordx4 v[10:13], v[10:11], off nt
	s_nop 0
	global_load_dwordx4 v[14:17], v[14:15], off nt
	v_or_b32_e32 v18, 16, v62
	v_or_b32_e32 v20, 20, v62
	v_ashrrev_i32_e32 v19, 31, v18
	v_ashrrev_i32_e32 v21, 31, v20
	v_lshlrev_b64 v[18:19], 12, v[18:19]
	v_lshlrev_b64 v[20:21], 12, v[20:21]
	v_lshl_add_u64 v[18:19], v[64:65], 0, v[18:19]
	v_lshl_add_u64 v[22:23], v[64:65], 0, v[20:21]
	global_load_dwordx4 v[18:21], v[18:19], off nt
	s_nop 0
	global_load_dwordx4 v[22:25], v[22:23], off nt
	v_or_b32_e32 v26, 24, v62
	v_or_b32_e32 v28, 28, v62
	v_ashrrev_i32_e32 v27, 31, v26
	v_ashrrev_i32_e32 v29, 31, v28
	v_lshlrev_b64 v[26:27], 12, v[26:27]
	v_lshlrev_b64 v[28:29], 12, v[28:29]
	v_lshl_add_u64 v[26:27], v[64:65], 0, v[26:27]
	v_lshl_add_u64 v[30:31], v[64:65], 0, v[28:29]
	global_load_dwordx4 v[26:29], v[26:27], off nt
	s_nop 0
	global_load_dwordx4 v[30:33], v[30:31], off nt
	v_or_b32_e32 v34, 32, v62
	v_or_b32_e32 v36, 36, v62
	v_ashrrev_i32_e32 v35, 31, v34
	v_ashrrev_i32_e32 v37, 31, v36
	v_lshlrev_b64 v[34:35], 12, v[34:35]
	v_lshlrev_b64 v[36:37], 12, v[36:37]
	v_lshl_add_u64 v[34:35], v[64:65], 0, v[34:35]
	v_lshl_add_u64 v[38:39], v[64:65], 0, v[36:37]
	global_load_dwordx4 v[34:37], v[34:35], off nt
	s_nop 0
	global_load_dwordx4 v[38:41], v[38:39], off nt
	v_or_b32_e32 v42, 40, v62
	v_or_b32_e32 v44, 44, v62
	v_ashrrev_i32_e32 v43, 31, v42
	v_ashrrev_i32_e32 v45, 31, v44
	v_lshlrev_b64 v[42:43], 12, v[42:43]
	v_lshlrev_b64 v[44:45], 12, v[44:45]
	v_lshl_add_u64 v[42:43], v[64:65], 0, v[42:43]
	v_lshl_add_u64 v[46:47], v[64:65], 0, v[44:45]
	v_or_b32_e32 v50, 48, v62
	global_load_dwordx4 v[42:45], v[42:43], off nt
	s_nop 0
	global_load_dwordx4 v[46:49], v[46:47], off nt
	v_ashrrev_i32_e32 v51, 31, v50
	v_lshlrev_b64 v[50:51], 12, v[50:51]
	v_or_b32_e32 v54, 52, v62
	v_lshl_add_u64 v[50:51], v[64:65], 0, v[50:51]
	v_ashrrev_i32_e32 v55, 31, v54
	global_load_dwordx4 v[50:53], v[50:51], off nt
	v_lshlrev_b64 v[54:55], 12, v[54:55]
	v_or_b32_e32 v58, 56, v62
	v_lshl_add_u64 v[54:55], v[64:65], 0, v[54:55]
	v_ashrrev_i32_e32 v59, 31, v58
	global_load_dwordx4 v[54:57], v[54:55], off nt
	v_lshlrev_b64 v[58:59], 12, v[58:59]
	v_or_b32_e32 v62, 60, v62
	v_lshl_add_u64 v[58:59], v[64:65], 0, v[58:59]
	v_ashrrev_i32_e32 v63, 31, v62
	global_load_dwordx4 v[58:61], v[58:59], off nt
	v_lshlrev_b64 v[62:63], 12, v[62:63]
	v_lshl_add_u64 v[62:63], v[64:65], 0, v[62:63]
	global_load_dwordx4 v[62:65], v[62:63], off nt
	v_add_u32_e32 v74, v77, v79
	s_ashr_i32 s11, s10, 31
	s_waitcnt vmcnt(15)
	ds_write2_b32 v74, v2, v3 offset1:1
	ds_write2_b32 v74, v4, v5 offset0:2 offset1:3
	v_add_u32_e32 v2, 0x410, v74
	s_waitcnt vmcnt(14)
	ds_write2_b32 v2, v6, v7 offset1:1
	v_add_u32_e32 v2, 0x418, v74
	ds_write2_b32 v2, v8, v9 offset1:1
	v_add_u32_e32 v2, 0x820, v74
	s_waitcnt vmcnt(13)
	ds_write2_b32 v2, v10, v11 offset1:1
	v_add_u32_e32 v2, 0x828, v74
	ds_write2_b32 v2, v12, v13 offset1:1
	v_add_u32_e32 v2, 0xc30, v74
	s_waitcnt vmcnt(12)
	ds_write2_b32 v2, v14, v15 offset1:1
	v_add_u32_e32 v2, 0xc38, v74
	ds_write2_b32 v2, v16, v17 offset1:1
	v_add_u32_e32 v2, 0x1040, v74
	s_waitcnt vmcnt(11)
	ds_write2_b32 v2, v18, v19 offset1:1
	v_add_u32_e32 v2, 0x1048, v74
	ds_write2_b32 v2, v20, v21 offset1:1
	v_add_u32_e32 v2, 0x1450, v74
	s_waitcnt vmcnt(10)
	ds_write2_b32 v2, v22, v23 offset1:1
	v_add_u32_e32 v2, 0x1458, v74
	ds_write2_b32 v2, v24, v25 offset1:1
	v_add_u32_e32 v2, 0x1860, v74
	v_add_u32_e32 v24, s6, v81
	s_waitcnt vmcnt(9)
	ds_write2_b32 v2, v26, v27 offset1:1
	v_add_u32_e32 v2, 0x1868, v74
	ds_write2_b32 v2, v28, v29 offset1:1
	v_add_u32_e32 v2, 0x1c70, v74
	s_waitcnt vmcnt(8)
	ds_write2_b32 v2, v30, v31 offset1:1
	v_add_u32_e32 v2, 0x1c78, v74
	ds_write2_b32 v2, v32, v33 offset1:1
	v_add_u32_e32 v2, 0x2080, v74
	v_add_u32_e32 v28, 0x400, v83
	s_waitcnt vmcnt(7)
	ds_write2_b32 v2, v34, v35 offset1:1
	v_add_u32_e32 v2, 0x2088, v74
	ds_write2_b32 v2, v36, v37 offset1:1
	v_add_u32_e32 v2, 0x2490, v74
	s_waitcnt vmcnt(6)
	ds_write2_b32 v2, v38, v39 offset1:1
	v_add_u32_e32 v2, 0x2498, v74
	ds_write2_b32 v2, v40, v41 offset1:1
	v_add_u32_e32 v2, 0x28a0, v74
	v_ashrrev_i32_e32 v25, 31, v24
	v_lshl_add_u64 v[22:23], s[10:11], 1, v[72:73]
	s_waitcnt vmcnt(5)
	ds_write2_b32 v2, v42, v43 offset1:1
	v_add_u32_e32 v2, 0x28a8, v74
	ds_write2_b32 v2, v44, v45 offset1:1
	v_add_u32_e32 v2, 0x2cb0, v74
	s_waitcnt vmcnt(4)
	ds_write2_b32 v2, v46, v47 offset1:1
	v_add_u32_e32 v2, 0x2cb8, v74
	ds_write2_b32 v2, v48, v49 offset1:1
	v_add_u32_e32 v2, 0x30c0, v74
	s_waitcnt vmcnt(3)
	ds_write2_b32 v2, v50, v51 offset1:1
	v_add_u32_e32 v2, 0x30c8, v74
	ds_write2_b32 v2, v52, v53 offset1:1
	v_add_u32_e32 v2, 0x34d0, v74
	s_waitcnt vmcnt(2)
	ds_write2_b32 v2, v54, v55 offset1:1
	v_add_u32_e32 v2, 0x34d8, v74
	ds_write2_b32 v2, v56, v57 offset1:1
	v_add_u32_e32 v2, 0x38e0, v74
	v_lshlrev_b64 v[26:27], 11, v[24:25]
	s_waitcnt vmcnt(1)
	ds_write2_b32 v2, v58, v59 offset1:1
	v_add_u32_e32 v2, 0x38e8, v74
	ds_write2_b32 v2, v60, v61 offset1:1
	v_add_u32_e32 v2, 0x3cf0, v74
	s_waitcnt vmcnt(0)
	ds_write2_b32 v2, v62, v63 offset1:1
	v_add_u32_e32 v2, 0x3cf8, v74
	ds_write2_b32 v2, v64, v65 offset1:1
	s_waitcnt lgkmcnt(0)
	ds_read2_b32 v[6:7], v83 offset0:65 offset1:73
	ds_read2_b32 v[8:9], v83 offset1:8
	ds_read2_b32 v[10:11], v83 offset0:130 offset1:138
	ds_read2_b32 v[12:13], v83 offset0:195 offset1:203
	ds_read2_b32 v[14:15], v28 offset0:4 offset1:12
	ds_read2_b32 v[16:17], v28 offset0:69 offset1:77
	ds_read2_b32 v[18:19], v28 offset0:134 offset1:142
	ds_read2_b32 v[20:21], v28 offset0:199 offset1:207
	v_lshl_add_u64 v[26:27], v[22:23], 0, v[26:27]
	s_waitcnt lgkmcnt(6)
	v_cvt_pk_bf16_f32 v2, v8, v6
	s_waitcnt lgkmcnt(2)
	v_cvt_pk_bf16_f32 v4, v14, v16
	v_cvt_pk_bf16_f32 v3, v10, v12
	s_waitcnt lgkmcnt(0)
	v_cvt_pk_bf16_f32 v5, v18, v20
	v_add_u32_e32 v6, 8, v24
	global_store_dwordx4 v[26:27], v[2:5], off sc1
	s_nop 1
	v_cvt_pk_bf16_f32 v2, v9, v7
	v_ashrrev_i32_e32 v7, 31, v6
	v_cvt_pk_bf16_f32 v3, v11, v13
	v_cvt_pk_bf16_f32 v4, v15, v17
	v_cvt_pk_bf16_f32 v5, v19, v21
	v_lshlrev_b64 v[6:7], 11, v[6:7]
	ds_read2_b32 v[8:9], v83 offset0:81 offset1:89
	ds_read2_b32 v[10:11], v83 offset0:16 offset1:24
	ds_read2_b32 v[12:13], v83 offset0:146 offset1:154
	ds_read2_b32 v[14:15], v83 offset0:211 offset1:219
	ds_read2_b32 v[16:17], v28 offset0:20 offset1:28
	ds_read2_b32 v[18:19], v28 offset0:85 offset1:93
	ds_read2_b32 v[20:21], v28 offset0:150 offset1:158
	ds_read2_b32 v[26:27], v28 offset0:215 offset1:223
	v_lshl_add_u64 v[6:7], v[22:23], 0, v[6:7]
	global_store_dwordx4 v[6:7], v[2:5], off sc1
	v_add_u32_e32 v6, 16, v24
	v_ashrrev_i32_e32 v7, 31, v6
	v_lshlrev_b64 v[6:7], 11, v[6:7]
	s_waitcnt lgkmcnt(6)
	v_cvt_pk_bf16_f32 v2, v10, v8
	s_waitcnt lgkmcnt(4)
	v_cvt_pk_bf16_f32 v3, v12, v14
	s_waitcnt lgkmcnt(2)
	v_cvt_pk_bf16_f32 v4, v16, v18
	s_waitcnt lgkmcnt(0)
	v_cvt_pk_bf16_f32 v5, v20, v26
	v_lshl_add_u64 v[6:7], v[22:23], 0, v[6:7]
	global_store_dwordx4 v[6:7], v[2:5], off sc1
	v_add_u32_e32 v6, 24, v24
	v_ashrrev_i32_e32 v7, 31, v6
	v_cvt_pk_bf16_f32 v2, v11, v9
	v_cvt_pk_bf16_f32 v3, v13, v15
	v_cvt_pk_bf16_f32 v4, v17, v19
	v_cvt_pk_bf16_f32 v5, v21, v27
	v_lshlrev_b64 v[6:7], 11, v[6:7]
	ds_read2_b32 v[8:9], v83 offset0:32 offset1:40
	ds_read2_b32 v[10:11], v83 offset0:97 offset1:105
	ds_read2_b32 v[12:13], v83 offset0:162 offset1:170
	ds_read2_b32 v[14:15], v83 offset0:227 offset1:235
	ds_read2_b32 v[16:17], v28 offset0:36 offset1:44
	ds_read2_b32 v[18:19], v28 offset0:101 offset1:109
	ds_read2_b32 v[20:21], v28 offset0:166 offset1:174
	ds_read2_b32 v[26:27], v28 offset0:231 offset1:239
	v_lshl_add_u64 v[6:7], v[22:23], 0, v[6:7]
	global_store_dwordx4 v[6:7], v[2:5], off sc1
	v_add_u32_e32 v6, 32, v24
	v_ashrrev_i32_e32 v7, 31, v6
	v_lshlrev_b64 v[6:7], 11, v[6:7]
	s_waitcnt lgkmcnt(6)
	v_cvt_pk_bf16_f32 v2, v8, v10
	s_waitcnt lgkmcnt(4)
	v_cvt_pk_bf16_f32 v3, v12, v14
	s_waitcnt lgkmcnt(2)
	v_cvt_pk_bf16_f32 v4, v16, v18
	s_waitcnt lgkmcnt(0)
	v_cvt_pk_bf16_f32 v5, v20, v26
	v_lshl_add_u64 v[6:7], v[22:23], 0, v[6:7]
	global_store_dwordx4 v[6:7], v[2:5], off sc1
	v_add_u32_e32 v6, 40, v24
	v_ashrrev_i32_e32 v7, 31, v6
	v_cvt_pk_bf16_f32 v2, v9, v11
	v_cvt_pk_bf16_f32 v3, v13, v15
	v_cvt_pk_bf16_f32 v4, v17, v19
	v_cvt_pk_bf16_f32 v5, v21, v27
	v_lshlrev_b64 v[6:7], 11, v[6:7]
	ds_read2_b32 v[8:9], v83 offset0:48 offset1:56
	ds_read2_b32 v[10:11], v83 offset0:113 offset1:121
	ds_read2_b32 v[12:13], v83 offset0:178 offset1:186
	ds_read2_b32 v[14:15], v83 offset0:243 offset1:251
	ds_read2_b32 v[16:17], v28 offset0:52 offset1:60
	ds_read2_b32 v[18:19], v28 offset0:117 offset1:125
	ds_read2_b32 v[20:21], v28 offset0:182 offset1:190
	ds_read2_b32 v[26:27], v28 offset0:247 offset1:255
	v_lshl_add_u64 v[6:7], v[22:23], 0, v[6:7]
	global_store_dwordx4 v[6:7], v[2:5], off sc1
	v_add_u32_e32 v6, 48, v24
	v_ashrrev_i32_e32 v7, 31, v6
	v_lshlrev_b64 v[6:7], 11, v[6:7]
	s_waitcnt lgkmcnt(6)
	v_cvt_pk_bf16_f32 v2, v8, v10
	s_waitcnt lgkmcnt(4)
	v_cvt_pk_bf16_f32 v3, v12, v14
	s_waitcnt lgkmcnt(2)
	v_cvt_pk_bf16_f32 v4, v16, v18
	s_waitcnt lgkmcnt(0)
	v_cvt_pk_bf16_f32 v5, v20, v26
	v_lshl_add_u64 v[6:7], v[22:23], 0, v[6:7]
	global_store_dwordx4 v[6:7], v[2:5], off sc1
	v_add_u32_e32 v6, 56, v24
	v_ashrrev_i32_e32 v7, 31, v6
	v_lshlrev_b64 v[6:7], 11, v[6:7]
	v_cvt_pk_bf16_f32 v2, v9, v11
	v_cvt_pk_bf16_f32 v3, v13, v15
	v_cvt_pk_bf16_f32 v4, v17, v19
	v_cvt_pk_bf16_f32 v5, v21, v27
	v_lshl_add_u64 v[6:7], v[22:23], 0, v[6:7]
	global_store_dwordx4 v[6:7], v[2:5], off sc1
	s_waitcnt lgkmcnt(0)
	s_branch .LBB0_346

.LBB0_461:
	s_or_b64 exec, exec, s[6:7]
	s_lshl_b64 s[4:5], s[4:5], 2
	v_readlane_b32 s6, v254, 57
	v_readlane_b32 s7, v254, 58
	s_add_u32 s4, s6, s4
	s_addc_u32 s5, s7, s5
	v_lshlrev_b32_e32 v6, 5, v21
	s_waitcnt lgkmcnt(0)
	s_barrier
	global_load_dwordx4 v[2:5], v6, s[4:5] offset:16
	s_nop 0
	global_load_dwordx4 v[6:9], v6, s[4:5]
	v_lshlrev_b32_e32 v21, 5, v10
	v_add_u32_e32 v12, 0, v21
	ds_read_b128 v[14:17], v12 offset:25088
	s_waitcnt vmcnt(2)
	ds_read_b128 v[22:25], v12 offset:25104
	s_movk_i32 s9, 0x7fff
	s_lshl_b64 s[12:13], s[30:31], 13
	v_readlane_b32 s4, v254, 59
	s_mov_b32 s14, 0xffff0000
	s_add_u32 s4, s4, s12
	v_readlane_b32 s5, v254, 61
	s_addc_u32 s5, s5, s13
	v_readlane_b32 s6, v254, 63
	s_mov_b32 s8, 0
	s_waitcnt vmcnt(1) lgkmcnt(0)
	v_pk_mul_f32 v[18:19], v[4:5], v[24:25]
	s_waitcnt vmcnt(0)
	v_pk_mul_f32 v[16:17], v[8:9], v[16:17]
	v_mov_b32_e32 v13, v8
	v_pk_mul_f32 v[14:15], v[6:7], v[14:15]
	v_mov_b32_e32 v8, v7
	v_mov_b32_e32 v7, v4
	v_pk_mul_f32 v[22:23], v[2:3], v[22:23]
	v_mov_b32_e32 v4, v3
	v_bfe_u32 v3, v17, 16, 1
	v_mov_b32_e32 v12, v6
	v_mov_b32_e32 v6, v2
	v_bfe_u32 v2, v19, 16, 1
	v_bfe_u32 v25, v15, 16, 1
	v_add3_u32 v3, v17, v3, s9
	v_bfe_u32 v17, v18, 16, 1
	v_bfe_u32 v24, v23, 16, 1
	v_add3_u32 v2, v19, v2, s9
	v_add3_u32 v19, v15, v25, s9
	v_bfe_u32 v15, v16, 16, 1
	v_add3_u32 v17, v18, v17, s9
	v_add3_u32 v23, v23, v24, s9
	v_bfe_u32 v24, v14, 16, 1
	v_bfe_u32 v25, v22, 16, 1
	v_add3_u32 v15, v16, v15, s9
	v_lshrrev_b32_e32 v17, 16, v17
	v_add3_u32 v16, v22, v25, s9
	v_add3_u32 v14, v14, v24, s9
	v_lshrrev_b32_e32 v15, 16, v15
	v_and_or_b32 v17, v2, s14, v17
	v_lshlrev_b32_e32 v2, 3, v10
	v_lshrrev_b32_e32 v14, 16, v14
	v_lshrrev_b32_e32 v16, 16, v16
	v_and_or_b32 v15, v3, s14, v15
	v_ashrrev_i32_e32 v3, 31, v2
	v_and_or_b32 v16, v23, s14, v16
	v_and_or_b32 v14, v19, s14, v14
	v_lshl_add_u64 v[18:19], v[2:3], 1, s[4:5]
	s_lshl_b64 s[4:5], s[30:31], 16
	global_store_dwordx4 v[18:19], v[14:17], off sc1
	s_add_u32 s16, s6, s4
	v_readlane_b32 s6, v255, 1
	v_and_b32_e32 v14, 31, v10
	v_lshlrev_b32_e32 v19, 6, v10
	s_addc_u32 s17, s6, s5
	v_readlane_b32 s6, v255, 3
	v_and_b32_e32 v15, 64, v19
	v_lshlrev_b32_e32 v16, 4, v14
	v_mov_b32_e32 v17, 0
	s_add_u32 s6, s6, s4
	v_readlane_b32 s4, v255, 5
	v_add_u32_e32 v18, 0, v15
	v_lshl_add_u64 v[14:15], s[16:17], 0, v[16:17]
	v_and_b32_e32 v16, 15, v10
	s_addc_u32 s7, s4, s5
	v_and_b32_e32 v19, 0x1c0, v19
	v_cmp_gt_u32_e64 s[4:5], 8, v16
	v_lshlrev_b32_e32 v16, 4, v16
	v_and_b32_e32 v3, 0x3c0, v21
	v_add_u32_e32 v19, 0, v19
	v_lshl_add_u64 v[16:17], s[6:7], 0, v[16:17]

.LBB0_463:
	v_cndmask_b32_e64 v21, 0, 1, s[6:7]
	v_cmp_ne_u32_e32 vcc, 1, v21
	v_add_u32_e32 v21, s16, v10
	v_ashrrev_i32_e32 v21, 5, v21
	v_add_u32_e32 v38, s15, v21
	v_and_b32_e32 v21, 63, v38
	s_movk_i32 s6, 0x3c0
	v_bitop3_b32 v22, v21, s6, v3 bitop3:0x36
	v_lshl_add_u32 v22, v22, 3, 0
	ds_read_b64 v[40:41], v22
	v_lshl_add_u32 v21, v21, 7, v18
	ds_read_b128 v[22:25], v21 offset:8704
	ds_read_b128 v[26:29], v21 offset:8720
	ds_read_b128 v[30:33], v21 offset:8736
	ds_read_b128 v[34:37], v21 offset:8752
	v_cmp_gt_u32_e64 s[6:7], 64, v38
	s_waitcnt lgkmcnt(3)
	v_mov_b32_e32 v44, v23
	s_waitcnt lgkmcnt(2)
	v_mov_b32_e32 v45, v27
	v_mov_b32_e32 v42, v22
	v_mov_b32_e32 v43, v26
	v_pk_mul_f32 v[44:45], v[40:41], v[44:45] op_sel:[1,0]
	v_ashrrev_i32_e32 v39, 31, v38
	v_pk_fma_f32 v[42:43], v[40:41], v[42:43], v[44:45] op_sel_hi:[0,1,1] neg_lo:[0,0,1] neg_hi:[0,0,1]
	v_mov_b32_e32 v44, v22
	v_pk_mov_b32 v[22:23], v[22:23], v[26:27] op_sel:[1,0]
	v_mov_b32_e32 v45, v27
	v_pk_mul_f32 v[22:23], v[40:41], v[22:23]
	v_mov_b32_e32 v26, v24
	v_pk_fma_f32 v[22:23], v[40:41], v[44:45], v[22:23] op_sel:[1,0,0] op_sel_hi:[0,1,1]
	v_cndmask_b32_e64 v23, v23, v43, s[6:7]
	v_cndmask_b32_e64 v22, v22, v42, s[6:7]
	v_mov_b32_e32 v42, v25
	v_mov_b32_e32 v43, v29
	v_mov_b32_e32 v27, v28
	v_pk_mul_f32 v[42:43], v[40:41], v[42:43] op_sel:[1,0]
	v_pk_mul_f32 v[22:23], v[12:13], v[22:23]
	v_pk_fma_f32 v[26:27], v[40:41], v[26:27], v[42:43] op_sel_hi:[0,1,1] neg_lo:[0,0,1] neg_hi:[0,0,1]
	v_mov_b32_e32 v42, v24
	v_pk_mov_b32 v[24:25], v[24:25], v[28:29] op_sel:[1,0]
	v_mov_b32_e32 v43, v29
	v_pk_mul_f32 v[24:25], v[40:41], v[24:25]
	s_waitcnt lgkmcnt(1)
	v_mov_b32_e32 v28, v31
	v_pk_fma_f32 v[24:25], v[40:41], v[42:43], v[24:25] op_sel:[1,0,0] op_sel_hi:[0,1,1]
	s_waitcnt lgkmcnt(0)
	v_mov_b32_e32 v29, v35
	v_cndmask_b32_e64 v25, v25, v27, s[6:7]
	v_cndmask_b32_e64 v24, v24, v26, s[6:7]
	v_mov_b32_e32 v26, v30
	v_mov_b32_e32 v27, v34
	v_pk_mul_f32 v[28:29], v[40:41], v[28:29] op_sel:[1,0]
	v_pk_mul_f32 v[24:25], v[8:9], v[24:25]
	v_pk_fma_f32 v[26:27], v[40:41], v[26:27], v[28:29] op_sel_hi:[0,1,1] neg_lo:[0,0,1] neg_hi:[0,0,1]
	v_mov_b32_e32 v28, v30
	v_pk_mov_b32 v[30:31], v[30:31], v[34:35] op_sel:[1,0]
	v_mov_b32_e32 v29, v35
	v_pk_mul_f32 v[30:31], v[40:41], v[30:31]
	s_movk_i32 s16, 0x200
	v_pk_fma_f32 v[28:29], v[40:41], v[28:29], v[30:31] op_sel:[1,0,0] op_sel_hi:[0,1,1]
	v_mov_b32_e32 v30, v33
	v_mov_b32_e32 v31, v37
	v_cndmask_b32_e64 v27, v29, v27, s[6:7]
	v_cndmask_b32_e64 v26, v28, v26, s[6:7]
	v_mov_b32_e32 v28, v32
	v_mov_b32_e32 v29, v36
	v_pk_mul_f32 v[30:31], v[40:41], v[30:31] op_sel:[1,0]
	v_pk_mul_f32 v[26:27], v[6:7], v[26:27]
	v_pk_fma_f32 v[28:29], v[40:41], v[28:29], v[30:31] op_sel_hi:[0,1,1] neg_lo:[0,0,1] neg_hi:[0,0,1]
	v_mov_b32_e32 v30, v32
	v_pk_mov_b32 v[32:33], v[32:33], v[36:37] op_sel:[1,0]
	v_mov_b32_e32 v31, v37
	v_pk_mul_f32 v[32:33], v[40:41], v[32:33]
	s_and_b64 vcc, exec, vcc
	v_pk_fma_f32 v[30:31], v[40:41], v[30:31], v[32:33] op_sel:[1,0,0] op_sel_hi:[0,1,1]
	v_cndmask_b32_e64 v29, v31, v29, s[6:7]
	v_cndmask_b32_e64 v28, v30, v28, s[6:7]
	v_pk_mul_f32 v[28:29], v[4:5], v[28:29]
	v_bfe_u32 v31, v25, 16, 1
	v_bfe_u32 v21, v29, 16, 1
	v_bfe_u32 v30, v28, 16, 1
	v_bfe_u32 v32, v24, 16, 1
	v_add3_u32 v21, v29, v21, s9
	v_bfe_u32 v29, v26, 16, 1
	v_add3_u32 v32, v24, v32, s9
	v_add3_u32 v31, v25, v31, s9
	v_add3_u32 v24, v28, v30, s9
	v_bfe_u32 v25, v22, 16, 1
	v_bfe_u32 v28, v23, 16, 1
	v_bfe_u32 v30, v27, 16, 1
	v_add3_u32 v26, v26, v29, s9
	v_add3_u32 v27, v27, v30, s9
	v_add3_u32 v23, v23, v28, s9
	v_add3_u32 v22, v22, v25, s9
	v_lshrrev_b32_e32 v26, 16, v26
	v_lshrrev_b32_e32 v22, 16, v22
	v_lshrrev_b32_e32 v23, 16, v23
	v_lshrrev_b32_e32 v25, 16, v27
	v_and_or_b32 v24, v24, s14, v26
	v_lshlrev_b64 v[26:27], 9, v[38:39]
	v_and_or_b32 v25, v21, s14, v25
	v_and_or_b32 v23, v31, s14, v23
	v_and_or_b32 v22, v32, s14, v22
	v_lshl_add_u64 v[26:27], v[14:15], 0, v[26:27]
	s_mov_b64 s[6:7], 0
	global_store_dwordx4 v[26:27], v[22:25], off sc1
	s_cbranch_vccz .LBB0_463
	s_lshl_b32 s15, s8, 6
	s_mov_b32 s16, 0
	s_mov_b64 s[6:7], -1
.LBB0_465:
	v_cndmask_b32_e64 v21, 0, 1, s[6:7]
	v_cmp_ne_u32_e32 vcc, 1, v21
	v_add_u32_e32 v21, s16, v10
	v_ashrrev_i32_e32 v21, 4, v21
	v_add_u32_e32 v54, s15, v21
	v_lshlrev_b32_e32 v22, 5, v54
	v_and_b32_e32 v22, 0xfffffe00, v22
	v_lshlrev_b32_e32 v21, 9, v21
	v_add_u32_e32 v34, v19, v22
	v_and_b32_e32 v21, 0x1e00, v21
	v_add_u32_e32 v21, v19, v21
	ds_read_b128 v[22:25], v34 offset:512
	ds_read_b128 v[26:29], v34 offset:528
	ds_read_b128 v[30:33], v34 offset:544
	ds_read_b128 v[34:37], v34 offset:560
	ds_read_b128 v[38:41], v21 offset:16896
	ds_read_b128 v[42:45], v21 offset:16912
	ds_read_b128 v[46:49], v21 offset:16928
	ds_read_b128 v[50:53], v21 offset:16944
	s_waitcnt lgkmcnt(7)
	v_mov_b32_e32 v56, v22
	s_waitcnt lgkmcnt(6)
	v_mov_b32_e32 v57, v26
	s_waitcnt lgkmcnt(2)
	v_mov_b32_e32 v59, v42
	v_mov_b32_e32 v26, v23
	v_mov_b32_e32 v42, v39
	v_mov_b32_e32 v58, v38
	v_pk_mul_f32 v[22:23], v[26:27], v[42:43]
	v_pk_mul_f32 v[38:39], v[56:57], v[42:43]
	v_pk_fma_f32 v[22:23], v[56:57], v[58:59], v[22:23] neg_lo:[0,0,1] neg_hi:[0,0,1]
	v_pk_fma_f32 v[26:27], v[26:27], v[58:59], v[38:39]
	v_ashrrev_i32_e32 v55, 31, v54
	v_cndmask_b32_e64 v21, -v27, v23, s[4:5]
	v_mov_b32_e32 v23, v28
	v_mov_b32_e32 v27, v44
	v_mov_b32_e32 v28, v25
	v_mov_b32_e32 v44, v41
	v_cndmask_b32_e64 v38, -v26, v22, s[4:5]
	v_mov_b32_e32 v22, v24
	v_mov_b32_e32 v26, v40
	v_pk_mul_f32 v[24:25], v[28:29], v[44:45]
	s_movk_i32 s16, 0x200
	v_pk_fma_f32 v[24:25], v[22:23], v[26:27], v[24:25] neg_lo:[0,0,1] neg_hi:[0,0,1]
	v_pk_mul_f32 v[22:23], v[22:23], v[44:45]
	s_mov_b64 s[6:7], 0
	v_pk_fma_f32 v[22:23], v[28:29], v[26:27], v[22:23]
	s_and_b64 vcc, exec, vcc
	v_cndmask_b32_e64 v29, -v23, v25, s[4:5]
	v_mov_b32_e32 v23, v34
	s_waitcnt lgkmcnt(0)
	v_mov_b32_e32 v25, v50
	v_mov_b32_e32 v34, v31
	v_mov_b32_e32 v50, v47
	v_cndmask_b32_e64 v28, -v22, v24, s[4:5]
	v_mov_b32_e32 v22, v30
	v_mov_b32_e32 v24, v46
	v_pk_mul_f32 v[26:27], v[34:35], v[50:51]
	s_nop 0
	v_pk_fma_f32 v[26:27], v[22:23], v[24:25], v[26:27] neg_lo:[0,0,1] neg_hi:[0,0,1]
	v_pk_mul_f32 v[22:23], v[22:23], v[50:51]
	s_nop 0
	v_pk_fma_f32 v[22:23], v[34:35], v[24:25], v[22:23]
	v_mov_b32_e32 v25, v52
	v_cndmask_b32_e64 v30, -v23, v27, s[4:5]
	v_mov_b32_e32 v23, v36
	v_mov_b32_e32 v36, v33
	v_mov_b32_e32 v52, v49
	v_cndmask_b32_e64 v31, -v22, v26, s[4:5]
	v_mov_b32_e32 v22, v32
	v_mov_b32_e32 v24, v48
	v_pk_mul_f32 v[26:27], v[36:37], v[52:53]
	s_nop 0
	v_pk_fma_f32 v[26:27], v[22:23], v[24:25], v[26:27] neg_lo:[0,0,1] neg_hi:[0,0,1]
	v_pk_mul_f32 v[22:23], v[22:23], v[52:53]
	s_nop 0
	v_pk_fma_f32 v[22:23], v[36:37], v[24:25], v[22:23]
	s_nop 0
	v_cndmask_b32_e64 v22, -v22, v26, s[4:5]
	v_cndmask_b32_e64 v23, -v23, v27, s[4:5]
	v_bfe_u32 v24, v23, 16, 1
	v_bfe_u32 v25, v22, 16, 1
	v_bfe_u32 v26, v29, 16, 1
	v_bfe_u32 v27, v28, 16, 1
	v_add3_u32 v27, v28, v27, s9
	v_add3_u32 v26, v29, v26, s9
	v_add3_u32 v22, v22, v25, s9
	v_add3_u32 v23, v23, v24, s9
	v_bfe_u32 v24, v38, 16, 1
	v_bfe_u32 v25, v21, 16, 1
	v_bfe_u32 v28, v31, 16, 1
	v_bfe_u32 v29, v30, 16, 1
	v_add3_u32 v29, v30, v29, s9
	v_add3_u32 v28, v31, v28, s9
	v_add3_u32 v21, v21, v25, s9
	v_add3_u32 v24, v38, v24, s9
	v_lshrrev_b32_e32 v30, 16, v24
	v_lshrrev_b32_e32 v21, 16, v21
	v_lshrrev_b32_e32 v24, 16, v28
	v_lshrrev_b32_e32 v25, 16, v29
	v_and_or_b32 v25, v23, s14, v25
	v_and_or_b32 v24, v22, s14, v24
	v_and_or_b32 v23, v26, s14, v21
	v_and_or_b32 v22, v27, s14, v30
	v_lshlrev_b64 v[26:27], 8, v[54:55]
	v_lshl_add_u64 v[26:27], v[16:17], 0, v[26:27]
	global_store_dwordx4 v[26:27], v[22:25], off sc1
	s_cbranch_vccz .LBB0_465
	s_add_i32 s8, s8, 1
	s_cmp_eq_u32 s8, 4
	s_cbranch_scc0 .LBB0_462
	v_cmp_gt_i32_e32 vcc, 64, v10
	s_and_saveexec_b64 s[4:5], vcc
	s_cbranch_execz .LBB0_469
	s_lshl_b64 s[6:7], s[10:11], 3
	v_readlane_b32 s8, v255, 6
	v_readlane_b32 s9, v255, 7
	s_add_u32 s8, s8, s6
	ds_read2st64_b64 v[4:7], v20 offset0:1 offset1:16
	s_addc_u32 s9, s9, s7
	s_add_u32 s6, s18, s6
	s_addc_u32 s7, s19, s7
	v_lshlrev_b64 v[8:9], 3, v[10:11]
	v_lshl_add_u64 v[12:13], s[6:7], 0, v[8:9]
	s_waitcnt lgkmcnt(0)
	global_store_dwordx2 v[12:13], v[4:5], off
	v_lshl_add_u64 v[4:5], s[8:9], 0, v[8:9]
	global_store_dwordx2 v[4:5], v[6:7], off

.LBB0_793:
	v_lshl_or_b32 v202, s10, 8, v230
	v_lshl_add_u32 v204, s11, 8, v228
	v_ashrrev_i32_e32 v203, 31, v202
	v_lshlrev_b64 v[240:241], 1, v[202:203]
	v_ashrrev_i32_e32 v205, 31, v204
	v_or_b32_e32 v218, 16, v204
	v_lshl_add_u64 v[90:91], s[44:45], 0, v[240:241]
	v_lshlrev_b64 v[242:243], 11, v[204:205]
	v_ashrrev_i32_e32 v219, 31, v218
	v_or_b32_e32 v214, 32, v204
	v_lshl_add_u64 v[92:93], v[90:91], 0, v[242:243]
	v_lshlrev_b64 v[220:221], 11, v[218:219]
	v_ashrrev_i32_e32 v215, 31, v214
	v_or_b32_e32 v210, 48, v204
	global_load_dwordx4 v[232:235], v[92:93], off
	global_load_dwordx4 v[236:239], v[92:93], off offset:256
	v_lshl_add_u64 v[92:93], v[90:91], 0, v[220:221]
	v_lshlrev_b64 v[216:217], 11, v[214:215]
	v_ashrrev_i32_e32 v211, 31, v210
	v_add_u32_e32 v206, 0x80, v204
	global_load_dwordx4 v[182:185], v[92:93], off
	global_load_dwordx4 v[178:181], v[92:93], off offset:256
	v_lshl_add_u64 v[92:93], v[90:91], 0, v[216:217]
	v_lshlrev_b64 v[212:213], 11, v[210:211]
	v_ashrrev_i32_e32 v207, 31, v206
	global_load_dwordx4 v[174:177], v[92:93], off
	global_load_dwordx4 v[170:173], v[92:93], off offset:256
	v_lshl_add_u64 v[92:93], v[90:91], 0, v[212:213]
	v_lshlrev_b64 v[208:209], 11, v[206:207]
	global_load_dwordx4 v[166:169], v[92:93], off
	global_load_dwordx4 v[162:165], v[92:93], off offset:256
	v_lshl_add_u64 v[92:93], v[90:91], 0, v[208:209]
	global_load_dwordx4 v[154:157], v[92:93], off
	global_load_dwordx4 v[146:149], v[92:93], off offset:256
	v_add_u32_e32 v92, 0x90, v204
	v_ashrrev_i32_e32 v93, 31, v92
	v_lshlrev_b64 v[92:93], 11, v[92:93]
	v_lshl_add_u64 v[92:93], v[90:91], 0, v[92:93]
	global_load_dwordx4 v[142:145], v[92:93], off
	global_load_dwordx4 v[130:133], v[92:93], off offset:256
	v_add_u32_e32 v92, 0xa0, v204
	v_ashrrev_i32_e32 v93, 31, v92
	v_lshlrev_b64 v[92:93], 11, v[92:93]
	v_lshl_add_u64 v[92:93], v[90:91], 0, v[92:93]
	global_load_dwordx4 v[122:125], v[92:93], off
	global_load_dwordx4 v[114:117], v[92:93], off offset:256
	v_add_u32_e32 v92, 0xb0, v204
	v_ashrrev_i32_e32 v93, 31, v92
	v_lshlrev_b64 v[92:93], 11, v[92:93]
	v_lshl_add_u64 v[90:91], v[90:91], 0, v[92:93]
	global_load_dwordx4 v[102:105], v[90:91], off
	s_nop 0
	global_load_dwordx4 v[90:93], v[90:91], off offset:256
	v_lshl_add_u64 v[242:243], s[44:45], 0, v[242:243]
	v_lshl_add_u64 v[240:241], v[242:243], 0, v[240:241]
	s_waitcnt vmcnt(0)
	s_nop 0
	v_lshlrev_b32_e32 v242, 16, v232
	v_and_b32_e32 v243, 0xffff0000, v232
	v_lshlrev_b32_e32 v232, 16, v233
	v_and_b32_e32 v233, 0xffff0000, v233
	v_lshlrev_b32_e32 v244, 16, v234
	v_and_b32_e32 v245, 0xffff0000, v234
	v_lshlrev_b32_e32 v234, 16, v235
	v_and_b32_e32 v235, 0xffff0000, v235
	v_pk_add_f32 v[160:161], v[160:161], v[232:233]
	v_pk_add_f32 v[158:159], v[158:159], v[242:243]
	v_pk_add_f32 v[232:233], v[152:153], v[234:235]
	v_pk_add_f32 v[234:235], v[150:151], v[244:245]
	v_cvt_pk_bf16_f32 v150, v158, v159
	v_cvt_pk_bf16_f32 v151, v160, v161
	s_nop 0
	v_cvt_pk_bf16_f32 v152, v234, v235
	v_cvt_pk_bf16_f32 v153, v232, v233
	global_store_dwordx4 v[240:241], v[150:153], off sc1
	s_nop 1
	v_mul_f32_e32 v150, v159, v159
	v_mul_f32_e32 v151, v160, v160
	v_fmac_f32_e32 v150, v158, v158
	v_fmac_f32_e32 v151, v161, v161
	v_add_f32_e32 v150, v150, v151
	v_mul_f32_e32 v151, v234, v234
	v_fmac_f32_e32 v151, v235, v235
	v_add_f32_e32 v150, v151, v150
	v_mul_f32_e32 v151, v232, v232
	v_fmac_f32_e32 v151, v233, v233
	v_add_f32_e32 v232, v151, v150
	v_lshlrev_b32_e32 v150, 16, v236
	v_and_b32_e32 v151, 0xffff0000, v236
	v_lshlrev_b32_e32 v152, 16, v237
	v_and_b32_e32 v153, 0xffff0000, v237
	v_lshlrev_b32_e32 v158, 16, v238
	v_and_b32_e32 v159, 0xffff0000, v238
	v_lshlrev_b32_e32 v160, 16, v239
	v_and_b32_e32 v161, 0xffff0000, v239
	v_pk_add_f32 v[140:141], v[140:141], v[152:153]
	v_pk_add_f32 v[138:139], v[138:139], v[150:151]
	v_pk_add_f32 v[152:153], v[134:135], v[158:159]
	v_cvt_pk_bf16_f32 v134, v138, v139
	v_cvt_pk_bf16_f32 v135, v140, v141
	v_pk_add_f32 v[150:151], v[136:137], v[160:161]
	v_cvt_pk_bf16_f32 v136, v152, v153
	s_nop 0
	v_cvt_pk_bf16_f32 v137, v150, v151
	global_store_dwordx4 v[240:241], v[134:137], off offset:256 sc1
	s_nop 1
	v_mul_f32_e32 v134, v139, v139
	v_mul_f32_e32 v135, v140, v140
	v_fmac_f32_e32 v134, v138, v138
	v_fmac_f32_e32 v135, v141, v141
	v_add_f32_e32 v134, v134, v135
	v_mul_f32_e32 v135, v152, v152
	v_fmac_f32_e32 v135, v153, v153
	v_add_f32_e32 v134, v135, v134
	v_mul_f32_e32 v135, v150, v150
	v_fmac_f32_e32 v135, v151, v151
	v_add_f32_e32 v134, v135, v134
	v_add_f32_e32 v134, v232, v134
	ds_bpermute_b32 v135, v225, v134
	s_waitcnt lgkmcnt(0)
	v_add_f32_e32 v134, v134, v135
	ds_bpermute_b32 v135, v226, v134
	s_and_saveexec_b64 s[20:21], s[4:5]
	s_cbranch_execz .LBB0_795
	s_waitcnt lgkmcnt(0)
	v_add_f32_e32 v134, v134, v135
	v_fma_f32 v134, v134, s17, 0.5
	v_trunc_f32_e32 v134, v134
	v_mul_f32_e32 v135, 0x2f800000, v134
	v_floor_f32_e32 v135, v135
	v_fmac_f32_e32 v134, 0xcf800000, v135
	v_cvt_u32_f32_e32 v134, v134
	v_cvt_u32_f32_e32 v135, v135
	v_lshl_add_u64 v[136:137], v[204:205], 3, s[24:25]
	global_atomic_add_x2 v[136:137], v[134:135], off
.LBB0_795:
	s_or_b64 exec, exec, s[20:21]
	v_lshlrev_b32_e32 v136, 16, v182
	v_and_b32_e32 v137, 0xffff0000, v182
	v_lshlrev_b32_e32 v138, 16, v183
	v_and_b32_e32 v139, 0xffff0000, v183
	v_lshlrev_b32_e32 v140, 16, v184
	v_and_b32_e32 v141, 0xffff0000, v184
	v_lshlrev_b32_e32 v150, 16, v185
	v_and_b32_e32 v151, 0xffff0000, v185
	v_pk_add_f32 v[126:127], v[126:127], v[136:137]
	v_pk_add_f32 v[128:129], v[128:129], v[138:139]
	v_pk_add_f32 v[136:137], v[120:121], v[150:151]
	v_pk_add_f32 v[120:121], v[118:119], v[140:141]
	v_cvt_pk_bf16_f32 v118, v126, v127
	v_mul_f32_e32 v127, v127, v127
	v_fmac_f32_e32 v127, v126, v126
	v_mul_f32_e32 v126, v128, v128
	v_fmac_f32_e32 v126, v129, v129
	v_add_f32_e32 v126, v127, v126
	v_mul_f32_e32 v127, v120, v120
	v_fmac_f32_e32 v127, v121, v121
	v_add_f32_e32 v126, v127, v126
	v_mul_f32_e32 v127, v136, v136
	v_fmac_f32_e32 v127, v137, v137
	v_cvt_pk_bf16_f32 v119, v128, v129
	v_add_f32_e32 v150, v127, v126
	v_lshlrev_b32_e32 v126, 16, v178
	v_and_b32_e32 v127, 0xffff0000, v178
	v_lshlrev_b32_e32 v128, 16, v179
	v_and_b32_e32 v129, 0xffff0000, v179
	v_lshlrev_b32_e32 v138, 16, v180
	v_and_b32_e32 v139, 0xffff0000, v180
	v_pk_add_f32 v[112:113], v[112:113], v[128:129]
	v_pk_add_f32 v[110:111], v[110:111], v[126:127]
	v_pk_add_f32 v[128:129], v[106:107], v[138:139]
	v_mul_f32_e32 v106, v111, v111
	v_mul_f32_e32 v107, v112, v112
	v_fmac_f32_e32 v106, v110, v110
	v_fmac_f32_e32 v107, v113, v113
	v_lshlrev_b32_e32 v140, 16, v181
	v_and_b32_e32 v141, 0xffff0000, v181
	v_add_f32_e32 v106, v106, v107
	v_mul_f32_e32 v107, v128, v128
	v_pk_add_f32 v[126:127], v[108:109], v[140:141]
	v_fmac_f32_e32 v107, v129, v129
	v_add_f32_e32 v106, v107, v106
	v_mul_f32_e32 v107, v126, v126
	v_fmac_f32_e32 v107, v127, v127
	v_add_f32_e32 v106, v107, v106
	v_add_f32_e32 v106, v150, v106
	ds_bpermute_b32 v107, v225, v106
	s_waitcnt lgkmcnt(1)
	v_lshl_add_u64 v[134:135], s[44:45], 0, v[220:221]
	v_lshl_add_u64 v[134:135], v[202:203], 1, v[134:135]
	v_cvt_pk_bf16_f32 v120, v120, v121
	v_cvt_pk_bf16_f32 v121, v136, v137
	s_waitcnt lgkmcnt(0)
	v_add_f32_e32 v106, v106, v107
	ds_bpermute_b32 v107, v226, v106
	global_store_dwordx4 v[134:135], v[118:121], off sc1
	v_cvt_pk_bf16_f32 v108, v110, v111
	v_cvt_pk_bf16_f32 v109, v112, v113
	v_cvt_pk_bf16_f32 v110, v128, v129
	v_cvt_pk_bf16_f32 v111, v126, v127
	global_store_dwordx4 v[134:135], v[108:111], off offset:256 sc1
	s_and_saveexec_b64 s[20:21], s[4:5]
	s_cbranch_execz .LBB0_797
	s_waitcnt lgkmcnt(0)
	v_add_f32_e32 v106, v106, v107
	v_fma_f32 v106, v106, s17, 0.5
	v_trunc_f32_e32 v106, v106
	v_mul_f32_e32 v107, 0x2f800000, v106
	v_floor_f32_e32 v107, v107
	v_fmac_f32_e32 v106, 0xcf800000, v107
	v_cvt_u32_f32_e32 v106, v106
	v_cvt_u32_f32_e32 v107, v107
	v_lshl_add_u64 v[108:109], v[218:219], 3, s[24:25]
	global_atomic_add_x2 v[108:109], v[106:107], off
.LBB0_797:
	s_or_b64 exec, exec, s[20:21]
	v_lshlrev_b32_e32 v108, 16, v174
	v_and_b32_e32 v109, 0xffff0000, v174
	v_lshlrev_b32_e32 v110, 16, v175
	v_and_b32_e32 v111, 0xffff0000, v175
	v_lshlrev_b32_e32 v112, 16, v176
	v_and_b32_e32 v113, 0xffff0000, v176
	v_lshlrev_b32_e32 v118, 16, v177
	v_and_b32_e32 v119, 0xffff0000, v177
	v_pk_add_f32 v[98:99], v[98:99], v[108:109]
	v_pk_add_f32 v[100:101], v[100:101], v[110:111]
	v_pk_add_f32 v[108:109], v[96:97], v[118:119]
	v_pk_add_f32 v[96:97], v[94:95], v[112:113]
	v_cvt_pk_bf16_f32 v94, v98, v99
	v_mul_f32_e32 v99, v99, v99
	v_fmac_f32_e32 v99, v98, v98
	v_mul_f32_e32 v98, v100, v100
	v_fmac_f32_e32 v98, v101, v101
	v_add_f32_e32 v98, v99, v98
	v_mul_f32_e32 v99, v96, v96
	v_fmac_f32_e32 v99, v97, v97
	v_add_f32_e32 v98, v99, v98
	v_mul_f32_e32 v99, v108, v108
	v_fmac_f32_e32 v99, v109, v109
	v_cvt_pk_bf16_f32 v95, v100, v101
	v_add_f32_e32 v118, v99, v98
	v_lshlrev_b32_e32 v98, 16, v170
	v_and_b32_e32 v99, 0xffff0000, v170
	v_lshlrev_b32_e32 v100, 16, v171
	v_and_b32_e32 v101, 0xffff0000, v171
	v_lshlrev_b32_e32 v110, 16, v172
	v_and_b32_e32 v111, 0xffff0000, v172
	v_pk_add_f32 v[88:89], v[88:89], v[100:101]
	v_pk_add_f32 v[86:87], v[86:87], v[98:99]
	v_pk_add_f32 v[100:101], v[82:83], v[110:111]
	v_mul_f32_e32 v82, v87, v87
	v_mul_f32_e32 v83, v88, v88
	v_fmac_f32_e32 v82, v86, v86
	v_fmac_f32_e32 v83, v89, v89
	v_lshlrev_b32_e32 v112, 16, v173
	v_and_b32_e32 v113, 0xffff0000, v173
	v_add_f32_e32 v82, v82, v83
	v_mul_f32_e32 v83, v100, v100
	v_pk_add_f32 v[98:99], v[84:85], v[112:113]
	v_fmac_f32_e32 v83, v101, v101
	v_add_f32_e32 v82, v83, v82
	v_mul_f32_e32 v83, v98, v98
	v_fmac_f32_e32 v83, v99, v99
	v_add_f32_e32 v82, v83, v82
	v_add_f32_e32 v82, v118, v82
	ds_bpermute_b32 v83, v225, v82
	s_waitcnt lgkmcnt(1)
	v_lshl_add_u64 v[106:107], s[44:45], 0, v[216:217]
	v_lshl_add_u64 v[106:107], v[202:203], 1, v[106:107]
	v_cvt_pk_bf16_f32 v96, v96, v97
	v_cvt_pk_bf16_f32 v97, v108, v109
	s_waitcnt lgkmcnt(0)
	v_add_f32_e32 v82, v82, v83
	ds_bpermute_b32 v83, v226, v82
	global_store_dwordx4 v[106:107], v[94:97], off sc1
	v_cvt_pk_bf16_f32 v84, v86, v87
	v_cvt_pk_bf16_f32 v85, v88, v89
	v_cvt_pk_bf16_f32 v86, v100, v101
	v_cvt_pk_bf16_f32 v87, v98, v99
	global_store_dwordx4 v[106:107], v[84:87], off offset:256 sc1
	s_and_saveexec_b64 s[20:21], s[4:5]
	s_cbranch_execz .LBB0_799
	s_waitcnt lgkmcnt(0)
	v_add_f32_e32 v82, v82, v83
	v_fma_f32 v82, v82, s17, 0.5
	v_trunc_f32_e32 v82, v82
	v_mul_f32_e32 v83, 0x2f800000, v82
	v_floor_f32_e32 v83, v83
	v_fmac_f32_e32 v82, 0xcf800000, v83
	v_cvt_u32_f32_e32 v82, v82
	v_cvt_u32_f32_e32 v83, v83
	v_lshl_add_u64 v[84:85], v[214:215], 3, s[24:25]
	global_atomic_add_x2 v[84:85], v[82:83], off
.LBB0_799:
	s_or_b64 exec, exec, s[20:21]
	v_lshlrev_b32_e32 v84, 16, v166
	v_and_b32_e32 v85, 0xffff0000, v166
	v_lshlrev_b32_e32 v86, 16, v167
	v_and_b32_e32 v87, 0xffff0000, v167
	v_lshlrev_b32_e32 v88, 16, v168
	v_and_b32_e32 v89, 0xffff0000, v168
	v_lshlrev_b32_e32 v94, 16, v169
	v_and_b32_e32 v95, 0xffff0000, v169
	v_pk_add_f32 v[78:79], v[78:79], v[84:85]
	v_pk_add_f32 v[80:81], v[80:81], v[86:87]
	v_pk_add_f32 v[84:85], v[76:77], v[94:95]
	v_pk_add_f32 v[76:77], v[74:75], v[88:89]
	v_cvt_pk_bf16_f32 v74, v78, v79
	v_mul_f32_e32 v79, v79, v79
	v_fmac_f32_e32 v79, v78, v78
	v_mul_f32_e32 v78, v80, v80
	v_fmac_f32_e32 v78, v81, v81
	v_add_f32_e32 v78, v79, v78
	v_mul_f32_e32 v79, v76, v76
	v_fmac_f32_e32 v79, v77, v77
	v_add_f32_e32 v78, v79, v78
	v_mul_f32_e32 v79, v84, v84
	v_fmac_f32_e32 v79, v85, v85
	v_cvt_pk_bf16_f32 v75, v80, v81
	v_add_f32_e32 v94, v79, v78
	v_lshlrev_b32_e32 v78, 16, v162
	v_and_b32_e32 v79, 0xffff0000, v162
	v_lshlrev_b32_e32 v80, 16, v163
	v_and_b32_e32 v81, 0xffff0000, v163
	v_lshlrev_b32_e32 v86, 16, v164
	v_and_b32_e32 v87, 0xffff0000, v164
	v_pk_add_f32 v[72:73], v[72:73], v[80:81]
	v_pk_add_f32 v[70:71], v[70:71], v[78:79]
	v_pk_add_f32 v[80:81], v[66:67], v[86:87]
	v_mul_f32_e32 v66, v71, v71
	v_mul_f32_e32 v67, v72, v72
	v_fmac_f32_e32 v66, v70, v70
	v_fmac_f32_e32 v67, v73, v73
	v_lshlrev_b32_e32 v88, 16, v165
	v_and_b32_e32 v89, 0xffff0000, v165
	v_add_f32_e32 v66, v66, v67
	v_mul_f32_e32 v67, v80, v80
	v_pk_add_f32 v[78:79], v[68:69], v[88:89]
	v_fmac_f32_e32 v67, v81, v81
	v_add_f32_e32 v66, v67, v66
	v_mul_f32_e32 v67, v78, v78
	v_fmac_f32_e32 v67, v79, v79
	v_add_f32_e32 v66, v67, v66
	v_add_f32_e32 v66, v94, v66
	ds_bpermute_b32 v67, v225, v66
	s_waitcnt lgkmcnt(1)
	v_lshl_add_u64 v[82:83], s[44:45], 0, v[212:213]
	v_lshl_add_u64 v[82:83], v[202:203], 1, v[82:83]
	v_cvt_pk_bf16_f32 v76, v76, v77
	v_cvt_pk_bf16_f32 v77, v84, v85
	s_waitcnt lgkmcnt(0)
	v_add_f32_e32 v66, v66, v67
	ds_bpermute_b32 v67, v226, v66
	global_store_dwordx4 v[82:83], v[74:77], off sc1
	v_cvt_pk_bf16_f32 v68, v70, v71
	v_cvt_pk_bf16_f32 v69, v72, v73
	v_cvt_pk_bf16_f32 v70, v80, v81
	v_cvt_pk_bf16_f32 v71, v78, v79
	global_store_dwordx4 v[82:83], v[68:71], off offset:256 sc1
	s_and_saveexec_b64 s[20:21], s[4:5]
	s_cbranch_execz .LBB0_801
	s_waitcnt lgkmcnt(0)
	v_add_f32_e32 v66, v66, v67
	v_fma_f32 v66, v66, s17, 0.5
	v_trunc_f32_e32 v66, v66
	v_mul_f32_e32 v67, 0x2f800000, v66
	v_floor_f32_e32 v67, v67
	v_fmac_f32_e32 v66, 0xcf800000, v67
	v_cvt_u32_f32_e32 v66, v66
	v_cvt_u32_f32_e32 v67, v67
	v_lshl_add_u64 v[68:69], v[210:211], 3, s[24:25]
	global_atomic_add_x2 v[68:69], v[66:67], off
.LBB0_801:
	s_or_b64 exec, exec, s[20:21]
	v_lshlrev_b32_e32 v68, 16, v154
	v_and_b32_e32 v69, 0xffff0000, v154
	v_lshlrev_b32_e32 v70, 16, v155
	v_and_b32_e32 v71, 0xffff0000, v155
	v_lshlrev_b32_e32 v72, 16, v156
	v_and_b32_e32 v73, 0xffff0000, v156
	v_lshlrev_b32_e32 v74, 16, v157
	v_and_b32_e32 v75, 0xffff0000, v157
	v_pk_add_f32 v[62:63], v[62:63], v[68:69]
	v_pk_add_f32 v[64:65], v[64:65], v[70:71]
	v_pk_add_f32 v[68:69], v[60:61], v[74:75]
	v_pk_add_f32 v[60:61], v[58:59], v[72:73]
	v_cvt_pk_bf16_f32 v58, v62, v63
	v_mul_f32_e32 v63, v63, v63
	v_fmac_f32_e32 v63, v62, v62
	v_mul_f32_e32 v62, v64, v64
	v_fmac_f32_e32 v62, v65, v65
	v_add_f32_e32 v62, v63, v62
	v_mul_f32_e32 v63, v60, v60
	v_fmac_f32_e32 v63, v61, v61
	v_add_f32_e32 v62, v63, v62
	v_mul_f32_e32 v63, v68, v68
	v_fmac_f32_e32 v63, v69, v69
	v_cvt_pk_bf16_f32 v59, v64, v65
	v_add_f32_e32 v74, v63, v62
	v_lshlrev_b32_e32 v62, 16, v146
	v_and_b32_e32 v63, 0xffff0000, v146
	v_lshlrev_b32_e32 v64, 16, v147
	v_and_b32_e32 v65, 0xffff0000, v147
	v_lshlrev_b32_e32 v70, 16, v148
	v_and_b32_e32 v71, 0xffff0000, v148
	v_pk_add_f32 v[56:57], v[56:57], v[64:65]
	v_pk_add_f32 v[54:55], v[54:55], v[62:63]
	v_pk_add_f32 v[64:65], v[50:51], v[70:71]
	v_mul_f32_e32 v50, v55, v55
	v_mul_f32_e32 v51, v56, v56
	v_fmac_f32_e32 v50, v54, v54
	v_fmac_f32_e32 v51, v57, v57
	v_lshlrev_b32_e32 v72, 16, v149
	v_and_b32_e32 v73, 0xffff0000, v149
	v_add_f32_e32 v50, v50, v51
	v_mul_f32_e32 v51, v64, v64
	v_pk_add_f32 v[62:63], v[52:53], v[72:73]
	v_fmac_f32_e32 v51, v65, v65
	v_add_f32_e32 v50, v51, v50
	v_mul_f32_e32 v51, v62, v62
	v_fmac_f32_e32 v51, v63, v63
	v_add_f32_e32 v50, v51, v50
	v_add_f32_e32 v50, v74, v50
	ds_bpermute_b32 v51, v225, v50
	s_waitcnt lgkmcnt(1)
	v_lshl_add_u64 v[66:67], s[44:45], 0, v[208:209]
	v_lshl_add_u64 v[66:67], v[202:203], 1, v[66:67]
	v_cvt_pk_bf16_f32 v60, v60, v61
	v_cvt_pk_bf16_f32 v61, v68, v69
	s_waitcnt lgkmcnt(0)
	v_add_f32_e32 v50, v50, v51
	ds_bpermute_b32 v51, v226, v50
	global_store_dwordx4 v[66:67], v[58:61], off sc1
	v_cvt_pk_bf16_f32 v52, v54, v55
	v_cvt_pk_bf16_f32 v53, v56, v57
	v_cvt_pk_bf16_f32 v54, v64, v65
	v_cvt_pk_bf16_f32 v55, v62, v63
	global_store_dwordx4 v[66:67], v[52:55], off offset:256 sc1
	s_and_saveexec_b64 s[20:21], s[4:5]
	s_cbranch_execz .LBB0_803
	s_waitcnt lgkmcnt(0)
	v_add_f32_e32 v50, v50, v51
	v_fma_f32 v50, v50, s17, 0.5
	v_trunc_f32_e32 v50, v50
	v_mul_f32_e32 v51, 0x2f800000, v50
	v_floor_f32_e32 v51, v51
	v_fmac_f32_e32 v50, 0xcf800000, v51
	v_cvt_u32_f32_e32 v50, v50
	v_cvt_u32_f32_e32 v51, v51
	v_lshl_add_u64 v[52:53], v[206:207], 3, s[24:25]
	global_atomic_add_x2 v[52:53], v[50:51], off
.LBB0_803:
	s_or_b64 exec, exec, s[20:21]
	v_lshlrev_b32_e32 v54, 16, v142
	v_and_b32_e32 v55, 0xffff0000, v142
	v_lshlrev_b32_e32 v56, 16, v143
	v_and_b32_e32 v57, 0xffff0000, v143
	v_lshlrev_b32_e32 v58, 16, v144
	v_and_b32_e32 v59, 0xffff0000, v144
	v_lshlrev_b32_e32 v60, 16, v145
	v_and_b32_e32 v61, 0xffff0000, v145
	v_pk_add_f32 v[46:47], v[46:47], v[54:55]
	v_pk_add_f32 v[48:49], v[48:49], v[56:57]
	v_pk_add_f32 v[54:55], v[44:45], v[60:61]
	v_pk_add_f32 v[44:45], v[42:43], v[58:59]
	v_cvt_pk_bf16_f32 v42, v46, v47
	v_mul_f32_e32 v47, v47, v47
	v_fmac_f32_e32 v47, v46, v46
	v_mul_f32_e32 v46, v48, v48
	v_fmac_f32_e32 v46, v49, v49
	v_add_f32_e32 v46, v47, v46
	v_mul_f32_e32 v47, v44, v44
	v_fmac_f32_e32 v47, v45, v45
	v_add_f32_e32 v46, v47, v46
	v_mul_f32_e32 v47, v54, v54
	v_fmac_f32_e32 v47, v55, v55
	v_cvt_pk_bf16_f32 v43, v48, v49
	v_add_f32_e32 v60, v47, v46
	v_lshlrev_b32_e32 v46, 16, v130
	v_and_b32_e32 v47, 0xffff0000, v130
	v_lshlrev_b32_e32 v48, 16, v131
	v_and_b32_e32 v49, 0xffff0000, v131
	v_lshlrev_b32_e32 v56, 16, v132
	v_and_b32_e32 v57, 0xffff0000, v132
	v_pk_add_f32 v[40:41], v[40:41], v[48:49]
	v_pk_add_f32 v[38:39], v[38:39], v[46:47]
	v_pk_add_f32 v[48:49], v[34:35], v[56:57]
	v_mul_f32_e32 v34, v39, v39
	v_mul_f32_e32 v35, v40, v40
	v_fmac_f32_e32 v34, v38, v38
	v_fmac_f32_e32 v35, v41, v41
	v_lshlrev_b32_e32 v58, 16, v133
	v_and_b32_e32 v59, 0xffff0000, v133
	v_add_f32_e32 v34, v34, v35
	v_mul_f32_e32 v35, v48, v48
	v_pk_add_f32 v[46:47], v[36:37], v[58:59]
	v_fmac_f32_e32 v35, v49, v49
	v_add_f32_e32 v34, v35, v34
	v_mul_f32_e32 v35, v46, v46
	v_fmac_f32_e32 v35, v47, v47
	v_add_f32_e32 v34, v35, v34
	v_add_f32_e32 v34, v60, v34
	ds_bpermute_b32 v35, v225, v34
	v_add_u32_e32 v50, 0x90, v204
	s_waitcnt lgkmcnt(1)
	v_ashrrev_i32_e32 v51, 31, v50
	v_lshlrev_b64 v[52:53], 11, v[50:51]
	v_lshl_add_u64 v[52:53], s[44:45], 0, v[52:53]
	s_waitcnt lgkmcnt(0)
	v_add_f32_e32 v34, v34, v35
	ds_bpermute_b32 v35, v226, v34
	v_lshl_add_u64 v[52:53], v[202:203], 1, v[52:53]
	v_cvt_pk_bf16_f32 v44, v44, v45
	v_cvt_pk_bf16_f32 v45, v54, v55
	global_store_dwordx4 v[52:53], v[42:45], off sc1
	v_cvt_pk_bf16_f32 v36, v38, v39
	v_cvt_pk_bf16_f32 v37, v40, v41
	v_cvt_pk_bf16_f32 v38, v48, v49
	v_cvt_pk_bf16_f32 v39, v46, v47
	global_store_dwordx4 v[52:53], v[36:39], off offset:256 sc1
	s_and_saveexec_b64 s[20:21], s[4:5]
	s_cbranch_execz .LBB0_805
	s_waitcnt lgkmcnt(0)
	v_add_f32_e32 v34, v34, v35
	v_fma_f32 v34, v34, s17, 0.5
	v_trunc_f32_e32 v34, v34
	v_mul_f32_e32 v35, 0x2f800000, v34
	v_floor_f32_e32 v35, v35
	v_fmac_f32_e32 v34, 0xcf800000, v35
	v_cvt_u32_f32_e32 v34, v34
	v_cvt_u32_f32_e32 v35, v35
	v_lshl_add_u64 v[36:37], v[50:51], 3, s[24:25]
	global_atomic_add_x2 v[36:37], v[34:35], off
.LBB0_805:
	s_or_b64 exec, exec, s[20:21]
	v_lshlrev_b32_e32 v38, 16, v122
	v_and_b32_e32 v39, 0xffff0000, v122
	v_lshlrev_b32_e32 v40, 16, v123
	v_and_b32_e32 v41, 0xffff0000, v123
	v_lshlrev_b32_e32 v42, 16, v124
	v_and_b32_e32 v43, 0xffff0000, v124
	v_lshlrev_b32_e32 v44, 16, v125
	v_and_b32_e32 v45, 0xffff0000, v125
	v_pk_add_f32 v[30:31], v[30:31], v[38:39]
	v_pk_add_f32 v[32:33], v[32:33], v[40:41]
	v_pk_add_f32 v[38:39], v[28:29], v[44:45]
	v_pk_add_f32 v[28:29], v[26:27], v[42:43]
	v_cvt_pk_bf16_f32 v26, v30, v31
	v_mul_f32_e32 v31, v31, v31
	v_fmac_f32_e32 v31, v30, v30
	v_mul_f32_e32 v30, v32, v32
	v_fmac_f32_e32 v30, v33, v33
	v_add_f32_e32 v30, v31, v30
	v_mul_f32_e32 v31, v28, v28
	v_fmac_f32_e32 v31, v29, v29
	v_add_f32_e32 v30, v31, v30
	v_mul_f32_e32 v31, v38, v38
	v_fmac_f32_e32 v31, v39, v39
	v_cvt_pk_bf16_f32 v27, v32, v33
	v_add_f32_e32 v44, v31, v30
	v_lshlrev_b32_e32 v30, 16, v114
	v_and_b32_e32 v31, 0xffff0000, v114
	v_lshlrev_b32_e32 v32, 16, v115
	v_and_b32_e32 v33, 0xffff0000, v115
	v_lshlrev_b32_e32 v40, 16, v116
	v_and_b32_e32 v41, 0xffff0000, v116
	v_pk_add_f32 v[24:25], v[24:25], v[32:33]
	v_pk_add_f32 v[22:23], v[22:23], v[30:31]
	v_pk_add_f32 v[32:33], v[18:19], v[40:41]
	v_mul_f32_e32 v18, v23, v23
	v_mul_f32_e32 v19, v24, v24
	v_fmac_f32_e32 v18, v22, v22
	v_fmac_f32_e32 v19, v25, v25
	v_lshlrev_b32_e32 v42, 16, v117
	v_and_b32_e32 v43, 0xffff0000, v117
	v_add_f32_e32 v18, v18, v19
	v_mul_f32_e32 v19, v32, v32
	v_pk_add_f32 v[30:31], v[20:21], v[42:43]
	v_fmac_f32_e32 v19, v33, v33
	v_add_f32_e32 v18, v19, v18
	v_mul_f32_e32 v19, v30, v30
	v_fmac_f32_e32 v19, v31, v31
	v_add_f32_e32 v18, v19, v18
	v_add_f32_e32 v18, v44, v18
	ds_bpermute_b32 v19, v225, v18
	v_add_u32_e32 v34, 0xa0, v204
	s_waitcnt lgkmcnt(1)
	v_ashrrev_i32_e32 v35, 31, v34
	v_lshlrev_b64 v[36:37], 11, v[34:35]
	v_lshl_add_u64 v[36:37], s[44:45], 0, v[36:37]
	s_waitcnt lgkmcnt(0)
	v_add_f32_e32 v18, v18, v19
	ds_bpermute_b32 v19, v226, v18
	v_lshl_add_u64 v[36:37], v[202:203], 1, v[36:37]
	v_cvt_pk_bf16_f32 v28, v28, v29
	v_cvt_pk_bf16_f32 v29, v38, v39
	global_store_dwordx4 v[36:37], v[26:29], off sc1
	v_cvt_pk_bf16_f32 v20, v22, v23
	v_cvt_pk_bf16_f32 v21, v24, v25
	v_cvt_pk_bf16_f32 v22, v32, v33
	v_cvt_pk_bf16_f32 v23, v30, v31
	global_store_dwordx4 v[36:37], v[20:23], off offset:256 sc1
	s_and_saveexec_b64 s[20:21], s[4:5]
	s_cbranch_execz .LBB0_807
	s_waitcnt lgkmcnt(0)
	v_add_f32_e32 v18, v18, v19
	v_fma_f32 v18, v18, s17, 0.5
	v_trunc_f32_e32 v18, v18
	v_mul_f32_e32 v19, 0x2f800000, v18
	v_floor_f32_e32 v19, v19
	v_fmac_f32_e32 v18, 0xcf800000, v19
	v_cvt_u32_f32_e32 v18, v18
	v_cvt_u32_f32_e32 v19, v19
	v_lshl_add_u64 v[20:21], v[34:35], 3, s[24:25]
	global_atomic_add_x2 v[20:21], v[18:19], off
.LBB0_807:
	s_or_b64 exec, exec, s[20:21]
	v_lshlrev_b32_e32 v22, 16, v102
	v_and_b32_e32 v23, 0xffff0000, v102
	v_lshlrev_b32_e32 v24, 16, v103
	v_and_b32_e32 v25, 0xffff0000, v103
	v_lshlrev_b32_e32 v26, 16, v104
	v_and_b32_e32 v27, 0xffff0000, v104
	v_lshlrev_b32_e32 v28, 16, v105
	v_and_b32_e32 v29, 0xffff0000, v105
	v_pk_add_f32 v[14:15], v[14:15], v[22:23]
	v_pk_add_f32 v[16:17], v[16:17], v[24:25]
	v_pk_add_f32 v[22:23], v[12:13], v[28:29]
	v_pk_add_f32 v[12:13], v[10:11], v[26:27]
	v_cvt_pk_bf16_f32 v10, v14, v15
	v_mul_f32_e32 v15, v15, v15
	v_fmac_f32_e32 v15, v14, v14
	v_mul_f32_e32 v14, v16, v16
	v_fmac_f32_e32 v14, v17, v17
	v_add_f32_e32 v14, v15, v14
	v_mul_f32_e32 v15, v12, v12
	v_fmac_f32_e32 v15, v13, v13
	v_add_f32_e32 v14, v15, v14
	v_mul_f32_e32 v15, v22, v22
	v_fmac_f32_e32 v15, v23, v23
	v_cvt_pk_bf16_f32 v11, v16, v17
	v_add_f32_e32 v28, v15, v14
	v_lshlrev_b32_e32 v14, 16, v90
	v_and_b32_e32 v15, 0xffff0000, v90
	v_lshlrev_b32_e32 v16, 16, v91
	v_and_b32_e32 v17, 0xffff0000, v91
	v_lshlrev_b32_e32 v24, 16, v92
	v_and_b32_e32 v25, 0xffff0000, v92
	v_pk_add_f32 v[8:9], v[8:9], v[16:17]
	v_pk_add_f32 v[6:7], v[6:7], v[14:15]
	v_pk_add_f32 v[16:17], v[2:3], v[24:25]
	v_mul_f32_e32 v2, v7, v7
	v_mul_f32_e32 v3, v8, v8
	v_fmac_f32_e32 v2, v6, v6
	v_fmac_f32_e32 v3, v9, v9
	v_lshlrev_b32_e32 v26, 16, v93
	v_and_b32_e32 v27, 0xffff0000, v93
	v_add_f32_e32 v2, v2, v3
	v_mul_f32_e32 v3, v16, v16
	v_pk_add_f32 v[14:15], v[4:5], v[26:27]
	v_fmac_f32_e32 v3, v17, v17
	v_add_f32_e32 v2, v3, v2
	v_mul_f32_e32 v3, v14, v14
	v_fmac_f32_e32 v3, v15, v15
	v_add_f32_e32 v2, v3, v2
	v_add_f32_e32 v2, v28, v2
	ds_bpermute_b32 v3, v225, v2
	v_add_u32_e32 v18, 0xb0, v204
	s_waitcnt lgkmcnt(1)
	v_ashrrev_i32_e32 v19, 31, v18
	v_lshlrev_b64 v[20:21], 11, v[18:19]
	v_lshl_add_u64 v[20:21], s[44:45], 0, v[20:21]
	s_waitcnt lgkmcnt(0)
	v_add_f32_e32 v2, v2, v3
	ds_bpermute_b32 v3, v226, v2
	v_lshl_add_u64 v[20:21], v[202:203], 1, v[20:21]
	v_cvt_pk_bf16_f32 v12, v12, v13
	v_cvt_pk_bf16_f32 v13, v22, v23
	global_store_dwordx4 v[20:21], v[10:13], off sc1
	v_cvt_pk_bf16_f32 v4, v6, v7
	v_cvt_pk_bf16_f32 v5, v8, v9
	v_cvt_pk_bf16_f32 v6, v16, v17
	v_cvt_pk_bf16_f32 v7, v14, v15
	global_store_dwordx4 v[20:21], v[4:7], off offset:256 sc1
	s_and_saveexec_b64 s[20:21], s[4:5]
	s_cbranch_execz .LBB0_809
	s_waitcnt lgkmcnt(0)
	v_add_f32_e32 v2, v2, v3
	v_fma_f32 v2, v2, s17, 0.5
	v_trunc_f32_e32 v2, v2
	v_mul_f32_e32 v3, 0x2f800000, v2
	v_floor_f32_e32 v3, v3
	v_fmac_f32_e32 v2, 0xcf800000, v3
	v_cvt_u32_f32_e32 v2, v2
	v_cvt_u32_f32_e32 v3, v3
	v_lshl_add_u64 v[4:5], v[18:19], 3, s[24:25]
	global_atomic_add_x2 v[4:5], v[2:3], off

.LBB0_880:
	v_lshl_add_u32 v146, s54, 8, v160
	v_ashrrev_i32_e32 v147, 31, v146
	v_lshl_add_u64 v[148:149], v[146:147], 3, s[24:25]
	global_load_dwordx2 v[168:169], v[148:149], off nt
	global_load_dwordx2 v[170:171], v[148:149], off offset:128 nt
	global_load_dwordx2 v[158:159], v[148:149], off offset:256 nt
	global_load_dwordx2 v[156:157], v[148:149], off offset:384 nt
	global_load_dwordx2 v[154:155], v[148:149], off offset:1024 nt
	global_load_dwordx2 v[152:153], v[148:149], off offset:1152 nt
	global_load_dwordx2 v[150:151], v[148:149], off offset:1280 nt
	s_nop 0
	global_load_dwordx2 v[148:149], v[148:149], off offset:1408 nt
	v_lshl_or_b32 v172, s50, 7, v162
	v_pk_mul_f32 v[174:175], v[114:115], v[122:123]
	v_mov_b64_e32 v[122:123], s[18:19]
	v_ashrrev_i32_e32 v173, 31, v172
	v_pk_mul_f32 v[176:177], v[106:107], v[110:111]
	v_mad_i64_i32 v[178:179], s[20:21], v146, s47, v[122:123]
	v_lshlrev_b64 v[110:111], 1, v[172:173]
	v_pk_mul_f32 v[128:129], v[120:121], v[128:129]
	v_pk_mul_f32 v[126:127], v[118:119], v[126:127]
	v_pk_mul_f32 v[124:125], v[116:117], v[124:125]
	v_pk_mul_f32 v[112:113], v[108:109], v[112:113]
	v_pk_mul_f32 v[100:101], v[104:105], v[100:101]
	v_pk_mul_f32 v[98:99], v[102:103], v[98:99]
	v_pk_mul_f32 v[88:89], v[96:97], v[88:89]
	v_pk_mul_f32 v[86:87], v[94:95], v[86:87]
	v_pk_mul_f32 v[84:85], v[92:93], v[84:85]
	v_pk_mul_f32 v[82:83], v[90:91], v[82:83]
	v_pk_mul_f32 v[72:73], v[80:81], v[72:73]
	v_pk_mul_f32 v[70:71], v[78:79], v[70:71]
	v_pk_mul_f32 v[68:69], v[76:77], v[68:69]
	v_pk_mul_f32 v[66:67], v[74:75], v[66:67]
	v_pk_mul_f32 v[56:57], v[64:65], v[56:57]
	v_pk_mul_f32 v[54:55], v[62:63], v[54:55]
	v_pk_mul_f32 v[52:53], v[60:61], v[52:53]
	v_pk_mul_f32 v[50:51], v[58:59], v[50:51]
	v_pk_mul_f32 v[40:41], v[48:49], v[40:41]
	v_pk_mul_f32 v[38:39], v[46:47], v[38:39]
	v_pk_mul_f32 v[36:37], v[44:45], v[36:37]
	v_pk_mul_f32 v[34:35], v[42:43], v[34:35]
	v_pk_mul_f32 v[24:25], v[32:33], v[24:25]
	v_pk_mul_f32 v[22:23], v[30:31], v[22:23]
	v_pk_mul_f32 v[20:21], v[28:29], v[20:21]
	v_pk_mul_f32 v[18:19], v[26:27], v[18:19]
	v_pk_mul_f32 v[8:9], v[16:17], v[8:9]
	v_pk_mul_f32 v[6:7], v[14:15], v[6:7]
	v_pk_mul_f32 v[4:5], v[12:13], v[4:5]
	v_pk_mul_f32 v[2:3], v[10:11], v[2:3]
	s_andn2_b64 vcc, exec, s[4:5]
	s_mov_b64 s[4:5], -1
	s_waitcnt vmcnt(0)
	s_nop 0
	v_ffbh_u32_e32 v147, v169
	v_ffbh_u32_e32 v167, v171
	v_min_u32_e32 v147, 32, v147
	v_min_u32_e32 v167, 32, v167
	v_lshlrev_b64 v[168:169], v147, v[168:169]
	v_lshlrev_b64 v[170:171], v167, v[170:171]
	v_min_u32_e32 v168, 1, v168
	v_min_u32_e32 v170, 1, v170
	v_or_b32_e32 v168, v169, v168
	v_or_b32_e32 v169, v171, v170
	v_cvt_f32_u32_e32 v168, v168
	v_cvt_f32_u32_e32 v169, v169
	v_sub_u32_e32 v147, 32, v147
	v_sub_u32_e32 v167, 32, v167
	v_ldexp_f32 v147, v168, v147
	v_ldexp_f32 v167, v169, v167
	v_fmamk_f32 v147, v147, 0x30800000, v166
	v_fmamk_f32 v167, v167, 0x30800000, v166
	v_rsq_f32_e32 v147, v147
	v_rsq_f32_e32 v167, v167
	v_lshl_add_u64 v[168:169], v[178:179], 0, v[110:111]
	v_mul_f32_e32 v170, 0xbfb8aa3b, v147
	v_mul_f32_e32 v178, 0xbfb8aa3b, v167
	v_pk_mul_f32 v[120:121], v[120:121], v[170:171] op_sel_hi:[1,0]
	v_pk_mul_f32 v[118:119], v[118:119], v[170:171] op_sel_hi:[1,0]
	v_pk_mul_f32 v[116:117], v[116:117], v[170:171] op_sel_hi:[1,0]
	v_pk_mul_f32 v[114:115], v[114:115], v[170:171] op_sel_hi:[1,0]
	v_pk_mul_f32 v[108:109], v[108:109], v[178:179] op_sel_hi:[1,0]
	v_pk_mul_f32 v[106:107], v[106:107], v[178:179] op_sel_hi:[1,0]
	v_pk_mul_f32 v[170:171], v[104:105], v[178:179] op_sel_hi:[1,0]
	v_pk_mul_f32 v[178:179], v[102:103], v[178:179] op_sel_hi:[1,0]
	v_exp_f32_e32 v118, v118
	v_exp_f32_e32 v119, v119
	v_exp_f32_e32 v120, v120
	v_exp_f32_e32 v121, v121
	v_exp_f32_e32 v116, v116
	v_exp_f32_e32 v117, v117
	v_exp_f32_e32 v106, v106
	v_exp_f32_e32 v107, v107
	v_exp_f32_e32 v178, v178
	v_exp_f32_e32 v179, v179
	v_exp_f32_e32 v170, v170
	v_exp_f32_e32 v171, v171
	v_exp_f32_e32 v114, v114
	v_exp_f32_e32 v115, v115
	v_exp_f32_e32 v108, v108
	v_exp_f32_e32 v109, v109
	v_pk_add_f32 v[120:121], v[120:121], 1.0 op_sel_hi:[1,0]
	v_pk_add_f32 v[118:119], v[118:119], 1.0 op_sel_hi:[1,0]
	v_pk_add_f32 v[116:117], v[116:117], 1.0 op_sel_hi:[1,0]
	v_pk_add_f32 v[106:107], v[106:107], 1.0 op_sel_hi:[1,0]
	v_pk_add_f32 v[170:171], v[170:171], 1.0 op_sel_hi:[1,0]
	v_pk_add_f32 v[178:179], v[178:179], 1.0 op_sel_hi:[1,0]
	v_pk_add_f32 v[114:115], v[114:115], 1.0 op_sel_hi:[1,0]
	v_pk_add_f32 v[108:109], v[108:109], 1.0 op_sel_hi:[1,0]
	v_rcp_f32_e32 v118, v118
	v_rcp_f32_e32 v119, v119
	v_rcp_f32_e32 v120, v120
	v_rcp_f32_e32 v121, v121
	v_rcp_f32_e32 v116, v116
	v_rcp_f32_e32 v117, v117
	v_rcp_f32_e32 v106, v106
	v_rcp_f32_e32 v107, v107
	v_rcp_f32_e32 v178, v178
	v_rcp_f32_e32 v179, v179
	v_rcp_f32_e32 v170, v170
	v_rcp_f32_e32 v171, v171
	v_rcp_f32_e32 v114, v114
	v_rcp_f32_e32 v115, v115
	v_rcp_f32_e32 v108, v108
	v_rcp_f32_e32 v109, v109
	v_mul_f32_e32 v172, v147, v147
	v_mul_f32_e32 v180, v167, v167
	v_pk_mul_f32 v[118:119], v[172:173], v[118:119] op_sel_hi:[0,1]
	v_pk_mul_f32 v[120:121], v[172:173], v[120:121] op_sel_hi:[0,1]
	v_pk_mul_f32 v[116:117], v[172:173], v[116:117] op_sel_hi:[0,1]
	v_pk_mul_f32 v[106:107], v[180:181], v[106:107] op_sel_hi:[0,1]
	v_pk_mul_f32 v[102:103], v[180:181], v[178:179] op_sel_hi:[0,1]
	v_pk_mul_f32 v[104:105], v[180:181], v[170:171] op_sel_hi:[0,1]
	v_pk_mul_f32 v[114:115], v[172:173], v[114:115] op_sel_hi:[0,1]
	v_pk_mul_f32 v[108:109], v[180:181], v[108:109] op_sel_hi:[0,1]
	v_pk_mul_f32 v[120:121], v[128:129], v[120:121]
	v_pk_mul_f32 v[118:119], v[126:127], v[118:119]
	v_pk_mul_f32 v[116:117], v[124:125], v[116:117]
	v_pk_mul_f32 v[124:125], v[176:177], v[106:107]
	v_cvt_pk_bf16_f32 v106, v118, v119
	v_cvt_pk_bf16_f32 v107, v120, v121
	v_pk_mul_f32 v[104:105], v[100:101], v[104:105]
	v_pk_mul_f32 v[100:101], v[98:99], v[102:103]
	v_ffbh_u32_e32 v102, v159
	v_pk_mul_f32 v[114:115], v[174:175], v[114:115]
	v_pk_mul_f32 v[112:113], v[112:113], v[108:109]
	v_cvt_pk_bf16_f32 v108, v114, v115
	v_cvt_pk_bf16_f32 v109, v116, v117
	global_store_dwordx4 v[168:169], v[106:109], off sc1
	v_cvt_pk_bf16_f32 v98, v124, v125
	v_cvt_pk_bf16_f32 v99, v112, v113
	v_cvt_pk_bf16_f32 v100, v100, v101
	v_cvt_pk_bf16_f32 v101, v104, v105
	s_nop 1
	v_min_u32_e32 v107, 32, v102
	v_lshlrev_b64 v[102:103], v107, v[158:159]
	v_min_u32_e32 v102, 1, v102
	v_or_b32_e32 v102, v103, v102
	v_cvt_f32_u32_e32 v102, v102
	v_sub_u32_e32 v103, 32, v107
	v_or_b32_e32 v106, 16, v146
	v_ldexp_f32 v102, v102, v103
	v_fmamk_f32 v102, v102, 0x30800000, v166
	v_rsq_f32_e32 v107, v102
	v_mad_i64_i32 v[102:103], s[20:21], v106, s47, v[122:123]
	v_lshl_add_u64 v[102:103], v[102:103], 0, v[110:111]
	global_store_dwordx4 v[102:103], v[98:101], off sc1
	v_mul_f32_e32 v106, v107, v107
	s_nop 0
	v_mul_f32_e32 v98, 0xbfb8aa3b, v107
	v_pk_mul_f32 v[100:101], v[96:97], v[98:99] op_sel_hi:[1,0]
	v_pk_mul_f32 v[102:103], v[94:95], v[98:99] op_sel_hi:[1,0]
	v_exp_f32_e32 v100, v100
	v_exp_f32_e32 v102, v102
	v_exp_f32_e32 v103, v103
	v_exp_f32_e32 v101, v101
	v_pk_mul_f32 v[104:105], v[92:93], v[98:99] op_sel_hi:[1,0]
	v_pk_mul_f32 v[98:99], v[90:91], v[98:99] op_sel_hi:[1,0]
	v_pk_add_f32 v[102:103], v[102:103], 1.0 op_sel_hi:[1,0]
	v_pk_add_f32 v[100:101], v[100:101], 1.0 op_sel_hi:[1,0]
	v_rcp_f32_e32 v102, v102
	v_rcp_f32_e32 v103, v103
	v_rcp_f32_e32 v100, v100
	v_rcp_f32_e32 v101, v101
	v_exp_f32_e32 v98, v98
	v_exp_f32_e32 v99, v99
	v_exp_f32_e32 v104, v104
	v_exp_f32_e32 v105, v105
	v_pk_mul_f32 v[94:95], v[106:107], v[102:103] op_sel_hi:[0,1]
	v_pk_mul_f32 v[96:97], v[106:107], v[100:101] op_sel_hi:[0,1]
	v_pk_mul_f32 v[88:89], v[88:89], v[96:97]
	v_pk_mul_f32 v[86:87], v[86:87], v[94:95]
	v_pk_add_f32 v[94:95], v[104:105], 1.0 op_sel_hi:[1,0]
	v_pk_add_f32 v[96:97], v[98:99], 1.0 op_sel_hi:[1,0]
	v_rcp_f32_e32 v94, v94
	v_rcp_f32_e32 v96, v96
	v_rcp_f32_e32 v97, v97
	v_rcp_f32_e32 v95, v95
	v_pk_mul_f32 v[90:91], v[106:107], v[96:97] op_sel_hi:[0,1]
	v_pk_mul_f32 v[92:93], v[106:107], v[94:95] op_sel_hi:[0,1]
	v_pk_mul_f32 v[92:93], v[84:85], v[92:93]
	v_pk_mul_f32 v[84:85], v[82:83], v[90:91]
	v_cvt_pk_bf16_f32 v82, v86, v87
	v_ffbh_u32_e32 v86, v157
	v_cvt_pk_bf16_f32 v83, v88, v89
	v_min_u32_e32 v88, 32, v86
	v_lshlrev_b64 v[86:87], v88, v[156:157]
	v_min_u32_e32 v86, 1, v86
	v_or_b32_e32 v86, v87, v86
	v_cvt_f32_u32_e32 v86, v86
	v_sub_u32_e32 v87, 32, v88
	v_or_b32_e32 v90, 32, v146
	v_cvt_pk_bf16_f32 v84, v84, v85
	v_ldexp_f32 v86, v86, v87
	v_fmamk_f32 v86, v86, 0x30800000, v166
	v_rsq_f32_e32 v91, v86
	v_mad_i64_i32 v[86:87], s[20:21], v90, s47, v[122:123]
	v_lshl_add_u64 v[86:87], v[86:87], 0, v[110:111]
	v_cvt_pk_bf16_f32 v85, v92, v93
	global_store_dwordx4 v[86:87], v[82:85], off sc1
	v_mul_f32_e32 v90, v91, v91
	s_nop 0
	v_mul_f32_e32 v82, 0xbfb8aa3b, v91
	v_pk_mul_f32 v[84:85], v[80:81], v[82:83] op_sel_hi:[1,0]
	v_pk_mul_f32 v[86:87], v[78:79], v[82:83] op_sel_hi:[1,0]
	v_exp_f32_e32 v84, v84
	v_exp_f32_e32 v86, v86
	v_exp_f32_e32 v87, v87
	v_exp_f32_e32 v85, v85
	v_pk_mul_f32 v[88:89], v[76:77], v[82:83] op_sel_hi:[1,0]
	v_pk_mul_f32 v[82:83], v[74:75], v[82:83] op_sel_hi:[1,0]
	v_pk_add_f32 v[86:87], v[86:87], 1.0 op_sel_hi:[1,0]
	v_pk_add_f32 v[84:85], v[84:85], 1.0 op_sel_hi:[1,0]
	v_rcp_f32_e32 v86, v86
	v_rcp_f32_e32 v87, v87
	v_rcp_f32_e32 v84, v84
	v_rcp_f32_e32 v85, v85
	v_exp_f32_e32 v82, v82
	v_exp_f32_e32 v83, v83
	v_exp_f32_e32 v88, v88
	v_exp_f32_e32 v89, v89
	v_pk_mul_f32 v[78:79], v[90:91], v[86:87] op_sel_hi:[0,1]
	v_pk_mul_f32 v[80:81], v[90:91], v[84:85] op_sel_hi:[0,1]
	v_pk_mul_f32 v[72:73], v[72:73], v[80:81]
	v_pk_mul_f32 v[70:71], v[70:71], v[78:79]
	v_pk_add_f32 v[78:79], v[88:89], 1.0 op_sel_hi:[1,0]
	v_pk_add_f32 v[80:81], v[82:83], 1.0 op_sel_hi:[1,0]
	v_rcp_f32_e32 v78, v78
	v_rcp_f32_e32 v80, v80
	v_rcp_f32_e32 v81, v81
	v_rcp_f32_e32 v79, v79
	v_pk_mul_f32 v[74:75], v[90:91], v[80:81] op_sel_hi:[0,1]
	v_pk_mul_f32 v[76:77], v[90:91], v[78:79] op_sel_hi:[0,1]
	v_pk_mul_f32 v[76:77], v[68:69], v[76:77]
	v_pk_mul_f32 v[68:69], v[66:67], v[74:75]
	v_cvt_pk_bf16_f32 v66, v70, v71
	v_ffbh_u32_e32 v70, v155
	v_cvt_pk_bf16_f32 v67, v72, v73
	v_min_u32_e32 v72, 32, v70
	v_lshlrev_b64 v[70:71], v72, v[154:155]
	v_min_u32_e32 v70, 1, v70
	v_or_b32_e32 v70, v71, v70
	v_cvt_f32_u32_e32 v73, v70
	v_sub_u32_e32 v72, 32, v72
	v_or_b32_e32 v74, 48, v146
	v_mad_i64_i32 v[70:71], s[20:21], v74, s47, v[122:123]
	v_ldexp_f32 v72, v73, v72
	v_fmamk_f32 v72, v72, 0x30800000, v166
	v_rsq_f32_e32 v74, v72
	v_lshl_add_u64 v[70:71], v[70:71], 0, v[110:111]
	v_cvt_pk_bf16_f32 v68, v68, v69
	v_cvt_pk_bf16_f32 v69, v76, v77
	global_store_dwordx4 v[70:71], v[66:69], off sc1
	v_add_u32_e32 v75, 0x80, v146
	s_nop 0
	v_mul_f32_e32 v66, 0xbfb8aa3b, v74
	v_pk_mul_f32 v[68:69], v[64:65], v[66:67] op_sel_hi:[1,0]
	v_pk_mul_f32 v[70:71], v[62:63], v[66:67] op_sel_hi:[1,0]
	v_exp_f32_e32 v68, v68
	v_exp_f32_e32 v70, v70
	v_exp_f32_e32 v71, v71
	v_exp_f32_e32 v69, v69
	v_pk_mul_f32 v[72:73], v[60:61], v[66:67] op_sel_hi:[1,0]
	v_pk_mul_f32 v[66:67], v[58:59], v[66:67] op_sel_hi:[1,0]
	v_pk_add_f32 v[70:71], v[70:71], 1.0 op_sel_hi:[1,0]
	v_pk_add_f32 v[68:69], v[68:69], 1.0 op_sel_hi:[1,0]
	v_rcp_f32_e32 v70, v70
	v_rcp_f32_e32 v71, v71
	v_rcp_f32_e32 v68, v68
	v_rcp_f32_e32 v69, v69
	v_exp_f32_e32 v66, v66
	v_exp_f32_e32 v67, v67
	v_exp_f32_e32 v72, v72
	v_exp_f32_e32 v73, v73
	v_mul_f32_e32 v74, v74, v74
	v_pk_mul_f32 v[62:63], v[74:75], v[70:71] op_sel_hi:[0,1]
	v_pk_mul_f32 v[64:65], v[74:75], v[68:69] op_sel_hi:[0,1]
	v_pk_mul_f32 v[56:57], v[56:57], v[64:65]
	v_pk_mul_f32 v[54:55], v[54:55], v[62:63]
	v_pk_add_f32 v[62:63], v[72:73], 1.0 op_sel_hi:[1,0]
	v_pk_add_f32 v[64:65], v[66:67], 1.0 op_sel_hi:[1,0]
	v_rcp_f32_e32 v62, v62
	v_rcp_f32_e32 v64, v64
	v_rcp_f32_e32 v65, v65
	v_rcp_f32_e32 v63, v63
	v_pk_mul_f32 v[58:59], v[74:75], v[64:65] op_sel_hi:[0,1]
	v_pk_mul_f32 v[60:61], v[74:75], v[62:63] op_sel_hi:[0,1]
	v_pk_mul_f32 v[60:61], v[52:53], v[60:61]
	v_pk_mul_f32 v[52:53], v[50:51], v[58:59]
	v_cvt_pk_bf16_f32 v50, v54, v55
	v_ffbh_u32_e32 v54, v153
	v_cvt_pk_bf16_f32 v51, v56, v57
	v_min_u32_e32 v56, 32, v54
	v_lshlrev_b64 v[54:55], v56, v[152:153]
	v_min_u32_e32 v54, 1, v54
	v_or_b32_e32 v54, v55, v54
	v_cvt_f32_u32_e32 v54, v54
	v_sub_u32_e32 v55, 32, v56
	v_cvt_pk_bf16_f32 v52, v52, v53
	v_cvt_pk_bf16_f32 v53, v60, v61
	v_ldexp_f32 v54, v54, v55
	v_fmamk_f32 v54, v54, 0x30800000, v166
	v_rsq_f32_e32 v58, v54
	v_mad_i64_i32 v[54:55], s[20:21], v75, s47, v[122:123]
	v_lshl_add_u64 v[54:55], v[54:55], 0, v[110:111]
	global_store_dwordx4 v[54:55], v[50:53], off sc1
	s_nop 1
	v_mul_f32_e32 v50, 0xbfb8aa3b, v58
	v_pk_mul_f32 v[52:53], v[48:49], v[50:51] op_sel_hi:[1,0]
	v_pk_mul_f32 v[54:55], v[46:47], v[50:51] op_sel_hi:[1,0]
	v_exp_f32_e32 v52, v52
	v_exp_f32_e32 v54, v54
	v_exp_f32_e32 v55, v55
	v_exp_f32_e32 v53, v53
	v_pk_mul_f32 v[56:57], v[44:45], v[50:51] op_sel_hi:[1,0]
	v_pk_mul_f32 v[50:51], v[42:43], v[50:51] op_sel_hi:[1,0]
	v_pk_add_f32 v[54:55], v[54:55], 1.0 op_sel_hi:[1,0]
	v_pk_add_f32 v[52:53], v[52:53], 1.0 op_sel_hi:[1,0]
	v_rcp_f32_e32 v54, v54
	v_rcp_f32_e32 v55, v55
	v_rcp_f32_e32 v52, v52
	v_rcp_f32_e32 v53, v53
	v_exp_f32_e32 v50, v50
	v_exp_f32_e32 v51, v51
	v_exp_f32_e32 v56, v56
	v_exp_f32_e32 v57, v57
	v_mul_f32_e32 v58, v58, v58
	v_pk_mul_f32 v[46:47], v[58:59], v[54:55] op_sel_hi:[0,1]
	v_pk_mul_f32 v[48:49], v[58:59], v[52:53] op_sel_hi:[0,1]
	v_pk_mul_f32 v[40:41], v[40:41], v[48:49]
	v_pk_mul_f32 v[38:39], v[38:39], v[46:47]
	v_pk_add_f32 v[46:47], v[56:57], 1.0 op_sel_hi:[1,0]
	v_pk_add_f32 v[48:49], v[50:51], 1.0 op_sel_hi:[1,0]
	v_rcp_f32_e32 v46, v46
	v_rcp_f32_e32 v48, v48
	v_rcp_f32_e32 v49, v49
	v_rcp_f32_e32 v47, v47
	v_pk_mul_f32 v[42:43], v[58:59], v[48:49] op_sel_hi:[0,1]
	v_pk_mul_f32 v[44:45], v[58:59], v[46:47] op_sel_hi:[0,1]
	v_pk_mul_f32 v[44:45], v[36:37], v[44:45]
	v_pk_mul_f32 v[36:37], v[34:35], v[42:43]
	v_cvt_pk_bf16_f32 v34, v38, v39
	v_ffbh_u32_e32 v38, v151
	v_cvt_pk_bf16_f32 v35, v40, v41
	v_min_u32_e32 v40, 32, v38
	v_lshlrev_b64 v[38:39], v40, v[150:151]
	v_min_u32_e32 v38, 1, v38
	v_or_b32_e32 v38, v39, v38
	v_cvt_f32_u32_e32 v38, v38
	v_sub_u32_e32 v39, 32, v40
	v_add_u32_e32 v42, 0x90, v146
	v_cvt_pk_bf16_f32 v36, v36, v37
	v_ldexp_f32 v38, v38, v39
	v_fmamk_f32 v38, v38, 0x30800000, v166
	v_rsq_f32_e32 v43, v38
	v_mad_i64_i32 v[38:39], s[20:21], v42, s47, v[122:123]
	v_lshl_add_u64 v[38:39], v[38:39], 0, v[110:111]
	v_cvt_pk_bf16_f32 v37, v44, v45
	global_store_dwordx4 v[38:39], v[34:37], off sc1
	v_mul_f32_e32 v42, v43, v43
	s_nop 0
	v_mul_f32_e32 v34, 0xbfb8aa3b, v43
	v_pk_mul_f32 v[36:37], v[32:33], v[34:35] op_sel_hi:[1,0]
	v_pk_mul_f32 v[38:39], v[30:31], v[34:35] op_sel_hi:[1,0]
	v_exp_f32_e32 v36, v36
	v_exp_f32_e32 v38, v38
	v_exp_f32_e32 v39, v39
	v_exp_f32_e32 v37, v37
	v_pk_mul_f32 v[40:41], v[28:29], v[34:35] op_sel_hi:[1,0]
	v_pk_mul_f32 v[34:35], v[26:27], v[34:35] op_sel_hi:[1,0]
	v_pk_add_f32 v[38:39], v[38:39], 1.0 op_sel_hi:[1,0]
	v_pk_add_f32 v[36:37], v[36:37], 1.0 op_sel_hi:[1,0]
	v_rcp_f32_e32 v38, v38
	v_rcp_f32_e32 v39, v39
	v_rcp_f32_e32 v36, v36
	v_rcp_f32_e32 v37, v37
	v_exp_f32_e32 v34, v34
	v_exp_f32_e32 v35, v35
	v_exp_f32_e32 v40, v40
	v_exp_f32_e32 v41, v41
	v_pk_mul_f32 v[30:31], v[42:43], v[38:39] op_sel_hi:[0,1]
	v_pk_mul_f32 v[32:33], v[42:43], v[36:37] op_sel_hi:[0,1]
	v_pk_mul_f32 v[24:25], v[24:25], v[32:33]
	v_pk_mul_f32 v[22:23], v[22:23], v[30:31]
	v_pk_add_f32 v[30:31], v[40:41], 1.0 op_sel_hi:[1,0]
	v_pk_add_f32 v[32:33], v[34:35], 1.0 op_sel_hi:[1,0]
	v_rcp_f32_e32 v30, v30
	v_rcp_f32_e32 v32, v32
	v_rcp_f32_e32 v33, v33
	v_rcp_f32_e32 v31, v31
	v_pk_mul_f32 v[26:27], v[42:43], v[32:33] op_sel_hi:[0,1]
	v_pk_mul_f32 v[28:29], v[42:43], v[30:31] op_sel_hi:[0,1]
	v_pk_mul_f32 v[28:29], v[20:21], v[28:29]
	v_pk_mul_f32 v[20:21], v[18:19], v[26:27]
	v_cvt_pk_bf16_f32 v18, v22, v23
	v_ffbh_u32_e32 v22, v149
	v_cvt_pk_bf16_f32 v19, v24, v25
	v_min_u32_e32 v24, 32, v22
	v_lshlrev_b64 v[22:23], v24, v[148:149]
	v_min_u32_e32 v22, 1, v22
	v_or_b32_e32 v22, v23, v22
	v_cvt_f32_u32_e32 v22, v22
	v_sub_u32_e32 v23, 32, v24
	v_add_u32_e32 v26, 0xa0, v146
	v_cvt_pk_bf16_f32 v20, v20, v21
	v_ldexp_f32 v22, v22, v23
	v_fmamk_f32 v22, v22, 0x30800000, v166
	v_rsq_f32_e32 v27, v22
	v_mad_i64_i32 v[22:23], s[20:21], v26, s47, v[122:123]
	v_lshl_add_u64 v[22:23], v[22:23], 0, v[110:111]
	v_cvt_pk_bf16_f32 v21, v28, v29
	global_store_dwordx4 v[22:23], v[18:21], off sc1
	v_mul_f32_e32 v26, v27, v27
	s_nop 0
	v_mul_f32_e32 v18, 0xbfb8aa3b, v27
	v_pk_mul_f32 v[20:21], v[16:17], v[18:19] op_sel_hi:[1,0]
	v_pk_mul_f32 v[22:23], v[14:15], v[18:19] op_sel_hi:[1,0]
	v_exp_f32_e32 v20, v20
	v_exp_f32_e32 v22, v22
	v_exp_f32_e32 v23, v23
	v_exp_f32_e32 v21, v21
	v_pk_mul_f32 v[24:25], v[12:13], v[18:19] op_sel_hi:[1,0]
	v_pk_mul_f32 v[18:19], v[10:11], v[18:19] op_sel_hi:[1,0]
	v_pk_add_f32 v[22:23], v[22:23], 1.0 op_sel_hi:[1,0]
	v_pk_add_f32 v[20:21], v[20:21], 1.0 op_sel_hi:[1,0]
	v_rcp_f32_e32 v22, v22
	v_rcp_f32_e32 v23, v23
	v_rcp_f32_e32 v20, v20
	v_rcp_f32_e32 v21, v21
	v_exp_f32_e32 v18, v18
	v_exp_f32_e32 v19, v19
	v_exp_f32_e32 v24, v24
	v_exp_f32_e32 v25, v25
	v_pk_mul_f32 v[14:15], v[26:27], v[22:23] op_sel_hi:[0,1]
	v_pk_mul_f32 v[16:17], v[26:27], v[20:21] op_sel_hi:[0,1]
	v_pk_mul_f32 v[8:9], v[8:9], v[16:17]
	v_pk_mul_f32 v[6:7], v[6:7], v[14:15]
	v_pk_add_f32 v[14:15], v[24:25], 1.0 op_sel_hi:[1,0]
	v_pk_add_f32 v[16:17], v[18:19], 1.0 op_sel_hi:[1,0]
	v_rcp_f32_e32 v14, v14
	v_rcp_f32_e32 v16, v16
	v_rcp_f32_e32 v17, v17
	v_rcp_f32_e32 v15, v15
	v_pk_mul_f32 v[10:11], v[26:27], v[16:17] op_sel_hi:[0,1]
	v_pk_mul_f32 v[12:13], v[26:27], v[14:15] op_sel_hi:[0,1]
	v_pk_mul_f32 v[12:13], v[4:5], v[12:13]
	v_pk_mul_f32 v[4:5], v[2:3], v[10:11]
	v_add_u32_e32 v10, 0xb0, v146
	v_cvt_pk_bf16_f32 v2, v6, v7
	v_mad_i64_i32 v[6:7], s[20:21], v10, s47, v[122:123]
	v_lshl_add_u64 v[6:7], v[6:7], 0, v[110:111]
	v_cvt_pk_bf16_f32 v3, v8, v9
	v_cvt_pk_bf16_f32 v4, v4, v5
	v_cvt_pk_bf16_f32 v5, v12, v13
	global_store_dwordx4 v[6:7], v[2:5], off sc1
	s_cbranch_vccnz .LBB0_869
	s_andn2_b64 vcc, exec, s[0:1]
	s_cbranch_vccnz .LBB0_868
	s_barrier
	s_branch .LBB0_868

.LBB0_887:
	s_ashr_i32 s0, s5, 31
	s_lshr_b32 s0, s0, 28
	s_add_i32 s0, s5, s0
	s_ashr_i32 s12, s0, 4
	s_lshl_b32 s0, s12, 6
	s_lshl_b32 s1, s12, 10
	s_sub_i32 s10, s6, s1
	v_or_b32_e32 v102, s0, v6
	s_ashr_i32 s11, s10, 31
	v_ashrrev_i32_e32 v103, 31, v102
	v_lshl_add_u64 v[104:105], s[10:11], 2, v[2:3]
	v_lshlrev_b64 v[42:43], 12, v[102:103]
	v_or_b32_e32 v46, 4, v102
	v_lshl_add_u64 v[42:43], v[104:105], 0, v[42:43]
	v_ashrrev_i32_e32 v47, 31, v46
	global_load_dwordx4 v[42:45], v[42:43], off nt
	v_lshlrev_b64 v[46:47], 12, v[46:47]
	v_or_b32_e32 v50, 8, v102
	v_lshl_add_u64 v[46:47], v[104:105], 0, v[46:47]
	v_ashrrev_i32_e32 v51, 31, v50
	global_load_dwordx4 v[46:49], v[46:47], off nt
	v_lshlrev_b64 v[50:51], 12, v[50:51]
	v_or_b32_e32 v54, 12, v102
	v_lshl_add_u64 v[50:51], v[104:105], 0, v[50:51]
	v_ashrrev_i32_e32 v55, 31, v54
	global_load_dwordx4 v[50:53], v[50:51], off nt
	v_lshlrev_b64 v[54:55], 12, v[54:55]
	v_or_b32_e32 v58, 16, v102
	v_lshl_add_u64 v[54:55], v[104:105], 0, v[54:55]
	v_ashrrev_i32_e32 v59, 31, v58
	global_load_dwordx4 v[54:57], v[54:55], off nt
	v_lshlrev_b64 v[58:59], 12, v[58:59]
	v_or_b32_e32 v62, 20, v102
	v_lshl_add_u64 v[58:59], v[104:105], 0, v[58:59]
	v_ashrrev_i32_e32 v63, 31, v62
	global_load_dwordx4 v[58:61], v[58:59], off nt
	v_lshlrev_b64 v[62:63], 12, v[62:63]
	v_or_b32_e32 v66, 24, v102
	v_lshl_add_u64 v[62:63], v[104:105], 0, v[62:63]
	v_ashrrev_i32_e32 v67, 31, v66
	global_load_dwordx4 v[62:65], v[62:63], off nt
	v_lshlrev_b64 v[66:67], 12, v[66:67]
	s_waitcnt vmcnt(32)
	v_or_b32_e32 v70, 28, v102
	v_lshl_add_u64 v[66:67], v[104:105], 0, v[66:67]
	v_ashrrev_i32_e32 v71, 31, v70
	global_load_dwordx4 v[66:69], v[66:67], off nt
	v_lshlrev_b64 v[70:71], 12, v[70:71]
	s_waitcnt vmcnt(32)
	v_or_b32_e32 v74, 32, v102
	v_lshl_add_u64 v[70:71], v[104:105], 0, v[70:71]
	v_ashrrev_i32_e32 v75, 31, v74
	global_load_dwordx4 v[70:73], v[70:71], off nt
	v_lshlrev_b64 v[74:75], 12, v[74:75]
	s_waitcnt vmcnt(31)
	v_or_b32_e32 v78, 36, v102
	v_lshl_add_u64 v[74:75], v[104:105], 0, v[74:75]
	v_ashrrev_i32_e32 v79, 31, v78
	global_load_dwordx4 v[74:77], v[74:75], off nt
	v_lshlrev_b64 v[78:79], 12, v[78:79]
	v_or_b32_e32 v82, 40, v102
	v_lshl_add_u64 v[78:79], v[104:105], 0, v[78:79]
	v_ashrrev_i32_e32 v83, 31, v82
	global_load_dwordx4 v[78:81], v[78:79], off nt
	v_lshlrev_b64 v[82:83], 12, v[82:83]
	s_waitcnt vmcnt(32)
	v_or_b32_e32 v86, 44, v102
	v_lshl_add_u64 v[82:83], v[104:105], 0, v[82:83]
	v_ashrrev_i32_e32 v87, 31, v86
	global_load_dwordx4 v[82:85], v[82:83], off nt
	v_lshlrev_b64 v[86:87], 12, v[86:87]
	s_waitcnt vmcnt(32)
	v_or_b32_e32 v90, 48, v102
	v_lshl_add_u64 v[86:87], v[104:105], 0, v[86:87]
	v_ashrrev_i32_e32 v91, 31, v90
	global_load_dwordx4 v[86:89], v[86:87], off nt
	v_lshlrev_b64 v[90:91], 12, v[90:91]
	v_or_b32_e32 v94, 52, v102
	v_lshl_add_u64 v[90:91], v[104:105], 0, v[90:91]
	v_ashrrev_i32_e32 v95, 31, v94
	global_load_dwordx4 v[90:93], v[90:91], off nt
	v_lshlrev_b64 v[94:95], 12, v[94:95]
	v_or_b32_e32 v98, 56, v102
	v_lshl_add_u64 v[94:95], v[104:105], 0, v[94:95]
	v_ashrrev_i32_e32 v99, 31, v98
	global_load_dwordx4 v[94:97], v[94:95], off nt
	v_lshlrev_b64 v[98:99], 12, v[98:99]
	v_or_b32_e32 v102, 60, v102
	v_lshl_add_u64 v[98:99], v[104:105], 0, v[98:99]
	v_ashrrev_i32_e32 v103, 31, v102
	global_load_dwordx4 v[98:101], v[98:99], off nt
	v_lshlrev_b64 v[102:103], 12, v[102:103]
	v_lshl_add_u64 v[102:103], v[104:105], 0, v[102:103]
	global_load_dwordx4 v[102:105], v[102:103], off nt
	s_waitcnt vmcnt(15)
	ds_write2_b32 v9, v42, v43 offset1:1
	ds_write2_b32 v9, v44, v45 offset0:2 offset1:3
	s_waitcnt vmcnt(14)
	ds_write2_b32 v10, v46, v47 offset1:1
	ds_write2_b32 v11, v48, v49 offset1:1
	s_waitcnt vmcnt(13)
	ds_write2_b32 v12, v50, v51 offset1:1
	ds_write2_b32 v13, v52, v53 offset1:1
	s_waitcnt vmcnt(12)
	ds_write2_b32 v14, v54, v55 offset1:1
	ds_write2_b32 v15, v56, v57 offset1:1
	s_waitcnt vmcnt(11)
	ds_write2_b32 v16, v58, v59 offset1:1
	ds_write2_b32 v17, v60, v61 offset1:1
	s_waitcnt vmcnt(10)
	ds_write2_b32 v18, v62, v63 offset1:1
	ds_write2_b32 v19, v64, v65 offset1:1
	s_waitcnt vmcnt(9)
	ds_write2_b32 v20, v66, v67 offset1:1
	ds_write2_b32 v21, v68, v69 offset1:1
	s_waitcnt vmcnt(8)
	ds_write2_b32 v22, v70, v71 offset1:1
	ds_write2_b32 v23, v72, v73 offset1:1
	s_waitcnt vmcnt(7)
	ds_write2_b32 v24, v74, v75 offset1:1
	ds_write2_b32 v25, v76, v77 offset1:1
	s_waitcnt vmcnt(6)
	ds_write2_b32 v26, v78, v79 offset1:1
	ds_write2_b32 v27, v80, v81 offset1:1
	s_waitcnt vmcnt(5)
	ds_write2_b32 v28, v82, v83 offset1:1
	ds_write2_b32 v29, v84, v85 offset1:1
	s_waitcnt vmcnt(4)
	ds_write2_b32 v30, v86, v87 offset1:1
	ds_write2_b32 v31, v88, v89 offset1:1
	s_waitcnt vmcnt(3)
	ds_write2_b32 v32, v90, v91 offset1:1
	ds_write2_b32 v33, v92, v93 offset1:1
	s_waitcnt vmcnt(2)
	ds_write2_b32 v34, v94, v95 offset1:1
	ds_write2_b32 v35, v96, v97 offset1:1
	s_waitcnt vmcnt(1)
	ds_write2_b32 v36, v98, v99 offset1:1
	ds_write2_b32 v37, v100, v101 offset1:1
	s_waitcnt vmcnt(0)
	ds_write2_b32 v38, v102, v103 offset1:1
	ds_write2_b32 v39, v104, v105 offset1:1
	s_waitcnt lgkmcnt(0)
	ds_read2_b32 v[48:49], v7 offset0:65 offset1:73
	ds_read2_b32 v[50:51], v7 offset1:8
	ds_read2_b32 v[52:53], v7 offset0:130 offset1:138
	ds_read2_b32 v[54:55], v7 offset0:195 offset1:203
	ds_read2_b32 v[56:57], v40 offset0:4 offset1:12
	ds_read2_b32 v[58:59], v40 offset0:69 offset1:77
	ds_read2_b32 v[60:61], v40 offset0:134 offset1:142
	ds_read2_b32 v[62:63], v40 offset0:199 offset1:207
	s_mul_i32 s12, s12, 0xffd40000
	s_ashr_i32 s1, s0, 31
	v_add_u32_e32 v64, s12, v8
	v_lshl_add_u64 v[46:47], s[0:1], 1, v[4:5]
	v_ashrrev_i32_e32 v65, 31, v64
	s_waitcnt lgkmcnt(6)
	v_cvt_pk_bf16_f32 v42, v50, v48
	s_waitcnt lgkmcnt(4)
	v_cvt_pk_bf16_f32 v43, v52, v54
	s_waitcnt lgkmcnt(2)
	v_cvt_pk_bf16_f32 v44, v56, v58
	s_waitcnt lgkmcnt(0)
	v_cvt_pk_bf16_f32 v45, v60, v62
	v_lshl_add_u64 v[66:67], v[64:65], 1, v[46:47]
	v_add_u32_e32 v48, 0x5800, v64
	global_store_dwordx4 v[66:67], v[42:45], off sc1
	v_add_u32_e32 v66, 0xb000, v64
	v_ashrrev_i32_e32 v67, 31, v66
	v_cvt_pk_bf16_f32 v42, v51, v49
	v_ashrrev_i32_e32 v49, 31, v48
	v_cvt_pk_bf16_f32 v43, v53, v55
	v_cvt_pk_bf16_f32 v44, v57, v59
	v_cvt_pk_bf16_f32 v45, v61, v63
	v_lshl_add_u64 v[48:49], v[48:49], 1, v[46:47]
	global_store_dwordx4 v[48:49], v[42:45], off sc1
	ds_read2_b32 v[48:49], v7 offset0:81 offset1:89
	ds_read2_b32 v[50:51], v7 offset0:16 offset1:24
	ds_read2_b32 v[52:53], v7 offset0:146 offset1:154
	ds_read2_b32 v[54:55], v7 offset0:211 offset1:219
	ds_read2_b32 v[56:57], v40 offset0:20 offset1:28
	ds_read2_b32 v[58:59], v40 offset0:85 offset1:93
	ds_read2_b32 v[60:61], v40 offset0:150 offset1:158
	ds_read2_b32 v[62:63], v40 offset0:215 offset1:223
	v_lshl_add_u64 v[66:67], v[66:67], 1, v[46:47]
	s_waitcnt lgkmcnt(6)
	v_cvt_pk_bf16_f32 v42, v50, v48
	s_waitcnt lgkmcnt(4)
	v_cvt_pk_bf16_f32 v43, v52, v54
	s_waitcnt lgkmcnt(2)
	v_cvt_pk_bf16_f32 v44, v56, v58
	s_waitcnt lgkmcnt(0)
	v_cvt_pk_bf16_f32 v45, v60, v62
	v_add_u32_e32 v48, 0x10800, v64
	global_store_dwordx4 v[66:67], v[42:45], off sc1
	v_add_u32_e32 v66, 0x16000, v64
	v_ashrrev_i32_e32 v67, 31, v66
	v_cvt_pk_bf16_f32 v42, v51, v49
	v_ashrrev_i32_e32 v49, 31, v48
	v_cvt_pk_bf16_f32 v43, v53, v55
	v_cvt_pk_bf16_f32 v44, v57, v59
	v_cvt_pk_bf16_f32 v45, v61, v63
	v_lshl_add_u64 v[48:49], v[48:49], 1, v[46:47]
	global_store_dwordx4 v[48:49], v[42:45], off sc1
	ds_read2_b32 v[48:49], v7 offset0:32 offset1:40
	ds_read2_b32 v[50:51], v7 offset0:97 offset1:105
	ds_read2_b32 v[52:53], v7 offset0:162 offset1:170
	ds_read2_b32 v[54:55], v7 offset0:227 offset1:235
	ds_read2_b32 v[56:57], v40 offset0:36 offset1:44
	ds_read2_b32 v[58:59], v40 offset0:101 offset1:109
	ds_read2_b32 v[60:61], v40 offset0:166 offset1:174
	ds_read2_b32 v[62:63], v40 offset0:231 offset1:239
	v_lshl_add_u64 v[66:67], v[66:67], 1, v[46:47]
	s_waitcnt lgkmcnt(6)
	v_cvt_pk_bf16_f32 v42, v48, v50
	s_waitcnt lgkmcnt(4)
	v_cvt_pk_bf16_f32 v43, v52, v54
	s_waitcnt lgkmcnt(2)
	v_cvt_pk_bf16_f32 v44, v56, v58
	s_waitcnt lgkmcnt(0)
	v_cvt_pk_bf16_f32 v45, v60, v62
	v_add_u32_e32 v48, 0x1b800, v64
	global_store_dwordx4 v[66:67], v[42:45], off sc1
	v_add_u32_e32 v66, 0x21000, v64
	v_ashrrev_i32_e32 v67, 31, v66
	v_cvt_pk_bf16_f32 v42, v49, v51
	v_ashrrev_i32_e32 v49, 31, v48
	v_cvt_pk_bf16_f32 v43, v53, v55
	v_cvt_pk_bf16_f32 v44, v57, v59
	v_cvt_pk_bf16_f32 v45, v61, v63
	v_lshl_add_u64 v[48:49], v[48:49], 1, v[46:47]
	global_store_dwordx4 v[48:49], v[42:45], off sc1
	ds_read2_b32 v[48:49], v7 offset0:48 offset1:56
	ds_read2_b32 v[50:51], v7 offset0:113 offset1:121
	ds_read2_b32 v[52:53], v7 offset0:178 offset1:186
	ds_read2_b32 v[54:55], v7 offset0:243 offset1:251
	ds_read2_b32 v[56:57], v40 offset0:52 offset1:60
	ds_read2_b32 v[58:59], v40 offset0:117 offset1:125
	ds_read2_b32 v[60:61], v40 offset0:182 offset1:190
	ds_read2_b32 v[62:63], v40 offset0:247 offset1:255
	v_lshl_add_u64 v[66:67], v[66:67], 1, v[46:47]
	s_waitcnt lgkmcnt(6)
	v_cvt_pk_bf16_f32 v42, v48, v50
	s_waitcnt lgkmcnt(4)
	v_cvt_pk_bf16_f32 v43, v52, v54
	s_waitcnt lgkmcnt(2)
	v_cvt_pk_bf16_f32 v44, v56, v58
	s_waitcnt lgkmcnt(0)
	v_cvt_pk_bf16_f32 v45, v60, v62
	v_add_u32_e32 v48, 0x26800, v64
	global_store_dwordx4 v[66:67], v[42:45], off sc1
	s_add_i32 s5, s5, s13
	s_mul_i32 s0, s13, 0x2c000
	v_cvt_pk_bf16_f32 v42, v49, v51
	v_ashrrev_i32_e32 v49, 31, v48
	v_cvt_pk_bf16_f32 v43, v53, v55
	v_cvt_pk_bf16_f32 v44, v57, v59
	v_cvt_pk_bf16_f32 v45, v61, v63
	v_lshl_add_u64 v[46:47], v[48:49], 1, v[46:47]
	global_store_dwordx4 v[46:47], v[42:45], off sc1
	s_waitcnt lgkmcnt(0)
	s_add_i32 s6, s6, s7
	v_add_u32_e32 v8, s0, v8
	s_cmpk_lt_i32 s5, 0x2c0
	s_cbranch_scc1 .LBB0_887

.LBB0_891:
	s_cmpk_gt_i32 s10, 0x1ff
	s_mov_b64 s[6:7], -1
	s_cbranch_scc0 .LBB0_893
	s_add_i32 s4, s10, 0xfe00
	s_and_b32 s6, s4, 0xffff
	s_mul_i32 s6, s6, 0xba2f
	s_lshr_b32 s7, s6, 16
	s_lshr_b32 s6, s6, 22
	s_mulk_i32 s6, 0x58
	s_sub_i32 s20, s4, s6
	s_and_b32 s6, s7, 0xffc0
	s_lshl_b32 s7, s20, 6
	s_and_b32 s17, s7, 0xffc0
	s_lshl_b32 s4, s17, 2
	v_or_b32_e32 v114, s6, v10
	s_waitcnt vmcnt(20)
	v_lshl_add_u64 v[112:113], v[4:5], 0, s[4:5]
	v_mad_u64_u32 v[52:53], s[22:23], v114, s16, v[112:113]
	v_lshlrev_b32_e32 v56, 2, v114
	global_load_dwordx4 v[52:55], v[52:53], off nt
	v_or_b32_e32 v60, 4, v114
	global_load_dword v116, v56, s[0:1]
	v_mad_u64_u32 v[56:57], s[22:23], v60, s16, v[112:113]
	v_lshlrev_b32_e32 v60, 2, v60
	global_load_dwordx4 v[56:59], v[56:57], off nt
	v_or_b32_e32 v64, 8, v114
	global_load_dword v118, v60, s[0:1]
	v_mad_u64_u32 v[60:61], s[22:23], v64, s16, v[112:113]
	v_lshlrev_b32_e32 v64, 2, v64
	global_load_dwordx4 v[60:63], v[60:61], off nt
	v_or_b32_e32 v68, 12, v114
	global_load_dword v120, v64, s[0:1]
	v_mad_u64_u32 v[64:65], s[22:23], v68, s16, v[112:113]
	v_lshlrev_b32_e32 v68, 2, v68
	global_load_dwordx4 v[64:67], v[64:65], off nt
	v_or_b32_e32 v72, 16, v114
	global_load_dword v122, v68, s[0:1]
	v_mad_u64_u32 v[68:69], s[22:23], v72, s16, v[112:113]
	v_lshlrev_b32_e32 v72, 2, v72
	global_load_dwordx4 v[68:71], v[68:69], off nt
	v_or_b32_e32 v76, 20, v114
	global_load_dword v124, v72, s[0:1]
	v_mad_u64_u32 v[72:73], s[22:23], v76, s16, v[112:113]
	v_lshlrev_b32_e32 v76, 2, v76
	global_load_dwordx4 v[72:75], v[72:73], off nt
	v_or_b32_e32 v80, 24, v114
	global_load_dword v126, v76, s[0:1]
	v_mad_u64_u32 v[76:77], s[22:23], v80, s16, v[112:113]
	v_lshlrev_b32_e32 v80, 2, v80
	global_load_dwordx4 v[76:79], v[76:77], off nt
	v_or_b32_e32 v84, 28, v114
	global_load_dword v128, v80, s[0:1]
	v_mad_u64_u32 v[80:81], s[22:23], v84, s16, v[112:113]
	v_lshlrev_b32_e32 v84, 2, v84
	global_load_dwordx4 v[80:83], v[80:81], off nt
	v_or_b32_e32 v88, 32, v114
	global_load_dword v130, v84, s[0:1]
	v_mad_u64_u32 v[84:85], s[22:23], v88, s16, v[112:113]
	v_lshlrev_b32_e32 v88, 2, v88
	global_load_dwordx4 v[84:87], v[84:85], off nt
	v_or_b32_e32 v92, 36, v114
	global_load_dword v132, v88, s[0:1]
	v_mad_u64_u32 v[88:89], s[22:23], v92, s16, v[112:113]
	v_lshlrev_b32_e32 v92, 2, v92
	global_load_dwordx4 v[88:91], v[88:89], off nt
	v_or_b32_e32 v96, 40, v114
	global_load_dword v134, v92, s[0:1]
	v_mad_u64_u32 v[92:93], s[22:23], v96, s16, v[112:113]
	v_lshlrev_b32_e32 v96, 2, v96
	global_load_dwordx4 v[92:95], v[92:93], off nt
	v_or_b32_e32 v100, 44, v114
	global_load_dword v136, v96, s[0:1]
	v_mad_u64_u32 v[96:97], s[22:23], v100, s16, v[112:113]
	v_lshlrev_b32_e32 v100, 2, v100
	global_load_dwordx4 v[96:99], v[96:97], off nt
	v_or_b32_e32 v104, 48, v114
	global_load_dword v138, v100, s[0:1]
	v_mad_u64_u32 v[100:101], s[22:23], v104, s16, v[112:113]
	v_lshlrev_b32_e32 v104, 2, v104
	global_load_dwordx4 v[100:103], v[100:101], off nt
	s_waitcnt vmcnt(44)
	v_or_b32_e32 v108, 52, v114
	global_load_dword v140, v104, s[0:1]
	v_mad_u64_u32 v[104:105], s[22:23], v108, s16, v[112:113]
	v_lshlrev_b32_e32 v108, 2, v108
	global_load_dwordx4 v[104:107], v[104:105], off nt
	v_or_b32_e32 v115, 56, v114
	global_load_dword v142, v108, s[0:1]
	v_mad_u64_u32 v[108:109], s[22:23], v115, s16, v[112:113]
	v_lshlrev_b32_e32 v115, 2, v115
	global_load_dwordx4 v[108:111], v[108:109], off nt
	v_or_b32_e32 v117, 60, v114
	global_load_dword v144, v115, s[0:1]
	v_mad_u64_u32 v[112:113], s[22:23], v117, s16, v[112:113]
	v_lshlrev_b32_e32 v117, 2, v117
	global_load_dword v146, v117, s[0:1]
	s_waitcnt vmcnt(29)
	v_pk_mul_f32 v[52:53], v[52:53], v[116:117] op_sel_hi:[1,0]
	global_load_dwordx4 v[112:115], v[112:113], off nt
	ds_write2_b32 v20, v52, v53 offset1:1
	v_pk_mul_f32 v[52:53], v[54:55], v[116:117] op_sel_hi:[1,0]
	ds_write2_b32 v20, v52, v53 offset0:2 offset1:3
	s_waitcnt vmcnt(28)
	v_pk_mul_f32 v[52:53], v[56:57], v[118:119] op_sel_hi:[1,0]
	ds_write2_b32 v21, v52, v53 offset1:1
	v_pk_mul_f32 v[52:53], v[58:59], v[118:119] op_sel_hi:[1,0]
	ds_write2_b32 v22, v52, v53 offset1:1
	s_waitcnt vmcnt(26)
	v_pk_mul_f32 v[52:53], v[60:61], v[120:121] op_sel_hi:[1,0]
	ds_write2_b32 v23, v52, v53 offset1:1
	v_pk_mul_f32 v[52:53], v[62:63], v[120:121] op_sel_hi:[1,0]
	ds_write2_b32 v24, v52, v53 offset1:1
	s_waitcnt vmcnt(24)
	v_pk_mul_f32 v[52:53], v[64:65], v[122:123] op_sel_hi:[1,0]
	ds_write2_b32 v25, v52, v53 offset1:1
	v_pk_mul_f32 v[52:53], v[66:67], v[122:123] op_sel_hi:[1,0]
	ds_write2_b32 v26, v52, v53 offset1:1
	s_waitcnt vmcnt(22)
	v_pk_mul_f32 v[52:53], v[68:69], v[124:125] op_sel_hi:[1,0]
	ds_write2_b32 v27, v52, v53 offset1:1
	v_pk_mul_f32 v[52:53], v[70:71], v[124:125] op_sel_hi:[1,0]
	ds_write2_b32 v28, v52, v53 offset1:1
	s_waitcnt vmcnt(20)
	v_pk_mul_f32 v[52:53], v[72:73], v[126:127] op_sel_hi:[1,0]
	ds_write2_b32 v29, v52, v53 offset1:1
	v_pk_mul_f32 v[52:53], v[74:75], v[126:127] op_sel_hi:[1,0]
	ds_write2_b32 v30, v52, v53 offset1:1
	s_and_b32 s4, s20, 0xffff
	s_cmp_lt_u32 s4, 44
	s_waitcnt vmcnt(18)
	v_pk_mul_f32 v[52:53], v[76:77], v[128:129] op_sel_hi:[1,0]
	ds_write2_b32 v31, v52, v53 offset1:1
	v_pk_mul_f32 v[52:53], v[78:79], v[128:129] op_sel_hi:[1,0]
	ds_write2_b32 v32, v52, v53 offset1:1
	s_cselect_b32 s4, 0, 0xfffff500
	s_cselect_b32 s20, 0, 0x80
	s_waitcnt vmcnt(16)
	v_pk_mul_f32 v[52:53], v[80:81], v[130:131] op_sel_hi:[1,0]
	ds_write2_b32 v33, v52, v53 offset1:1
	v_pk_mul_f32 v[52:53], v[82:83], v[130:131] op_sel_hi:[1,0]
	ds_write2_b32 v34, v52, v53 offset1:1
	s_add_i32 s4, s4, s17
	s_lshl_b32 s4, s4, 1
	s_waitcnt vmcnt(14)
	v_pk_mul_f32 v[52:53], v[84:85], v[132:133] op_sel_hi:[1,0]
	ds_write2_b32 v35, v52, v53 offset1:1
	v_pk_mul_f32 v[52:53], v[86:87], v[132:133] op_sel_hi:[1,0]
	ds_write2_b32 v36, v52, v53 offset1:1
	s_and_b32 s7, s7, 64
	s_and_b32 s4, s4, 0xffffff00
	s_waitcnt vmcnt(12)
	v_pk_mul_f32 v[52:53], v[88:89], v[134:135] op_sel_hi:[1,0]
	ds_write2_b32 v37, v52, v53 offset1:1
	v_pk_mul_f32 v[52:53], v[90:91], v[134:135] op_sel_hi:[1,0]
	ds_write2_b32 v38, v52, v53 offset1:1
	s_or_b32 s7, s7, s20
	s_or_b32 s7, s7, s4
	s_waitcnt vmcnt(10)
	v_pk_mul_f32 v[52:53], v[92:93], v[136:137] op_sel_hi:[1,0]
	ds_write2_b32 v39, v52, v53 offset1:1
	v_pk_mul_f32 v[52:53], v[94:95], v[136:137] op_sel_hi:[1,0]
	ds_write2_b32 v40, v52, v53 offset1:1
	v_or_b32_e32 v74, s7, v11
	s_lshl_b32 s4, s6, 1
	s_waitcnt vmcnt(8)
	v_pk_mul_f32 v[52:53], v[96:97], v[138:139] op_sel_hi:[1,0]
	ds_write2_b32 v41, v52, v53 offset1:1
	v_pk_mul_f32 v[52:53], v[98:99], v[138:139] op_sel_hi:[1,0]
	ds_write2_b32 v42, v52, v53 offset1:1
	v_ashrrev_i32_e32 v75, 31, v74
	v_lshl_add_u64 v[72:73], v[6:7], 0, s[4:5]
	s_waitcnt vmcnt(6)
	v_pk_mul_f32 v[52:53], v[100:101], v[140:141] op_sel_hi:[1,0]
	ds_write2_b32 v43, v52, v53 offset1:1
	v_pk_mul_f32 v[52:53], v[102:103], v[140:141] op_sel_hi:[1,0]
	ds_write2_b32 v44, v52, v53 offset1:1
	v_lshlrev_b64 v[74:75], 11, v[74:75]
	v_lshl_add_u64 v[74:75], v[72:73], 0, v[74:75]
	s_waitcnt vmcnt(4)
	v_pk_mul_f32 v[52:53], v[104:105], v[142:143] op_sel_hi:[1,0]
	ds_write2_b32 v45, v52, v53 offset1:1
	v_pk_mul_f32 v[52:53], v[106:107], v[142:143] op_sel_hi:[1,0]
	ds_write2_b32 v46, v52, v53 offset1:1
	s_waitcnt vmcnt(2)
	v_pk_mul_f32 v[52:53], v[108:109], v[144:145] op_sel_hi:[1,0]
	ds_write2_b32 v47, v52, v53 offset1:1
	v_pk_mul_f32 v[52:53], v[110:111], v[144:145] op_sel_hi:[1,0]
	ds_write2_b32 v48, v52, v53 offset1:1
	s_waitcnt vmcnt(0)
	v_pk_mul_f32 v[52:53], v[112:113], v[146:147] op_sel_hi:[1,0]
	ds_write2_b32 v49, v52, v53 offset1:1
	v_pk_mul_f32 v[52:53], v[114:115], v[146:147] op_sel_hi:[1,0]
	ds_write2_b32 v50, v52, v53 offset1:1
	s_waitcnt lgkmcnt(0)
	ds_read2_b32 v[56:57], v12 offset0:65 offset1:73
	ds_read2_b32 v[58:59], v12 offset1:8
	ds_read2_b32 v[60:61], v12 offset0:130 offset1:138
	ds_read2_b32 v[62:63], v12 offset0:195 offset1:203
	ds_read2_b32 v[64:65], v51 offset0:4 offset1:12
	ds_read2_b32 v[66:67], v51 offset0:69 offset1:77
	ds_read2_b32 v[68:69], v51 offset0:134 offset1:142
	ds_read2_b32 v[70:71], v51 offset0:199 offset1:207
	s_waitcnt lgkmcnt(6)
	v_cvt_pk_bf16_f32 v52, v58, v56
	s_waitcnt lgkmcnt(4)
	v_cvt_pk_bf16_f32 v53, v60, v62
	s_waitcnt lgkmcnt(2)
	v_cvt_pk_bf16_f32 v54, v64, v66
	v_or_b32_e32 v56, s7, v13
	s_waitcnt lgkmcnt(0)
	v_cvt_pk_bf16_f32 v55, v68, v70
	global_store_dwordx4 v[74:75], v[52:55], off sc1
	s_nop 1
	v_cvt_pk_bf16_f32 v52, v59, v57
	v_ashrrev_i32_e32 v57, 31, v56
	v_cvt_pk_bf16_f32 v53, v61, v63
	v_cvt_pk_bf16_f32 v54, v65, v67
	v_cvt_pk_bf16_f32 v55, v69, v71
	v_lshlrev_b64 v[56:57], 11, v[56:57]
	ds_read2_b32 v[58:59], v12 offset0:81 offset1:89
	ds_read2_b32 v[60:61], v12 offset0:16 offset1:24
	ds_read2_b32 v[62:63], v12 offset0:146 offset1:154
	ds_read2_b32 v[64:65], v12 offset0:211 offset1:219
	ds_read2_b32 v[66:67], v51 offset0:20 offset1:28
	ds_read2_b32 v[68:69], v51 offset0:85 offset1:93
	ds_read2_b32 v[70:71], v51 offset0:150 offset1:158
	ds_read2_b32 v[74:75], v51 offset0:215 offset1:223
	v_lshl_add_u64 v[56:57], v[72:73], 0, v[56:57]
	global_store_dwordx4 v[56:57], v[52:55], off sc1
	v_or_b32_e32 v56, s7, v14
	v_ashrrev_i32_e32 v57, 31, v56
	v_lshlrev_b64 v[56:57], 11, v[56:57]
	s_waitcnt lgkmcnt(6)
	v_cvt_pk_bf16_f32 v52, v60, v58
	s_waitcnt lgkmcnt(4)
	v_cvt_pk_bf16_f32 v53, v62, v64
	s_waitcnt lgkmcnt(2)
	v_cvt_pk_bf16_f32 v54, v66, v68
	s_waitcnt lgkmcnt(0)
	v_cvt_pk_bf16_f32 v55, v70, v74
	v_lshl_add_u64 v[56:57], v[72:73], 0, v[56:57]
	global_store_dwordx4 v[56:57], v[52:55], off sc1
	v_or_b32_e32 v56, s7, v15
	v_ashrrev_i32_e32 v57, 31, v56
	v_cvt_pk_bf16_f32 v52, v61, v59
	v_cvt_pk_bf16_f32 v53, v63, v65
	v_cvt_pk_bf16_f32 v54, v67, v69
	v_cvt_pk_bf16_f32 v55, v71, v75
	v_lshlrev_b64 v[56:57], 11, v[56:57]
	ds_read2_b32 v[58:59], v12 offset0:32 offset1:40
	ds_read2_b32 v[60:61], v12 offset0:97 offset1:105
	ds_read2_b32 v[62:63], v12 offset0:162 offset1:170
	ds_read2_b32 v[64:65], v12 offset0:227 offset1:235
	ds_read2_b32 v[66:67], v51 offset0:36 offset1:44
	ds_read2_b32 v[68:69], v51 offset0:101 offset1:109
	ds_read2_b32 v[70:71], v51 offset0:166 offset1:174
	ds_read2_b32 v[74:75], v51 offset0:231 offset1:239
	v_lshl_add_u64 v[56:57], v[72:73], 0, v[56:57]
	global_store_dwordx4 v[56:57], v[52:55], off sc1
	v_or_b32_e32 v56, s7, v16
	v_ashrrev_i32_e32 v57, 31, v56
	v_lshlrev_b64 v[56:57], 11, v[56:57]
	s_waitcnt lgkmcnt(6)
	v_cvt_pk_bf16_f32 v52, v58, v60
	s_waitcnt lgkmcnt(4)
	v_cvt_pk_bf16_f32 v53, v62, v64
	s_waitcnt lgkmcnt(2)
	v_cvt_pk_bf16_f32 v54, v66, v68
	s_waitcnt lgkmcnt(0)
	v_cvt_pk_bf16_f32 v55, v70, v74
	v_lshl_add_u64 v[56:57], v[72:73], 0, v[56:57]
	global_store_dwordx4 v[56:57], v[52:55], off sc1
	v_or_b32_e32 v56, s7, v17
	v_ashrrev_i32_e32 v57, 31, v56
	v_cvt_pk_bf16_f32 v52, v59, v61
	v_cvt_pk_bf16_f32 v53, v63, v65
	v_cvt_pk_bf16_f32 v54, v67, v69
	v_cvt_pk_bf16_f32 v55, v71, v75
	v_lshlrev_b64 v[56:57], 11, v[56:57]
	ds_read2_b32 v[58:59], v12 offset0:48 offset1:56
	ds_read2_b32 v[60:61], v12 offset0:113 offset1:121
	ds_read2_b32 v[62:63], v12 offset0:178 offset1:186
	ds_read2_b32 v[64:65], v12 offset0:243 offset1:251
	ds_read2_b32 v[66:67], v51 offset0:52 offset1:60
	ds_read2_b32 v[68:69], v51 offset0:117 offset1:125
	ds_read2_b32 v[70:71], v51 offset0:182 offset1:190
	ds_read2_b32 v[74:75], v51 offset0:247 offset1:255
	v_lshl_add_u64 v[56:57], v[72:73], 0, v[56:57]
	global_store_dwordx4 v[56:57], v[52:55], off sc1
	v_or_b32_e32 v56, s7, v18
	v_ashrrev_i32_e32 v57, 31, v56
	v_lshlrev_b64 v[56:57], 11, v[56:57]
	s_waitcnt lgkmcnt(6)
	v_cvt_pk_bf16_f32 v52, v58, v60
	s_waitcnt lgkmcnt(4)
	v_cvt_pk_bf16_f32 v53, v62, v64
	s_waitcnt lgkmcnt(2)
	v_cvt_pk_bf16_f32 v54, v66, v68
	s_waitcnt lgkmcnt(0)
	v_cvt_pk_bf16_f32 v55, v70, v74
	v_lshl_add_u64 v[56:57], v[72:73], 0, v[56:57]
	global_store_dwordx4 v[56:57], v[52:55], off sc1
	v_or_b32_e32 v56, s7, v19
	v_ashrrev_i32_e32 v57, 31, v56
	v_lshlrev_b64 v[56:57], 11, v[56:57]
	v_cvt_pk_bf16_f32 v52, v59, v61
	v_cvt_pk_bf16_f32 v53, v63, v65
	v_cvt_pk_bf16_f32 v54, v67, v69
	v_cvt_pk_bf16_f32 v55, v71, v75
	v_lshl_add_u64 v[56:57], v[72:73], 0, v[56:57]
	global_store_dwordx4 v[56:57], v[52:55], off sc1
	s_waitcnt lgkmcnt(0)
	s_cbranch_execnz .LBB0_890
	s_branch .LBB0_894

.LBB0_894:
	s_ashr_i32 s4, s10, 31
	s_lshr_b32 s4, s4, 27
	s_add_i32 s4, s10, s4
	s_ashr_i32 s7, s4, 5
	s_lshl_b32 s6, s7, 6
	s_lshl_b32 s7, s7, 11
	s_waitcnt vmcnt(20)
	v_or_b32_e32 v112, s6, v10
	s_sub_i32 s24, s11, s7
	v_or_b32_e32 v54, 4, v112
	v_or_b32_e32 v60, 8, v112
	v_or_b32_e32 v62, 12, v112
	v_or_b32_e32 v68, 16, v112
	v_or_b32_e32 v70, 20, v112
	v_or_b32_e32 v76, 24, v112
	v_or_b32_e32 v78, 28, v112
	v_or_b32_e32 v84, 32, v112
	v_or_b32_e32 v86, 36, v112
	v_or_b32_e32 v92, 40, v112
	v_or_b32_e32 v94, 44, v112
	v_or_b32_e32 v100, 48, v112
	v_or_b32_e32 v102, 52, v112
	s_ashr_i32 s25, s24, 31
	v_ashrrev_i32_e32 v113, 31, v112
	v_ashrrev_i32_e32 v55, 31, v54
	v_ashrrev_i32_e32 v61, 31, v60
	v_ashrrev_i32_e32 v63, 31, v62
	v_ashrrev_i32_e32 v69, 31, v68
	v_ashrrev_i32_e32 v71, 31, v70
	v_ashrrev_i32_e32 v77, 31, v76
	v_ashrrev_i32_e32 v79, 31, v78
	v_ashrrev_i32_e32 v85, 31, v84
	v_ashrrev_i32_e32 v87, 31, v86
	v_ashrrev_i32_e32 v93, 31, v92
	v_ashrrev_i32_e32 v95, 31, v94
	v_ashrrev_i32_e32 v101, 31, v100
	v_ashrrev_i32_e32 v103, 31, v102
	v_lshl_add_u64 v[114:115], s[24:25], 2, v[2:3]
	v_lshlrev_b64 v[52:53], 13, v[112:113]
	v_lshlrev_b64 v[54:55], 13, v[54:55]
	v_lshlrev_b64 v[60:61], 13, v[60:61]
	v_lshlrev_b64 v[62:63], 13, v[62:63]
	v_lshlrev_b64 v[68:69], 13, v[68:69]
	v_lshlrev_b64 v[70:71], 13, v[70:71]
	v_lshlrev_b64 v[76:77], 13, v[76:77]
	v_lshlrev_b64 v[78:79], 13, v[78:79]
	v_lshlrev_b64 v[84:85], 13, v[84:85]
	v_lshlrev_b64 v[86:87], 13, v[86:87]
	v_lshlrev_b64 v[92:93], 13, v[92:93]
	v_lshlrev_b64 v[94:95], 13, v[94:95]
	v_lshlrev_b64 v[100:101], 13, v[100:101]
	v_lshlrev_b64 v[102:103], 13, v[102:103]
	v_lshl_add_u64 v[52:53], v[114:115], 0, v[52:53]
	v_lshl_add_u64 v[56:57], v[114:115], 0, v[54:55]
	v_lshl_add_u64 v[60:61], v[114:115], 0, v[60:61]
	v_lshl_add_u64 v[64:65], v[114:115], 0, v[62:63]
	v_lshl_add_u64 v[68:69], v[114:115], 0, v[68:69]
	v_lshl_add_u64 v[72:73], v[114:115], 0, v[70:71]
	v_lshl_add_u64 v[76:77], v[114:115], 0, v[76:77]
	v_lshl_add_u64 v[80:81], v[114:115], 0, v[78:79]
	v_lshl_add_u64 v[84:85], v[114:115], 0, v[84:85]
	v_lshl_add_u64 v[88:89], v[114:115], 0, v[86:87]
	v_lshl_add_u64 v[92:93], v[114:115], 0, v[92:93]
	v_lshl_add_u64 v[96:97], v[114:115], 0, v[94:95]
	v_lshl_add_u64 v[100:101], v[114:115], 0, v[100:101]
	v_lshl_add_u64 v[104:105], v[114:115], 0, v[102:103]
	global_load_dwordx4 v[52:55], v[52:53], off nt
	s_nop 0
	global_load_dwordx4 v[56:59], v[56:57], off nt
	s_nop 0
	global_load_dwordx4 v[60:63], v[60:61], off nt
	s_nop 0
	global_load_dwordx4 v[64:67], v[64:65], off nt
	s_nop 0
	global_load_dwordx4 v[68:71], v[68:69], off nt
	s_nop 0
	global_load_dwordx4 v[72:75], v[72:73], off nt
	s_nop 0
	global_load_dwordx4 v[76:79], v[76:77], off nt
	s_nop 0
	global_load_dwordx4 v[80:83], v[80:81], off nt
	s_nop 0
	global_load_dwordx4 v[84:87], v[84:85], off nt
	s_nop 0
	global_load_dwordx4 v[88:91], v[88:89], off nt
	s_nop 0
	global_load_dwordx4 v[92:95], v[92:93], off nt
	s_nop 0
	global_load_dwordx4 v[96:99], v[96:97], off nt
	s_nop 0
	global_load_dwordx4 v[100:103], v[100:101], off nt
	s_nop 0
	global_load_dwordx4 v[104:107], v[104:105], off nt
	s_waitcnt vmcnt(33)
	v_or_b32_e32 v108, 56, v112
	v_ashrrev_i32_e32 v109, 31, v108
	v_lshlrev_b64 v[108:109], 13, v[108:109]
	v_or_b32_e32 v112, 60, v112
	v_lshl_add_u64 v[108:109], v[114:115], 0, v[108:109]
	v_ashrrev_i32_e32 v113, 31, v112
	global_load_dwordx4 v[108:111], v[108:109], off nt
	v_lshlrev_b64 v[112:113], 13, v[112:113]
	v_lshl_add_u64 v[112:113], v[114:115], 0, v[112:113]
	global_load_dwordx4 v[112:115], v[112:113], off nt
	s_andn2_b32 s4, s4, 31
	s_sub_i32 s4, s10, s4
	s_cmp_lt_i32 s4, 16
	s_cselect_b32 s4, 16, 0xfffffc00
	s_cselect_b32 s7, 0, 0x80
	s_add_i32 s4, s24, s4
	s_lshl_b32 s4, s4, 1
	s_and_b32 s17, s24, 64
	s_waitcnt vmcnt(15)
	ds_write2_b32 v20, v52, v53 offset1:1
	ds_write2_b32 v20, v54, v55 offset0:2 offset1:3
	s_waitcnt vmcnt(14)
	ds_write2_b32 v21, v56, v57 offset1:1
	ds_write2_b32 v22, v58, v59 offset1:1
	s_waitcnt vmcnt(13)
	ds_write2_b32 v23, v60, v61 offset1:1
	ds_write2_b32 v24, v62, v63 offset1:1
	s_waitcnt vmcnt(12)
	ds_write2_b32 v25, v64, v65 offset1:1
	ds_write2_b32 v26, v66, v67 offset1:1
	s_waitcnt vmcnt(11)
	ds_write2_b32 v27, v68, v69 offset1:1
	ds_write2_b32 v28, v70, v71 offset1:1
	s_waitcnt vmcnt(10)
	ds_write2_b32 v29, v72, v73 offset1:1
	ds_write2_b32 v30, v74, v75 offset1:1
	s_waitcnt vmcnt(9)
	ds_write2_b32 v31, v76, v77 offset1:1
	ds_write2_b32 v32, v78, v79 offset1:1
	s_waitcnt vmcnt(8)
	ds_write2_b32 v33, v80, v81 offset1:1
	ds_write2_b32 v34, v82, v83 offset1:1
	s_waitcnt vmcnt(7)
	ds_write2_b32 v35, v84, v85 offset1:1
	ds_write2_b32 v36, v86, v87 offset1:1
	s_waitcnt vmcnt(6)
	ds_write2_b32 v37, v88, v89 offset1:1
	ds_write2_b32 v38, v90, v91 offset1:1
	s_waitcnt vmcnt(5)
	ds_write2_b32 v39, v92, v93 offset1:1
	ds_write2_b32 v40, v94, v95 offset1:1
	s_waitcnt vmcnt(4)
	ds_write2_b32 v41, v96, v97 offset1:1
	ds_write2_b32 v42, v98, v99 offset1:1
	s_waitcnt vmcnt(3)
	ds_write2_b32 v43, v100, v101 offset1:1
	ds_write2_b32 v44, v102, v103 offset1:1
	s_waitcnt vmcnt(2)
	ds_write2_b32 v45, v104, v105 offset1:1
	ds_write2_b32 v46, v106, v107 offset1:1
	s_waitcnt vmcnt(1)
	ds_write2_b32 v47, v108, v109 offset1:1
	ds_write2_b32 v48, v110, v111 offset1:1
	s_waitcnt vmcnt(0)
	ds_write2_b32 v49, v112, v113 offset1:1
	ds_write2_b32 v50, v114, v115 offset1:1
	s_waitcnt lgkmcnt(0)
	s_and_b32 s4, s4, 0xffffff00
	s_or_b32 s7, s17, s7
	ds_read2_b32 v[56:57], v12 offset0:65 offset1:73
	ds_read2_b32 v[58:59], v12 offset1:8
	ds_read2_b32 v[60:61], v12 offset0:130 offset1:138
	ds_read2_b32 v[62:63], v12 offset0:195 offset1:203
	ds_read2_b32 v[64:65], v51 offset0:4 offset1:12
	ds_read2_b32 v[66:67], v51 offset0:69 offset1:77
	ds_read2_b32 v[68:69], v51 offset0:134 offset1:142
	ds_read2_b32 v[70:71], v51 offset0:199 offset1:207
	s_or_b32 s4, s7, s4
	v_or_b32_e32 v74, s4, v11
	s_ashr_i32 s7, s6, 31
	v_ashrrev_i32_e32 v75, 31, v74
	v_lshl_add_u64 v[72:73], s[6:7], 1, v[8:9]
	v_lshlrev_b64 v[74:75], 11, v[74:75]
	s_waitcnt lgkmcnt(6)
	v_cvt_pk_bf16_f32 v52, v58, v56
	s_waitcnt lgkmcnt(4)
	v_cvt_pk_bf16_f32 v53, v60, v62
	s_waitcnt lgkmcnt(2)
	v_cvt_pk_bf16_f32 v54, v64, v66
	s_waitcnt lgkmcnt(0)
	v_cvt_pk_bf16_f32 v55, v68, v70
	v_lshl_add_u64 v[74:75], v[72:73], 0, v[74:75]
	v_or_b32_e32 v56, s4, v13
	global_store_dwordx4 v[74:75], v[52:55], off sc1
	s_nop 1
	v_cvt_pk_bf16_f32 v52, v59, v57
	v_ashrrev_i32_e32 v57, 31, v56
	v_cvt_pk_bf16_f32 v53, v61, v63
	v_cvt_pk_bf16_f32 v54, v65, v67
	v_cvt_pk_bf16_f32 v55, v69, v71
	v_lshlrev_b64 v[56:57], 11, v[56:57]
	ds_read2_b32 v[58:59], v12 offset0:81 offset1:89
	ds_read2_b32 v[60:61], v12 offset0:16 offset1:24
	ds_read2_b32 v[62:63], v12 offset0:146 offset1:154
	ds_read2_b32 v[64:65], v12 offset0:211 offset1:219
	ds_read2_b32 v[66:67], v51 offset0:20 offset1:28
	ds_read2_b32 v[68:69], v51 offset0:85 offset1:93
	ds_read2_b32 v[70:71], v51 offset0:150 offset1:158
	ds_read2_b32 v[74:75], v51 offset0:215 offset1:223
	v_lshl_add_u64 v[56:57], v[72:73], 0, v[56:57]
	global_store_dwordx4 v[56:57], v[52:55], off sc1
	v_or_b32_e32 v56, s4, v14
	v_ashrrev_i32_e32 v57, 31, v56
	v_lshlrev_b64 v[56:57], 11, v[56:57]
	s_waitcnt lgkmcnt(6)
	v_cvt_pk_bf16_f32 v52, v60, v58
	s_waitcnt lgkmcnt(4)
	v_cvt_pk_bf16_f32 v53, v62, v64
	s_waitcnt lgkmcnt(2)
	v_cvt_pk_bf16_f32 v54, v66, v68
	s_waitcnt lgkmcnt(0)
	v_cvt_pk_bf16_f32 v55, v70, v74
	v_lshl_add_u64 v[56:57], v[72:73], 0, v[56:57]
	global_store_dwordx4 v[56:57], v[52:55], off sc1
	v_or_b32_e32 v56, s4, v15
	v_ashrrev_i32_e32 v57, 31, v56
	v_cvt_pk_bf16_f32 v52, v61, v59
	v_cvt_pk_bf16_f32 v53, v63, v65
	v_cvt_pk_bf16_f32 v54, v67, v69
	v_cvt_pk_bf16_f32 v55, v71, v75
	v_lshlrev_b64 v[56:57], 11, v[56:57]
	ds_read2_b32 v[58:59], v12 offset0:32 offset1:40
	ds_read2_b32 v[60:61], v12 offset0:97 offset1:105
	ds_read2_b32 v[62:63], v12 offset0:162 offset1:170
	ds_read2_b32 v[64:65], v12 offset0:227 offset1:235
	ds_read2_b32 v[66:67], v51 offset0:36 offset1:44
	ds_read2_b32 v[68:69], v51 offset0:101 offset1:109
	ds_read2_b32 v[70:71], v51 offset0:166 offset1:174
	ds_read2_b32 v[74:75], v51 offset0:231 offset1:239
	v_lshl_add_u64 v[56:57], v[72:73], 0, v[56:57]
	global_store_dwordx4 v[56:57], v[52:55], off sc1
	v_or_b32_e32 v56, s4, v16
	v_ashrrev_i32_e32 v57, 31, v56
	v_lshlrev_b64 v[56:57], 11, v[56:57]
	s_waitcnt lgkmcnt(6)
	v_cvt_pk_bf16_f32 v52, v58, v60
	s_waitcnt lgkmcnt(4)
	v_cvt_pk_bf16_f32 v53, v62, v64
	s_waitcnt lgkmcnt(2)
	v_cvt_pk_bf16_f32 v54, v66, v68
	s_waitcnt lgkmcnt(0)
	v_cvt_pk_bf16_f32 v55, v70, v74
	v_lshl_add_u64 v[56:57], v[72:73], 0, v[56:57]
	global_store_dwordx4 v[56:57], v[52:55], off sc1
	v_or_b32_e32 v56, s4, v17
	v_ashrrev_i32_e32 v57, 31, v56
	v_cvt_pk_bf16_f32 v52, v59, v61
	v_cvt_pk_bf16_f32 v53, v63, v65
	v_cvt_pk_bf16_f32 v54, v67, v69
	v_cvt_pk_bf16_f32 v55, v71, v75
	v_lshlrev_b64 v[56:57], 11, v[56:57]
	ds_read2_b32 v[58:59], v12 offset0:48 offset1:56
	ds_read2_b32 v[60:61], v12 offset0:113 offset1:121
	ds_read2_b32 v[62:63], v12 offset0:178 offset1:186
	ds_read2_b32 v[64:65], v12 offset0:243 offset1:251
	ds_read2_b32 v[66:67], v51 offset0:52 offset1:60
	ds_read2_b32 v[68:69], v51 offset0:117 offset1:125
	ds_read2_b32 v[70:71], v51 offset0:182 offset1:190
	ds_read2_b32 v[74:75], v51 offset0:247 offset1:255
	v_lshl_add_u64 v[56:57], v[72:73], 0, v[56:57]
	global_store_dwordx4 v[56:57], v[52:55], off sc1
	v_or_b32_e32 v56, s4, v18
	v_ashrrev_i32_e32 v57, 31, v56
	v_lshlrev_b64 v[56:57], 11, v[56:57]
	s_waitcnt lgkmcnt(6)
	v_cvt_pk_bf16_f32 v52, v58, v60
	s_waitcnt lgkmcnt(4)
	v_cvt_pk_bf16_f32 v53, v62, v64
	s_waitcnt lgkmcnt(2)
	v_cvt_pk_bf16_f32 v54, v66, v68
	s_waitcnt lgkmcnt(0)
	v_cvt_pk_bf16_f32 v55, v70, v74
	v_lshl_add_u64 v[56:57], v[72:73], 0, v[56:57]
	global_store_dwordx4 v[56:57], v[52:55], off sc1
	v_or_b32_e32 v56, s4, v19
	v_ashrrev_i32_e32 v57, 31, v56
	v_lshlrev_b64 v[56:57], 11, v[56:57]
	v_cvt_pk_bf16_f32 v52, v59, v61
	v_cvt_pk_bf16_f32 v53, v63, v65
	v_cvt_pk_bf16_f32 v54, v67, v69
	v_cvt_pk_bf16_f32 v55, v71, v75
	v_lshl_add_u64 v[56:57], v[72:73], 0, v[56:57]
	global_store_dwordx4 v[56:57], v[52:55], off sc1
	s_waitcnt lgkmcnt(0)
	s_branch .LBB0_890

.LBB0_981:
	v_lshl_or_b32 v202, s20, 8, v230
	v_lshl_add_u32 v204, s21, 8, v228
	v_ashrrev_i32_e32 v203, 31, v202
	v_lshlrev_b64 v[240:241], 1, v[202:203]
	v_ashrrev_i32_e32 v205, 31, v204
	v_or_b32_e32 v218, 16, v204
	v_lshl_add_u64 v[90:91], s[44:45], 0, v[240:241]
	v_lshlrev_b64 v[242:243], 11, v[204:205]
	v_ashrrev_i32_e32 v219, 31, v218
	v_or_b32_e32 v214, 32, v204
	v_lshl_add_u64 v[92:93], v[90:91], 0, v[242:243]
	v_lshlrev_b64 v[220:221], 11, v[218:219]
	v_ashrrev_i32_e32 v215, 31, v214
	v_or_b32_e32 v210, 48, v204
	global_load_dwordx4 v[232:235], v[92:93], off
	global_load_dwordx4 v[236:239], v[92:93], off offset:256
	v_lshl_add_u64 v[92:93], v[90:91], 0, v[220:221]
	v_lshlrev_b64 v[216:217], 11, v[214:215]
	v_ashrrev_i32_e32 v211, 31, v210
	v_add_u32_e32 v206, 0x80, v204
	global_load_dwordx4 v[182:185], v[92:93], off
	global_load_dwordx4 v[178:181], v[92:93], off offset:256
	v_lshl_add_u64 v[92:93], v[90:91], 0, v[216:217]
	v_lshlrev_b64 v[212:213], 11, v[210:211]
	v_ashrrev_i32_e32 v207, 31, v206
	global_load_dwordx4 v[174:177], v[92:93], off
	global_load_dwordx4 v[170:173], v[92:93], off offset:256
	v_lshl_add_u64 v[92:93], v[90:91], 0, v[212:213]
	v_lshlrev_b64 v[208:209], 11, v[206:207]
	global_load_dwordx4 v[166:169], v[92:93], off
	global_load_dwordx4 v[162:165], v[92:93], off offset:256
	v_lshl_add_u64 v[92:93], v[90:91], 0, v[208:209]
	global_load_dwordx4 v[150:153], v[92:93], off
	global_load_dwordx4 v[146:149], v[92:93], off offset:256
	v_add_u32_e32 v92, 0x90, v204
	v_ashrrev_i32_e32 v93, 31, v92
	v_lshlrev_b64 v[92:93], 11, v[92:93]
	v_lshl_add_u64 v[92:93], v[90:91], 0, v[92:93]
	global_load_dwordx4 v[142:145], v[92:93], off
	global_load_dwordx4 v[130:133], v[92:93], off offset:256
	v_add_u32_e32 v92, 0xa0, v204
	v_ashrrev_i32_e32 v93, 31, v92
	v_lshlrev_b64 v[92:93], 11, v[92:93]
	v_lshl_add_u64 v[92:93], v[90:91], 0, v[92:93]
	global_load_dwordx4 v[122:125], v[92:93], off
	global_load_dwordx4 v[114:117], v[92:93], off offset:256
	v_add_u32_e32 v92, 0xb0, v204
	v_ashrrev_i32_e32 v93, 31, v92
	v_lshlrev_b64 v[92:93], 11, v[92:93]
	v_lshl_add_u64 v[90:91], v[90:91], 0, v[92:93]
	global_load_dwordx4 v[102:105], v[90:91], off
	s_nop 0
	global_load_dwordx4 v[90:93], v[90:91], off offset:256
	v_lshl_add_u64 v[242:243], s[44:45], 0, v[242:243]
	v_lshl_add_u64 v[240:241], v[242:243], 0, v[240:241]
	s_waitcnt vmcnt(0)
	s_nop 0
	v_lshlrev_b32_e32 v242, 16, v232
	v_and_b32_e32 v243, 0xffff0000, v232
	v_lshlrev_b32_e32 v232, 16, v233
	v_and_b32_e32 v233, 0xffff0000, v233
	v_lshlrev_b32_e32 v244, 16, v234
	v_and_b32_e32 v245, 0xffff0000, v234
	v_lshlrev_b32_e32 v234, 16, v235
	v_and_b32_e32 v235, 0xffff0000, v235
	v_pk_add_f32 v[160:161], v[160:161], v[232:233]
	v_pk_add_f32 v[158:159], v[158:159], v[242:243]
	v_pk_add_f32 v[232:233], v[156:157], v[234:235]
	v_pk_add_f32 v[234:235], v[154:155], v[244:245]
	v_cvt_pk_bf16_f32 v154, v158, v159
	v_cvt_pk_bf16_f32 v155, v160, v161
	s_nop 0
	v_cvt_pk_bf16_f32 v156, v234, v235
	v_cvt_pk_bf16_f32 v157, v232, v233
	global_store_dwordx4 v[240:241], v[154:157], off sc1
	s_nop 1
	v_mul_f32_e32 v154, v159, v159
	v_mul_f32_e32 v155, v160, v160
	v_fmac_f32_e32 v154, v158, v158
	v_fmac_f32_e32 v155, v161, v161
	v_add_f32_e32 v154, v154, v155
	v_mul_f32_e32 v155, v234, v234
	v_fmac_f32_e32 v155, v235, v235
	v_add_f32_e32 v154, v155, v154
	v_mul_f32_e32 v155, v232, v232
	v_fmac_f32_e32 v155, v233, v233
	v_add_f32_e32 v232, v155, v154
	v_lshlrev_b32_e32 v154, 16, v236
	v_and_b32_e32 v155, 0xffff0000, v236
	v_lshlrev_b32_e32 v156, 16, v237
	v_and_b32_e32 v157, 0xffff0000, v237
	v_lshlrev_b32_e32 v158, 16, v238
	v_and_b32_e32 v159, 0xffff0000, v238
	v_lshlrev_b32_e32 v160, 16, v239
	v_and_b32_e32 v161, 0xffff0000, v239
	v_pk_add_f32 v[140:141], v[140:141], v[156:157]
	v_pk_add_f32 v[138:139], v[138:139], v[154:155]
	v_pk_add_f32 v[156:157], v[134:135], v[158:159]
	v_cvt_pk_bf16_f32 v134, v138, v139
	v_cvt_pk_bf16_f32 v135, v140, v141
	v_pk_add_f32 v[154:155], v[136:137], v[160:161]
	v_cvt_pk_bf16_f32 v136, v156, v157
	s_nop 0
	v_cvt_pk_bf16_f32 v137, v154, v155
	global_store_dwordx4 v[240:241], v[134:137], off offset:256 sc1
	s_nop 1
	v_mul_f32_e32 v134, v139, v139
	v_mul_f32_e32 v135, v140, v140
	v_fmac_f32_e32 v134, v138, v138
	v_fmac_f32_e32 v135, v141, v141
	v_add_f32_e32 v134, v134, v135
	v_mul_f32_e32 v135, v156, v156
	v_fmac_f32_e32 v135, v157, v157
	v_add_f32_e32 v134, v135, v134
	v_mul_f32_e32 v135, v154, v154
	v_fmac_f32_e32 v135, v155, v155
	v_add_f32_e32 v134, v135, v134
	v_add_f32_e32 v134, v232, v134
	ds_bpermute_b32 v135, v225, v134
	s_waitcnt lgkmcnt(0)
	v_add_f32_e32 v134, v134, v135
	ds_bpermute_b32 v135, v226, v134
	s_and_saveexec_b64 s[20:21], s[4:5]
	s_cbranch_execz .LBB0_983
	s_waitcnt lgkmcnt(0)
	v_add_f32_e32 v134, v134, v135
	v_fma_f32 v134, v134, s36, 0.5
	v_trunc_f32_e32 v134, v134
	v_mul_f32_e32 v135, 0x2f800000, v134
	v_floor_f32_e32 v135, v135
	v_fmac_f32_e32 v134, 0xcf800000, v135
	v_cvt_u32_f32_e32 v134, v134
	v_cvt_u32_f32_e32 v135, v135
	v_lshl_add_u64 v[136:137], v[204:205], 3, s[48:49]
	global_atomic_add_x2 v[136:137], v[134:135], off
.LBB0_983:
	s_or_b64 exec, exec, s[20:21]
	v_lshlrev_b32_e32 v136, 16, v182
	v_and_b32_e32 v137, 0xffff0000, v182
	v_lshlrev_b32_e32 v138, 16, v183
	v_and_b32_e32 v139, 0xffff0000, v183
	v_lshlrev_b32_e32 v140, 16, v184
	v_and_b32_e32 v141, 0xffff0000, v184
	v_lshlrev_b32_e32 v154, 16, v185
	v_and_b32_e32 v155, 0xffff0000, v185
	v_pk_add_f32 v[126:127], v[126:127], v[136:137]
	v_pk_add_f32 v[128:129], v[128:129], v[138:139]
	v_pk_add_f32 v[136:137], v[120:121], v[154:155]
	v_pk_add_f32 v[120:121], v[118:119], v[140:141]
	v_cvt_pk_bf16_f32 v118, v126, v127
	v_mul_f32_e32 v127, v127, v127
	v_fmac_f32_e32 v127, v126, v126
	v_mul_f32_e32 v126, v128, v128
	v_fmac_f32_e32 v126, v129, v129
	v_add_f32_e32 v126, v127, v126
	v_mul_f32_e32 v127, v120, v120
	v_fmac_f32_e32 v127, v121, v121
	v_add_f32_e32 v126, v127, v126
	v_mul_f32_e32 v127, v136, v136
	v_fmac_f32_e32 v127, v137, v137
	v_cvt_pk_bf16_f32 v119, v128, v129
	v_add_f32_e32 v154, v127, v126
	v_lshlrev_b32_e32 v126, 16, v178
	v_and_b32_e32 v127, 0xffff0000, v178
	v_lshlrev_b32_e32 v128, 16, v179
	v_and_b32_e32 v129, 0xffff0000, v179
	v_lshlrev_b32_e32 v138, 16, v180
	v_and_b32_e32 v139, 0xffff0000, v180
	v_pk_add_f32 v[112:113], v[112:113], v[128:129]
	v_pk_add_f32 v[110:111], v[110:111], v[126:127]
	v_pk_add_f32 v[128:129], v[106:107], v[138:139]
	v_mul_f32_e32 v106, v111, v111
	v_mul_f32_e32 v107, v112, v112
	v_fmac_f32_e32 v106, v110, v110
	v_fmac_f32_e32 v107, v113, v113
	v_lshlrev_b32_e32 v140, 16, v181
	v_and_b32_e32 v141, 0xffff0000, v181
	v_add_f32_e32 v106, v106, v107
	v_mul_f32_e32 v107, v128, v128
	v_pk_add_f32 v[126:127], v[108:109], v[140:141]
	v_fmac_f32_e32 v107, v129, v129
	v_add_f32_e32 v106, v107, v106
	v_mul_f32_e32 v107, v126, v126
	v_fmac_f32_e32 v107, v127, v127
	v_add_f32_e32 v106, v107, v106
	v_add_f32_e32 v106, v154, v106
	ds_bpermute_b32 v107, v225, v106
	s_waitcnt lgkmcnt(1)
	v_lshl_add_u64 v[134:135], s[44:45], 0, v[220:221]
	v_lshl_add_u64 v[134:135], v[202:203], 1, v[134:135]
	v_cvt_pk_bf16_f32 v120, v120, v121
	v_cvt_pk_bf16_f32 v121, v136, v137
	s_waitcnt lgkmcnt(0)
	v_add_f32_e32 v106, v106, v107
	ds_bpermute_b32 v107, v226, v106
	global_store_dwordx4 v[134:135], v[118:121], off sc1
	v_cvt_pk_bf16_f32 v108, v110, v111
	v_cvt_pk_bf16_f32 v109, v112, v113
	v_cvt_pk_bf16_f32 v110, v128, v129
	v_cvt_pk_bf16_f32 v111, v126, v127
	global_store_dwordx4 v[134:135], v[108:111], off offset:256 sc1
	s_and_saveexec_b64 s[20:21], s[4:5]
	s_cbranch_execz .LBB0_985
	s_waitcnt lgkmcnt(0)
	v_add_f32_e32 v106, v106, v107
	v_fma_f32 v106, v106, s36, 0.5
	v_trunc_f32_e32 v106, v106
	v_mul_f32_e32 v107, 0x2f800000, v106
	v_floor_f32_e32 v107, v107
	v_fmac_f32_e32 v106, 0xcf800000, v107
	v_cvt_u32_f32_e32 v106, v106
	v_cvt_u32_f32_e32 v107, v107
	v_lshl_add_u64 v[108:109], v[218:219], 3, s[48:49]
	global_atomic_add_x2 v[108:109], v[106:107], off
.LBB0_985:
	s_or_b64 exec, exec, s[20:21]
	v_lshlrev_b32_e32 v108, 16, v174
	v_and_b32_e32 v109, 0xffff0000, v174
	v_lshlrev_b32_e32 v110, 16, v175
	v_and_b32_e32 v111, 0xffff0000, v175
	v_lshlrev_b32_e32 v112, 16, v176
	v_and_b32_e32 v113, 0xffff0000, v176
	v_lshlrev_b32_e32 v118, 16, v177
	v_and_b32_e32 v119, 0xffff0000, v177
	v_pk_add_f32 v[98:99], v[98:99], v[108:109]
	v_pk_add_f32 v[100:101], v[100:101], v[110:111]
	v_pk_add_f32 v[108:109], v[96:97], v[118:119]
	v_pk_add_f32 v[96:97], v[94:95], v[112:113]
	v_cvt_pk_bf16_f32 v94, v98, v99
	v_mul_f32_e32 v99, v99, v99
	v_fmac_f32_e32 v99, v98, v98
	v_mul_f32_e32 v98, v100, v100
	v_fmac_f32_e32 v98, v101, v101
	v_add_f32_e32 v98, v99, v98
	v_mul_f32_e32 v99, v96, v96
	v_fmac_f32_e32 v99, v97, v97
	v_add_f32_e32 v98, v99, v98
	v_mul_f32_e32 v99, v108, v108
	v_fmac_f32_e32 v99, v109, v109
	v_cvt_pk_bf16_f32 v95, v100, v101
	v_add_f32_e32 v118, v99, v98
	v_lshlrev_b32_e32 v98, 16, v170
	v_and_b32_e32 v99, 0xffff0000, v170
	v_lshlrev_b32_e32 v100, 16, v171
	v_and_b32_e32 v101, 0xffff0000, v171
	v_lshlrev_b32_e32 v110, 16, v172
	v_and_b32_e32 v111, 0xffff0000, v172
	v_pk_add_f32 v[88:89], v[88:89], v[100:101]
	v_pk_add_f32 v[86:87], v[86:87], v[98:99]
	v_pk_add_f32 v[100:101], v[82:83], v[110:111]
	v_mul_f32_e32 v82, v87, v87
	v_mul_f32_e32 v83, v88, v88
	v_fmac_f32_e32 v82, v86, v86
	v_fmac_f32_e32 v83, v89, v89
	v_lshlrev_b32_e32 v112, 16, v173
	v_and_b32_e32 v113, 0xffff0000, v173
	v_add_f32_e32 v82, v82, v83
	v_mul_f32_e32 v83, v100, v100
	v_pk_add_f32 v[98:99], v[84:85], v[112:113]
	v_fmac_f32_e32 v83, v101, v101
	v_add_f32_e32 v82, v83, v82
	v_mul_f32_e32 v83, v98, v98
	v_fmac_f32_e32 v83, v99, v99
	v_add_f32_e32 v82, v83, v82
	v_add_f32_e32 v82, v118, v82
	ds_bpermute_b32 v83, v225, v82
	s_waitcnt lgkmcnt(1)
	v_lshl_add_u64 v[106:107], s[44:45], 0, v[216:217]
	v_lshl_add_u64 v[106:107], v[202:203], 1, v[106:107]
	v_cvt_pk_bf16_f32 v96, v96, v97
	v_cvt_pk_bf16_f32 v97, v108, v109
	s_waitcnt lgkmcnt(0)
	v_add_f32_e32 v82, v82, v83
	ds_bpermute_b32 v83, v226, v82
	global_store_dwordx4 v[106:107], v[94:97], off sc1
	v_cvt_pk_bf16_f32 v84, v86, v87
	v_cvt_pk_bf16_f32 v85, v88, v89
	v_cvt_pk_bf16_f32 v86, v100, v101
	v_cvt_pk_bf16_f32 v87, v98, v99
	global_store_dwordx4 v[106:107], v[84:87], off offset:256 sc1
	s_and_saveexec_b64 s[20:21], s[4:5]
	s_cbranch_execz .LBB0_987
	s_waitcnt lgkmcnt(0)
	v_add_f32_e32 v82, v82, v83
	v_fma_f32 v82, v82, s36, 0.5
	v_trunc_f32_e32 v82, v82
	v_mul_f32_e32 v83, 0x2f800000, v82
	v_floor_f32_e32 v83, v83
	v_fmac_f32_e32 v82, 0xcf800000, v83
	v_cvt_u32_f32_e32 v82, v82
	v_cvt_u32_f32_e32 v83, v83
	v_lshl_add_u64 v[84:85], v[214:215], 3, s[48:49]
	global_atomic_add_x2 v[84:85], v[82:83], off
.LBB0_987:
	s_or_b64 exec, exec, s[20:21]
	v_lshlrev_b32_e32 v84, 16, v166
	v_and_b32_e32 v85, 0xffff0000, v166
	v_lshlrev_b32_e32 v86, 16, v167
	v_and_b32_e32 v87, 0xffff0000, v167
	v_lshlrev_b32_e32 v88, 16, v168
	v_and_b32_e32 v89, 0xffff0000, v168
	v_lshlrev_b32_e32 v94, 16, v169
	v_and_b32_e32 v95, 0xffff0000, v169
	v_pk_add_f32 v[78:79], v[78:79], v[84:85]
	v_pk_add_f32 v[80:81], v[80:81], v[86:87]
	v_pk_add_f32 v[84:85], v[76:77], v[94:95]
	v_pk_add_f32 v[76:77], v[74:75], v[88:89]
	v_cvt_pk_bf16_f32 v74, v78, v79
	v_mul_f32_e32 v79, v79, v79
	v_fmac_f32_e32 v79, v78, v78
	v_mul_f32_e32 v78, v80, v80
	v_fmac_f32_e32 v78, v81, v81
	v_add_f32_e32 v78, v79, v78
	v_mul_f32_e32 v79, v76, v76
	v_fmac_f32_e32 v79, v77, v77
	v_add_f32_e32 v78, v79, v78
	v_mul_f32_e32 v79, v84, v84
	v_fmac_f32_e32 v79, v85, v85
	v_cvt_pk_bf16_f32 v75, v80, v81
	v_add_f32_e32 v94, v79, v78
	v_lshlrev_b32_e32 v78, 16, v162
	v_and_b32_e32 v79, 0xffff0000, v162
	v_lshlrev_b32_e32 v80, 16, v163
	v_and_b32_e32 v81, 0xffff0000, v163
	v_lshlrev_b32_e32 v86, 16, v164
	v_and_b32_e32 v87, 0xffff0000, v164
	v_pk_add_f32 v[72:73], v[72:73], v[80:81]
	v_pk_add_f32 v[70:71], v[70:71], v[78:79]
	v_pk_add_f32 v[80:81], v[66:67], v[86:87]
	v_mul_f32_e32 v66, v71, v71
	v_mul_f32_e32 v67, v72, v72
	v_fmac_f32_e32 v66, v70, v70
	v_fmac_f32_e32 v67, v73, v73
	v_lshlrev_b32_e32 v88, 16, v165
	v_and_b32_e32 v89, 0xffff0000, v165
	v_add_f32_e32 v66, v66, v67
	v_mul_f32_e32 v67, v80, v80
	v_pk_add_f32 v[78:79], v[68:69], v[88:89]
	v_fmac_f32_e32 v67, v81, v81
	v_add_f32_e32 v66, v67, v66
	v_mul_f32_e32 v67, v78, v78
	v_fmac_f32_e32 v67, v79, v79
	v_add_f32_e32 v66, v67, v66
	v_add_f32_e32 v66, v94, v66
	ds_bpermute_b32 v67, v225, v66
	s_waitcnt lgkmcnt(1)
	v_lshl_add_u64 v[82:83], s[44:45], 0, v[212:213]
	v_lshl_add_u64 v[82:83], v[202:203], 1, v[82:83]
	v_cvt_pk_bf16_f32 v76, v76, v77
	v_cvt_pk_bf16_f32 v77, v84, v85
	s_waitcnt lgkmcnt(0)
	v_add_f32_e32 v66, v66, v67
	ds_bpermute_b32 v67, v226, v66
	global_store_dwordx4 v[82:83], v[74:77], off sc1
	v_cvt_pk_bf16_f32 v68, v70, v71
	v_cvt_pk_bf16_f32 v69, v72, v73
	v_cvt_pk_bf16_f32 v70, v80, v81
	v_cvt_pk_bf16_f32 v71, v78, v79
	global_store_dwordx4 v[82:83], v[68:71], off offset:256 sc1
	s_and_saveexec_b64 s[20:21], s[4:5]
	s_cbranch_execz .LBB0_989
	s_waitcnt lgkmcnt(0)
	v_add_f32_e32 v66, v66, v67
	v_fma_f32 v66, v66, s36, 0.5
	v_trunc_f32_e32 v66, v66
	v_mul_f32_e32 v67, 0x2f800000, v66
	v_floor_f32_e32 v67, v67
	v_fmac_f32_e32 v66, 0xcf800000, v67
	v_cvt_u32_f32_e32 v66, v66
	v_cvt_u32_f32_e32 v67, v67
	v_lshl_add_u64 v[68:69], v[210:211], 3, s[48:49]
	global_atomic_add_x2 v[68:69], v[66:67], off
.LBB0_989:
	s_or_b64 exec, exec, s[20:21]
	v_lshlrev_b32_e32 v68, 16, v150
	v_and_b32_e32 v69, 0xffff0000, v150
	v_lshlrev_b32_e32 v70, 16, v151
	v_and_b32_e32 v71, 0xffff0000, v151
	v_lshlrev_b32_e32 v72, 16, v152
	v_and_b32_e32 v73, 0xffff0000, v152
	v_lshlrev_b32_e32 v74, 16, v153
	v_and_b32_e32 v75, 0xffff0000, v153
	v_pk_add_f32 v[62:63], v[62:63], v[68:69]
	v_pk_add_f32 v[64:65], v[64:65], v[70:71]
	v_pk_add_f32 v[68:69], v[60:61], v[74:75]
	v_pk_add_f32 v[60:61], v[58:59], v[72:73]
	v_cvt_pk_bf16_f32 v58, v62, v63
	v_mul_f32_e32 v63, v63, v63
	v_fmac_f32_e32 v63, v62, v62
	v_mul_f32_e32 v62, v64, v64
	v_fmac_f32_e32 v62, v65, v65
	v_add_f32_e32 v62, v63, v62
	v_mul_f32_e32 v63, v60, v60
	v_fmac_f32_e32 v63, v61, v61
	v_add_f32_e32 v62, v63, v62
	v_mul_f32_e32 v63, v68, v68
	v_fmac_f32_e32 v63, v69, v69
	v_cvt_pk_bf16_f32 v59, v64, v65
	v_add_f32_e32 v74, v63, v62
	v_lshlrev_b32_e32 v62, 16, v146
	v_and_b32_e32 v63, 0xffff0000, v146
	v_lshlrev_b32_e32 v64, 16, v147
	v_and_b32_e32 v65, 0xffff0000, v147
	v_lshlrev_b32_e32 v70, 16, v148
	v_and_b32_e32 v71, 0xffff0000, v148
	v_pk_add_f32 v[56:57], v[56:57], v[64:65]
	v_pk_add_f32 v[54:55], v[54:55], v[62:63]
	v_pk_add_f32 v[64:65], v[50:51], v[70:71]
	v_mul_f32_e32 v50, v55, v55
	v_mul_f32_e32 v51, v56, v56
	v_fmac_f32_e32 v50, v54, v54
	v_fmac_f32_e32 v51, v57, v57
	v_lshlrev_b32_e32 v72, 16, v149
	v_and_b32_e32 v73, 0xffff0000, v149
	v_add_f32_e32 v50, v50, v51
	v_mul_f32_e32 v51, v64, v64
	v_pk_add_f32 v[62:63], v[52:53], v[72:73]
	v_fmac_f32_e32 v51, v65, v65
	v_add_f32_e32 v50, v51, v50
	v_mul_f32_e32 v51, v62, v62
	v_fmac_f32_e32 v51, v63, v63
	v_add_f32_e32 v50, v51, v50
	v_add_f32_e32 v50, v74, v50
	ds_bpermute_b32 v51, v225, v50
	s_waitcnt lgkmcnt(1)
	v_lshl_add_u64 v[66:67], s[44:45], 0, v[208:209]
	v_lshl_add_u64 v[66:67], v[202:203], 1, v[66:67]
	v_cvt_pk_bf16_f32 v60, v60, v61
	v_cvt_pk_bf16_f32 v61, v68, v69
	s_waitcnt lgkmcnt(0)
	v_add_f32_e32 v50, v50, v51
	ds_bpermute_b32 v51, v226, v50
	global_store_dwordx4 v[66:67], v[58:61], off sc1
	v_cvt_pk_bf16_f32 v52, v54, v55
	v_cvt_pk_bf16_f32 v53, v56, v57
	v_cvt_pk_bf16_f32 v54, v64, v65
	v_cvt_pk_bf16_f32 v55, v62, v63
	global_store_dwordx4 v[66:67], v[52:55], off offset:256 sc1
	s_and_saveexec_b64 s[20:21], s[4:5]
	s_cbranch_execz .LBB0_991
	s_waitcnt lgkmcnt(0)
	v_add_f32_e32 v50, v50, v51
	v_fma_f32 v50, v50, s36, 0.5
	v_trunc_f32_e32 v50, v50
	v_mul_f32_e32 v51, 0x2f800000, v50
	v_floor_f32_e32 v51, v51
	v_fmac_f32_e32 v50, 0xcf800000, v51
	v_cvt_u32_f32_e32 v50, v50
	v_cvt_u32_f32_e32 v51, v51
	v_lshl_add_u64 v[52:53], v[206:207], 3, s[48:49]
	global_atomic_add_x2 v[52:53], v[50:51], off
.LBB0_991:
	s_or_b64 exec, exec, s[20:21]
	v_lshlrev_b32_e32 v54, 16, v142
	v_and_b32_e32 v55, 0xffff0000, v142
	v_lshlrev_b32_e32 v56, 16, v143
	v_and_b32_e32 v57, 0xffff0000, v143
	v_lshlrev_b32_e32 v58, 16, v144
	v_and_b32_e32 v59, 0xffff0000, v144
	v_lshlrev_b32_e32 v60, 16, v145
	v_and_b32_e32 v61, 0xffff0000, v145
	v_pk_add_f32 v[46:47], v[46:47], v[54:55]
	v_pk_add_f32 v[48:49], v[48:49], v[56:57]
	v_pk_add_f32 v[54:55], v[44:45], v[60:61]
	v_pk_add_f32 v[44:45], v[42:43], v[58:59]
	v_cvt_pk_bf16_f32 v42, v46, v47
	v_mul_f32_e32 v47, v47, v47
	v_fmac_f32_e32 v47, v46, v46
	v_mul_f32_e32 v46, v48, v48
	v_fmac_f32_e32 v46, v49, v49
	v_add_f32_e32 v46, v47, v46
	v_mul_f32_e32 v47, v44, v44
	v_fmac_f32_e32 v47, v45, v45
	v_add_f32_e32 v46, v47, v46
	v_mul_f32_e32 v47, v54, v54
	v_fmac_f32_e32 v47, v55, v55
	v_cvt_pk_bf16_f32 v43, v48, v49
	v_add_f32_e32 v60, v47, v46
	v_lshlrev_b32_e32 v46, 16, v130
	v_and_b32_e32 v47, 0xffff0000, v130
	v_lshlrev_b32_e32 v48, 16, v131
	v_and_b32_e32 v49, 0xffff0000, v131
	v_lshlrev_b32_e32 v56, 16, v132
	v_and_b32_e32 v57, 0xffff0000, v132
	v_pk_add_f32 v[40:41], v[40:41], v[48:49]
	v_pk_add_f32 v[38:39], v[38:39], v[46:47]
	v_pk_add_f32 v[48:49], v[34:35], v[56:57]
	v_mul_f32_e32 v34, v39, v39
	v_mul_f32_e32 v35, v40, v40
	v_fmac_f32_e32 v34, v38, v38
	v_fmac_f32_e32 v35, v41, v41
	v_lshlrev_b32_e32 v58, 16, v133
	v_and_b32_e32 v59, 0xffff0000, v133
	v_add_f32_e32 v34, v34, v35
	v_mul_f32_e32 v35, v48, v48
	v_pk_add_f32 v[46:47], v[36:37], v[58:59]
	v_fmac_f32_e32 v35, v49, v49
	v_add_f32_e32 v34, v35, v34
	v_mul_f32_e32 v35, v46, v46
	v_fmac_f32_e32 v35, v47, v47
	v_add_f32_e32 v34, v35, v34
	v_add_f32_e32 v34, v60, v34
	ds_bpermute_b32 v35, v225, v34
	v_add_u32_e32 v50, 0x90, v204
	s_waitcnt lgkmcnt(1)
	v_ashrrev_i32_e32 v51, 31, v50
	v_lshlrev_b64 v[52:53], 11, v[50:51]
	v_lshl_add_u64 v[52:53], s[44:45], 0, v[52:53]
	s_waitcnt lgkmcnt(0)
	v_add_f32_e32 v34, v34, v35
	ds_bpermute_b32 v35, v226, v34
	v_lshl_add_u64 v[52:53], v[202:203], 1, v[52:53]
	v_cvt_pk_bf16_f32 v44, v44, v45
	v_cvt_pk_bf16_f32 v45, v54, v55
	global_store_dwordx4 v[52:53], v[42:45], off sc1
	v_cvt_pk_bf16_f32 v36, v38, v39
	v_cvt_pk_bf16_f32 v37, v40, v41
	v_cvt_pk_bf16_f32 v38, v48, v49
	v_cvt_pk_bf16_f32 v39, v46, v47
	global_store_dwordx4 v[52:53], v[36:39], off offset:256 sc1
	s_and_saveexec_b64 s[20:21], s[4:5]
	s_cbranch_execz .LBB0_993
	s_waitcnt lgkmcnt(0)
	v_add_f32_e32 v34, v34, v35
	v_fma_f32 v34, v34, s36, 0.5
	v_trunc_f32_e32 v34, v34
	v_mul_f32_e32 v35, 0x2f800000, v34
	v_floor_f32_e32 v35, v35
	v_fmac_f32_e32 v34, 0xcf800000, v35
	v_cvt_u32_f32_e32 v34, v34
	v_cvt_u32_f32_e32 v35, v35
	v_lshl_add_u64 v[36:37], v[50:51], 3, s[48:49]
	global_atomic_add_x2 v[36:37], v[34:35], off
.LBB0_993:
	s_or_b64 exec, exec, s[20:21]
	v_lshlrev_b32_e32 v38, 16, v122
	v_and_b32_e32 v39, 0xffff0000, v122
	v_lshlrev_b32_e32 v40, 16, v123
	v_and_b32_e32 v41, 0xffff0000, v123
	v_lshlrev_b32_e32 v42, 16, v124
	v_and_b32_e32 v43, 0xffff0000, v124
	v_lshlrev_b32_e32 v44, 16, v125
	v_and_b32_e32 v45, 0xffff0000, v125
	v_pk_add_f32 v[30:31], v[30:31], v[38:39]
	v_pk_add_f32 v[32:33], v[32:33], v[40:41]
	v_pk_add_f32 v[38:39], v[28:29], v[44:45]
	v_pk_add_f32 v[28:29], v[26:27], v[42:43]
	v_cvt_pk_bf16_f32 v26, v30, v31
	v_mul_f32_e32 v31, v31, v31
	v_fmac_f32_e32 v31, v30, v30
	v_mul_f32_e32 v30, v32, v32
	v_fmac_f32_e32 v30, v33, v33
	v_add_f32_e32 v30, v31, v30
	v_mul_f32_e32 v31, v28, v28
	v_fmac_f32_e32 v31, v29, v29
	v_add_f32_e32 v30, v31, v30
	v_mul_f32_e32 v31, v38, v38
	v_fmac_f32_e32 v31, v39, v39
	v_cvt_pk_bf16_f32 v27, v32, v33
	v_add_f32_e32 v44, v31, v30
	v_lshlrev_b32_e32 v30, 16, v114
	v_and_b32_e32 v31, 0xffff0000, v114
	v_lshlrev_b32_e32 v32, 16, v115
	v_and_b32_e32 v33, 0xffff0000, v115
	v_lshlrev_b32_e32 v40, 16, v116
	v_and_b32_e32 v41, 0xffff0000, v116
	v_pk_add_f32 v[24:25], v[24:25], v[32:33]
	v_pk_add_f32 v[22:23], v[22:23], v[30:31]
	v_pk_add_f32 v[32:33], v[18:19], v[40:41]
	v_mul_f32_e32 v18, v23, v23
	v_mul_f32_e32 v19, v24, v24
	v_fmac_f32_e32 v18, v22, v22
	v_fmac_f32_e32 v19, v25, v25
	v_lshlrev_b32_e32 v42, 16, v117
	v_and_b32_e32 v43, 0xffff0000, v117
	v_add_f32_e32 v18, v18, v19
	v_mul_f32_e32 v19, v32, v32
	v_pk_add_f32 v[30:31], v[20:21], v[42:43]
	v_fmac_f32_e32 v19, v33, v33
	v_add_f32_e32 v18, v19, v18
	v_mul_f32_e32 v19, v30, v30
	v_fmac_f32_e32 v19, v31, v31
	v_add_f32_e32 v18, v19, v18
	v_add_f32_e32 v18, v44, v18
	ds_bpermute_b32 v19, v225, v18
	v_add_u32_e32 v34, 0xa0, v204
	s_waitcnt lgkmcnt(1)
	v_ashrrev_i32_e32 v35, 31, v34
	v_lshlrev_b64 v[36:37], 11, v[34:35]
	v_lshl_add_u64 v[36:37], s[44:45], 0, v[36:37]
	s_waitcnt lgkmcnt(0)
	v_add_f32_e32 v18, v18, v19
	ds_bpermute_b32 v19, v226, v18
	v_lshl_add_u64 v[36:37], v[202:203], 1, v[36:37]
	v_cvt_pk_bf16_f32 v28, v28, v29
	v_cvt_pk_bf16_f32 v29, v38, v39
	global_store_dwordx4 v[36:37], v[26:29], off sc1
	v_cvt_pk_bf16_f32 v20, v22, v23
	v_cvt_pk_bf16_f32 v21, v24, v25
	v_cvt_pk_bf16_f32 v22, v32, v33
	v_cvt_pk_bf16_f32 v23, v30, v31
	global_store_dwordx4 v[36:37], v[20:23], off offset:256 sc1
	s_and_saveexec_b64 s[20:21], s[4:5]
	s_cbranch_execz .LBB0_995
	s_waitcnt lgkmcnt(0)
	v_add_f32_e32 v18, v18, v19
	v_fma_f32 v18, v18, s36, 0.5
	v_trunc_f32_e32 v18, v18
	v_mul_f32_e32 v19, 0x2f800000, v18
	v_floor_f32_e32 v19, v19
	v_fmac_f32_e32 v18, 0xcf800000, v19
	v_cvt_u32_f32_e32 v18, v18
	v_cvt_u32_f32_e32 v19, v19
	v_lshl_add_u64 v[20:21], v[34:35], 3, s[48:49]
	global_atomic_add_x2 v[20:21], v[18:19], off
.LBB0_995:
	s_or_b64 exec, exec, s[20:21]
	v_lshlrev_b32_e32 v22, 16, v102
	v_and_b32_e32 v23, 0xffff0000, v102
	v_lshlrev_b32_e32 v24, 16, v103
	v_and_b32_e32 v25, 0xffff0000, v103
	v_lshlrev_b32_e32 v26, 16, v104
	v_and_b32_e32 v27, 0xffff0000, v104
	v_lshlrev_b32_e32 v28, 16, v105
	v_and_b32_e32 v29, 0xffff0000, v105
	v_pk_add_f32 v[14:15], v[14:15], v[22:23]
	v_pk_add_f32 v[16:17], v[16:17], v[24:25]
	v_pk_add_f32 v[22:23], v[12:13], v[28:29]
	v_pk_add_f32 v[12:13], v[10:11], v[26:27]
	v_cvt_pk_bf16_f32 v10, v14, v15
	v_mul_f32_e32 v15, v15, v15
	v_fmac_f32_e32 v15, v14, v14
	v_mul_f32_e32 v14, v16, v16
	v_fmac_f32_e32 v14, v17, v17
	v_add_f32_e32 v14, v15, v14
	v_mul_f32_e32 v15, v12, v12
	v_fmac_f32_e32 v15, v13, v13
	v_add_f32_e32 v14, v15, v14
	v_mul_f32_e32 v15, v22, v22
	v_fmac_f32_e32 v15, v23, v23
	v_cvt_pk_bf16_f32 v11, v16, v17
	v_add_f32_e32 v28, v15, v14
	v_lshlrev_b32_e32 v14, 16, v90
	v_and_b32_e32 v15, 0xffff0000, v90
	v_lshlrev_b32_e32 v16, 16, v91
	v_and_b32_e32 v17, 0xffff0000, v91
	v_lshlrev_b32_e32 v24, 16, v92
	v_and_b32_e32 v25, 0xffff0000, v92
	v_pk_add_f32 v[8:9], v[8:9], v[16:17]
	v_pk_add_f32 v[6:7], v[6:7], v[14:15]
	v_pk_add_f32 v[16:17], v[2:3], v[24:25]
	v_mul_f32_e32 v2, v7, v7
	v_mul_f32_e32 v3, v8, v8
	v_fmac_f32_e32 v2, v6, v6
	v_fmac_f32_e32 v3, v9, v9
	v_lshlrev_b32_e32 v26, 16, v93
	v_and_b32_e32 v27, 0xffff0000, v93
	v_add_f32_e32 v2, v2, v3
	v_mul_f32_e32 v3, v16, v16
	v_pk_add_f32 v[14:15], v[4:5], v[26:27]
	v_fmac_f32_e32 v3, v17, v17
	v_add_f32_e32 v2, v3, v2
	v_mul_f32_e32 v3, v14, v14
	v_fmac_f32_e32 v3, v15, v15
	v_add_f32_e32 v2, v3, v2
	v_add_f32_e32 v2, v28, v2
	ds_bpermute_b32 v3, v225, v2
	v_add_u32_e32 v18, 0xb0, v204
	s_waitcnt lgkmcnt(1)
	v_ashrrev_i32_e32 v19, 31, v18
	v_lshlrev_b64 v[20:21], 11, v[18:19]
	v_lshl_add_u64 v[20:21], s[44:45], 0, v[20:21]
	s_waitcnt lgkmcnt(0)
	v_add_f32_e32 v2, v2, v3
	ds_bpermute_b32 v3, v226, v2
	v_lshl_add_u64 v[20:21], v[202:203], 1, v[20:21]
	v_cvt_pk_bf16_f32 v12, v12, v13
	v_cvt_pk_bf16_f32 v13, v22, v23
	global_store_dwordx4 v[20:21], v[10:13], off sc1
	v_cvt_pk_bf16_f32 v4, v6, v7
	v_cvt_pk_bf16_f32 v5, v8, v9
	v_cvt_pk_bf16_f32 v6, v16, v17
	v_cvt_pk_bf16_f32 v7, v14, v15
	global_store_dwordx4 v[20:21], v[4:7], off offset:256 sc1
	s_and_saveexec_b64 s[20:21], s[4:5]
	s_cbranch_execz .LBB0_997
	s_waitcnt lgkmcnt(0)
	v_add_f32_e32 v2, v2, v3
	v_fma_f32 v2, v2, s36, 0.5
	v_trunc_f32_e32 v2, v2
	v_mul_f32_e32 v3, 0x2f800000, v2
	v_floor_f32_e32 v3, v3
	v_fmac_f32_e32 v2, 0xcf800000, v3
	v_cvt_u32_f32_e32 v2, v2
	v_cvt_u32_f32_e32 v3, v3
	v_lshl_add_u64 v[4:5], v[18:19], 3, s[48:49]
	global_atomic_add_x2 v[4:5], v[2:3], off

.LBB0_1170:
	v_lshl_or_b32 v190, s11, 7, v213
	v_lshl_add_u32 v192, s10, 8, v211
	v_ashrrev_i32_e32 v191, 31, v190
	v_or_b32_e32 v206, 16, v192
	v_readlane_b32 s48, v254, 29
	v_lshlrev_b64 v[220:221], 1, v[190:191]
	v_ashrrev_i32_e32 v193, 31, v192
	v_ashrrev_i32_e32 v207, 31, v206
	v_or_b32_e32 v202, 32, v192
	v_or_b32_e32 v198, 48, v192
	v_lshlrev_b64 v[66:67], 2, v[190:191]
	v_readlane_b32 s58, v254, 39
	v_readlane_b32 s59, v254, 40
	v_lshl_add_u64 v[86:87], s[44:45], 0, v[220:221]
	v_lshlrev_b64 v[228:229], 11, v[192:193]
	v_lshlrev_b64 v[208:209], 11, v[206:207]
	v_ashrrev_i32_e32 v203, 31, v202
	v_ashrrev_i32_e32 v199, 31, v198
	v_lshl_add_u64 v[70:71], s[58:59], 0, v[66:67]
	v_lshl_add_u64 v[78:79], s[18:19], 0, v[66:67]
	v_lshl_add_u64 v[88:89], v[86:87], 0, v[228:229]
	v_lshl_add_u64 v[102:103], v[86:87], 0, v[208:209]
	v_lshlrev_b64 v[204:205], 11, v[202:203]
	v_lshlrev_b64 v[200:201], 11, v[198:199]
	global_load_dwordx4 v[66:69], v[70:71], off offset:16
	global_load_dwordx4 v[74:77], v[70:71], off
	s_nop 0
	global_load_dwordx4 v[70:73], v[78:79], off offset:16
	s_nop 0
	global_load_dwordx4 v[78:81], v[78:79], off
	s_nop 0
	global_load_dwordx4 v[216:219], v[88:89], off
	global_load_dwordx4 v[170:173], v[102:103], off
	v_lshl_add_u64 v[88:89], v[86:87], 0, v[204:205]
	v_lshl_add_u64 v[102:103], v[86:87], 0, v[200:201]
	global_load_dwordx4 v[166:169], v[88:89], off
	global_load_dwordx4 v[158:161], v[102:103], off
	v_add_u32_e32 v194, 0x80, v192
	v_add_u32_e32 v102, 0x90, v192
	v_ashrrev_i32_e32 v195, 31, v194
	v_ashrrev_i32_e32 v103, 31, v102
	v_lshlrev_b64 v[196:197], 11, v[194:195]
	v_lshlrev_b64 v[102:103], 11, v[102:103]
	v_lshl_add_u64 v[88:89], v[86:87], 0, v[196:197]
	v_lshl_add_u64 v[102:103], v[86:87], 0, v[102:103]
	global_load_dwordx4 v[130:133], v[88:89], off
	global_load_dwordx4 v[110:113], v[102:103], off
	v_add_u32_e32 v88, 0xa0, v192
	v_add_u32_e32 v102, 0xb0, v192
	v_ashrrev_i32_e32 v89, 31, v88
	v_ashrrev_i32_e32 v103, 31, v102
	v_lshlrev_b64 v[88:89], 11, v[88:89]
	v_lshlrev_b64 v[102:103], 11, v[102:103]
	v_lshl_add_u64 v[88:89], v[86:87], 0, v[88:89]
	v_lshl_add_u64 v[86:87], v[86:87], 0, v[102:103]
	global_load_dwordx4 v[102:105], v[88:89], off
	s_nop 0
	global_load_dwordx4 v[86:89], v[86:87], off
	v_readlane_b32 s49, v254, 30
	v_readlane_b32 s50, v254, 31
	v_readlane_b32 s51, v254, 32
	v_readlane_b32 s52, v254, 33
	v_readlane_b32 s53, v254, 34
	v_readlane_b32 s54, v254, 35
	v_readlane_b32 s55, v254, 36
	v_readlane_b32 s56, v254, 37
	v_readlane_b32 s57, v254, 38
	v_readlane_b32 s60, v254, 41
	v_readlane_b32 s61, v254, 42
	v_readlane_b32 s62, v254, 43
	v_readlane_b32 s63, v254, 44
	s_waitcnt vmcnt(0)
	v_pk_add_f32 v[156:157], v[156:157], v[80:81]
	v_pk_add_f32 v[154:155], v[154:155], v[78:79]
	v_pk_add_f32 v[148:149], v[148:149], v[72:73]
	v_pk_add_f32 v[146:147], v[146:147], v[70:71]
	v_pk_mul_f32 v[156:157], v[156:157], s[64:65] op_sel_hi:[1,0]
	v_pk_mul_f32 v[154:155], v[154:155], s[64:65] op_sel_hi:[1,0]
	v_pk_mul_f32 v[148:149], v[148:149], s[64:65] op_sel_hi:[1,0]
	v_pk_mul_f32 v[146:147], v[146:147], s[64:65] op_sel_hi:[1,0]
	v_exp_f32_e32 v154, v154
	v_exp_f32_e32 v155, v155
	v_exp_f32_e32 v156, v156
	v_exp_f32_e32 v157, v157
	v_exp_f32_e32 v146, v146
	v_exp_f32_e32 v148, v148
	v_exp_f32_e32 v149, v149
	v_exp_f32_e32 v147, v147
	v_pk_add_f32 v[156:157], v[156:157], 1.0 op_sel_hi:[1,0]
	v_pk_add_f32 v[154:155], v[154:155], 1.0 op_sel_hi:[1,0]
	v_pk_add_f32 v[148:149], v[148:149], 1.0 op_sel_hi:[1,0]
	v_pk_add_f32 v[146:147], v[146:147], 1.0 op_sel_hi:[1,0]
	v_rcp_f32_e32 v154, v154
	v_rcp_f32_e32 v155, v155
	v_rcp_f32_e32 v156, v156
	v_rcp_f32_e32 v157, v157
	v_rcp_f32_e32 v146, v146
	v_rcp_f32_e32 v147, v147
	v_rcp_f32_e32 v148, v148
	v_rcp_f32_e32 v149, v149
	v_pk_add_f32 v[164:165], v[164:165], v[76:77]
	v_pk_add_f32 v[162:163], v[162:163], v[74:75]
	v_pk_add_f32 v[152:153], v[152:153], v[68:69]
	v_pk_add_f32 v[150:151], v[150:151], v[66:67]
	v_lshlrev_b32_e32 v230, 16, v216
	v_and_b32_e32 v231, 0xffff0000, v216
	v_lshlrev_b32_e32 v216, 16, v217
	v_and_b32_e32 v217, 0xffff0000, v217
	v_lshlrev_b32_e32 v232, 16, v218
	v_and_b32_e32 v233, 0xffff0000, v218
	v_lshlrev_b32_e32 v218, 16, v219
	v_and_b32_e32 v219, 0xffff0000, v219
	v_pk_fma_f32 v[156:157], v[164:165], v[156:157], v[216:217]
	v_pk_fma_f32 v[154:155], v[162:163], v[154:155], v[230:231]
	v_pk_fma_f32 v[152:153], v[152:153], v[148:149], v[218:219]
	v_pk_fma_f32 v[150:151], v[150:151], v[146:147], v[232:233]
	v_mul_f32_e32 v162, v155, v155
	v_mul_f32_e32 v163, v157, v157
	v_mul_f32_e32 v146, v151, v151
	v_mul_f32_e32 v147, v153, v153
	v_fmac_f32_e32 v162, v154, v154
	v_fmac_f32_e32 v163, v156, v156
	v_fmac_f32_e32 v146, v150, v150
	v_fmac_f32_e32 v147, v152, v152
	v_add_f32_e32 v162, v162, v163
	v_add_f32_e32 v146, v146, v147
	v_add_f32_e32 v149, v162, v146
	ds_bpermute_b32 v164, v225, v149
	v_lshl_add_u64 v[146:147], s[44:45], 0, v[228:229]
	v_lshl_add_u64 v[162:163], v[146:147], 0, v[220:221]
	v_cvt_pk_bf16_f32 v148, v154, v155
	s_waitcnt lgkmcnt(0)
	v_add_f32_e32 v146, v149, v164
	ds_bpermute_b32 v147, v226, v146
	v_cvt_pk_bf16_f32 v149, v156, v157
	v_cvt_pk_bf16_f32 v150, v150, v151
	v_cvt_pk_bf16_f32 v151, v152, v153
	global_store_dwordx4 v[162:163], v[148:151], off sc1
	s_and_saveexec_b64 s[20:21], s[4:5]
	s_cbranch_execz .LBB0_1172
	s_waitcnt lgkmcnt(0)
	v_add_f32_e32 v146, v146, v147
	v_fma_f32 v146, v146, s36, 0.5
	v_trunc_f32_e32 v146, v146
	v_mul_f32_e32 v147, 0x2f800000, v146
	v_floor_f32_e32 v147, v147
	v_fmac_f32_e32 v146, 0xcf800000, v147
	v_cvt_u32_f32_e32 v146, v146
	v_cvt_u32_f32_e32 v147, v147
	v_lshl_add_u64 v[148:149], v[192:193], 3, s[26:27]
	global_atomic_add_x2 v[148:149], v[146:147], off
.LBB0_1172:
	s_or_b64 exec, exec, s[20:21]
	v_pk_add_f32 v[140:141], v[140:141], v[80:81]
	v_pk_add_f32 v[138:139], v[138:139], v[78:79]
	v_pk_add_f32 v[128:129], v[128:129], v[72:73]
	v_pk_add_f32 v[126:127], v[126:127], v[70:71]
	v_pk_mul_f32 v[140:141], v[140:141], s[64:65] op_sel_hi:[1,0]
	v_pk_mul_f32 v[138:139], v[138:139], s[64:65] op_sel_hi:[1,0]
	v_pk_mul_f32 v[128:129], v[128:129], s[64:65] op_sel_hi:[1,0]
	v_pk_mul_f32 v[126:127], v[126:127], s[64:65] op_sel_hi:[1,0]
	v_exp_f32_e32 v138, v138
	v_exp_f32_e32 v139, v139
	v_exp_f32_e32 v140, v140
	v_exp_f32_e32 v141, v141
	v_exp_f32_e32 v126, v126
	v_exp_f32_e32 v127, v127
	v_exp_f32_e32 v128, v128
	v_exp_f32_e32 v129, v129
	v_pk_add_f32 v[140:141], v[140:141], 1.0 op_sel_hi:[1,0]
	v_pk_add_f32 v[138:139], v[138:139], 1.0 op_sel_hi:[1,0]
	v_pk_add_f32 v[126:127], v[126:127], 1.0 op_sel_hi:[1,0]
	v_pk_add_f32 v[128:129], v[128:129], 1.0 op_sel_hi:[1,0]
	v_rcp_f32_e32 v138, v138
	v_rcp_f32_e32 v139, v139
	v_rcp_f32_e32 v140, v140
	v_rcp_f32_e32 v141, v141
	v_rcp_f32_e32 v126, v126
	v_rcp_f32_e32 v127, v127
	v_rcp_f32_e32 v128, v128
	v_rcp_f32_e32 v129, v129
	v_lshlrev_b32_e32 v148, 16, v170
	v_and_b32_e32 v149, 0xffff0000, v170
	v_lshlrev_b32_e32 v150, 16, v171
	v_and_b32_e32 v151, 0xffff0000, v171
	v_lshlrev_b32_e32 v152, 16, v172
	v_and_b32_e32 v153, 0xffff0000, v172
	v_lshlrev_b32_e32 v154, 16, v173
	v_and_b32_e32 v155, 0xffff0000, v173
	v_pk_add_f32 v[144:145], v[144:145], v[76:77]
	v_pk_add_f32 v[142:143], v[142:143], v[74:75]
	v_pk_add_f32 v[136:137], v[136:137], v[68:69]
	v_pk_add_f32 v[134:135], v[134:135], v[66:67]
	v_pk_fma_f32 v[140:141], v[144:145], v[140:141], v[150:151]
	v_pk_fma_f32 v[138:139], v[142:143], v[138:139], v[148:149]
	v_pk_fma_f32 v[136:137], v[136:137], v[128:129], v[154:155]
	v_pk_fma_f32 v[128:129], v[134:135], v[126:127], v[152:153]
	v_mul_f32_e32 v142, v139, v139
	v_mul_f32_e32 v143, v141, v141
	v_mul_f32_e32 v126, v129, v129
	v_mul_f32_e32 v127, v137, v137
	v_fmac_f32_e32 v142, v138, v138
	v_fmac_f32_e32 v143, v140, v140
	v_fmac_f32_e32 v126, v128, v128
	v_fmac_f32_e32 v127, v136, v136
	s_waitcnt lgkmcnt(0)
	v_lshl_add_u64 v[146:147], s[44:45], 0, v[208:209]
	v_add_f32_e32 v142, v142, v143
	v_add_f32_e32 v126, v126, v127
	v_add_f32_e32 v142, v142, v126
	v_lshl_add_u64 v[134:135], v[190:191], 1, v[146:147]
	v_cvt_pk_bf16_f32 v126, v138, v139
	v_cvt_pk_bf16_f32 v127, v140, v141
	v_cvt_pk_bf16_f32 v128, v128, v129
	v_cvt_pk_bf16_f32 v129, v136, v137
	global_store_dwordx4 v[134:135], v[126:129], off sc1
	ds_bpermute_b32 v126, v225, v142
	s_waitcnt lgkmcnt(0)
	v_add_f32_e32 v126, v142, v126
	ds_bpermute_b32 v127, v226, v126
	s_and_saveexec_b64 s[20:21], s[4:5]
	s_cbranch_execz .LBB0_1174
	s_waitcnt lgkmcnt(0)
	v_add_f32_e32 v126, v126, v127
	v_fma_f32 v126, v126, s36, 0.5
	v_trunc_f32_e32 v126, v126
	v_mul_f32_e32 v127, 0x2f800000, v126
	v_floor_f32_e32 v127, v127
	v_fmac_f32_e32 v126, 0xcf800000, v127
	v_cvt_u32_f32_e32 v126, v126
	v_cvt_u32_f32_e32 v127, v127
	v_lshl_add_u64 v[128:129], v[206:207], 3, s[26:27]
	global_atomic_add_x2 v[128:129], v[126:127], off
.LBB0_1174:
	s_or_b64 exec, exec, s[20:21]
	v_pk_add_f32 v[120:121], v[120:121], v[80:81]
	v_pk_add_f32 v[118:119], v[118:119], v[78:79]
	v_pk_add_f32 v[108:109], v[108:109], v[72:73]
	v_pk_add_f32 v[106:107], v[106:107], v[70:71]
	v_pk_mul_f32 v[120:121], v[120:121], s[64:65] op_sel_hi:[1,0]
	v_pk_mul_f32 v[118:119], v[118:119], s[64:65] op_sel_hi:[1,0]
	v_pk_mul_f32 v[108:109], v[108:109], s[64:65] op_sel_hi:[1,0]
	v_pk_mul_f32 v[106:107], v[106:107], s[64:65] op_sel_hi:[1,0]
	v_exp_f32_e32 v118, v118
	v_exp_f32_e32 v119, v119
	v_exp_f32_e32 v120, v120
	v_exp_f32_e32 v121, v121
	v_exp_f32_e32 v106, v106
	v_exp_f32_e32 v107, v107
	v_exp_f32_e32 v108, v108
	v_exp_f32_e32 v109, v109
	v_pk_add_f32 v[120:121], v[120:121], 1.0 op_sel_hi:[1,0]
	v_pk_add_f32 v[118:119], v[118:119], 1.0 op_sel_hi:[1,0]
	v_pk_add_f32 v[106:107], v[106:107], 1.0 op_sel_hi:[1,0]
	v_pk_add_f32 v[108:109], v[108:109], 1.0 op_sel_hi:[1,0]
	v_rcp_f32_e32 v118, v118
	v_rcp_f32_e32 v119, v119
	v_rcp_f32_e32 v120, v120
	v_rcp_f32_e32 v121, v121
	v_rcp_f32_e32 v106, v106
	v_rcp_f32_e32 v107, v107
	v_rcp_f32_e32 v108, v108
	v_rcp_f32_e32 v109, v109
	v_lshlrev_b32_e32 v128, 16, v166
	v_and_b32_e32 v129, 0xffff0000, v166
	v_lshlrev_b32_e32 v134, 16, v167
	v_and_b32_e32 v135, 0xffff0000, v167
	v_lshlrev_b32_e32 v136, 16, v168
	v_and_b32_e32 v137, 0xffff0000, v168
	v_lshlrev_b32_e32 v138, 16, v169
	v_and_b32_e32 v139, 0xffff0000, v169
	v_pk_add_f32 v[124:125], v[124:125], v[76:77]
	v_pk_add_f32 v[122:123], v[122:123], v[74:75]
	v_pk_add_f32 v[116:117], v[116:117], v[68:69]
	v_pk_add_f32 v[114:115], v[114:115], v[66:67]
	v_pk_fma_f32 v[120:121], v[124:125], v[120:121], v[134:135]
	v_pk_fma_f32 v[118:119], v[122:123], v[118:119], v[128:129]
	v_pk_fma_f32 v[116:117], v[116:117], v[108:109], v[138:139]
	v_pk_fma_f32 v[108:109], v[114:115], v[106:107], v[136:137]
	v_mul_f32_e32 v122, v119, v119
	v_mul_f32_e32 v123, v121, v121
	v_mul_f32_e32 v106, v109, v109
	v_mul_f32_e32 v107, v117, v117
	v_fmac_f32_e32 v122, v118, v118
	v_fmac_f32_e32 v123, v120, v120
	v_fmac_f32_e32 v106, v108, v108
	v_fmac_f32_e32 v107, v116, v116
	s_waitcnt lgkmcnt(0)
	v_lshl_add_u64 v[126:127], s[44:45], 0, v[204:205]
	v_add_f32_e32 v122, v122, v123
	v_add_f32_e32 v106, v106, v107
	v_add_f32_e32 v122, v122, v106
	v_lshl_add_u64 v[114:115], v[190:191], 1, v[126:127]
	v_cvt_pk_bf16_f32 v106, v118, v119
	v_cvt_pk_bf16_f32 v107, v120, v121
	v_cvt_pk_bf16_f32 v108, v108, v109
	v_cvt_pk_bf16_f32 v109, v116, v117
	global_store_dwordx4 v[114:115], v[106:109], off sc1
	ds_bpermute_b32 v106, v225, v122
	s_waitcnt lgkmcnt(0)
	v_add_f32_e32 v106, v122, v106
	ds_bpermute_b32 v107, v226, v106
	s_and_saveexec_b64 s[20:21], s[4:5]
	s_cbranch_execz .LBB0_1176
	s_waitcnt lgkmcnt(0)
	v_add_f32_e32 v106, v106, v107
	v_fma_f32 v106, v106, s36, 0.5
	v_trunc_f32_e32 v106, v106
	v_mul_f32_e32 v107, 0x2f800000, v106
	v_floor_f32_e32 v107, v107
	v_fmac_f32_e32 v106, 0xcf800000, v107
	v_cvt_u32_f32_e32 v106, v106
	v_cvt_u32_f32_e32 v107, v107
	v_lshl_add_u64 v[108:109], v[202:203], 3, s[26:27]
	global_atomic_add_x2 v[108:109], v[106:107], off
.LBB0_1176:
	s_or_b64 exec, exec, s[20:21]
	v_pk_add_f32 v[96:97], v[96:97], v[80:81]
	v_pk_add_f32 v[94:95], v[94:95], v[78:79]
	v_pk_add_f32 v[84:85], v[84:85], v[72:73]
	v_pk_add_f32 v[82:83], v[82:83], v[70:71]
	v_pk_mul_f32 v[96:97], v[96:97], s[64:65] op_sel_hi:[1,0]
	v_pk_mul_f32 v[94:95], v[94:95], s[64:65] op_sel_hi:[1,0]
	v_pk_mul_f32 v[84:85], v[84:85], s[64:65] op_sel_hi:[1,0]
	v_pk_mul_f32 v[82:83], v[82:83], s[64:65] op_sel_hi:[1,0]
	v_exp_f32_e32 v94, v94
	v_exp_f32_e32 v95, v95
	v_exp_f32_e32 v96, v96
	v_exp_f32_e32 v97, v97
	v_exp_f32_e32 v82, v82
	v_exp_f32_e32 v83, v83
	v_exp_f32_e32 v84, v84
	v_exp_f32_e32 v85, v85
	v_pk_add_f32 v[96:97], v[96:97], 1.0 op_sel_hi:[1,0]
	v_pk_add_f32 v[94:95], v[94:95], 1.0 op_sel_hi:[1,0]
	v_pk_add_f32 v[82:83], v[82:83], 1.0 op_sel_hi:[1,0]
	v_pk_add_f32 v[84:85], v[84:85], 1.0 op_sel_hi:[1,0]
	v_rcp_f32_e32 v94, v94
	v_rcp_f32_e32 v95, v95
	v_rcp_f32_e32 v96, v96
	v_rcp_f32_e32 v97, v97
	v_rcp_f32_e32 v82, v82
	v_rcp_f32_e32 v83, v83
	v_rcp_f32_e32 v84, v84
	v_rcp_f32_e32 v85, v85
	v_lshlrev_b32_e32 v108, 16, v158
	v_and_b32_e32 v109, 0xffff0000, v158
	v_lshlrev_b32_e32 v114, 16, v159
	v_and_b32_e32 v115, 0xffff0000, v159
	v_lshlrev_b32_e32 v116, 16, v160
	v_and_b32_e32 v117, 0xffff0000, v160
	v_lshlrev_b32_e32 v118, 16, v161
	v_and_b32_e32 v119, 0xffff0000, v161
	v_pk_add_f32 v[100:101], v[100:101], v[76:77]
	v_pk_add_f32 v[98:99], v[98:99], v[74:75]
	v_pk_add_f32 v[92:93], v[92:93], v[68:69]
	v_pk_add_f32 v[90:91], v[90:91], v[66:67]
	v_pk_fma_f32 v[96:97], v[100:101], v[96:97], v[114:115]
	v_pk_fma_f32 v[94:95], v[98:99], v[94:95], v[108:109]
	v_pk_fma_f32 v[92:93], v[92:93], v[84:85], v[118:119]
	v_pk_fma_f32 v[84:85], v[90:91], v[82:83], v[116:117]
	v_mul_f32_e32 v98, v95, v95
	v_mul_f32_e32 v99, v97, v97
	v_mul_f32_e32 v82, v85, v85
	v_mul_f32_e32 v83, v93, v93
	v_fmac_f32_e32 v98, v94, v94
	v_fmac_f32_e32 v99, v96, v96
	v_fmac_f32_e32 v82, v84, v84
	v_fmac_f32_e32 v83, v92, v92
	s_waitcnt lgkmcnt(0)
	v_lshl_add_u64 v[106:107], s[44:45], 0, v[200:201]
	v_add_f32_e32 v98, v98, v99
	v_add_f32_e32 v82, v82, v83
	v_add_f32_e32 v98, v98, v82
	v_lshl_add_u64 v[90:91], v[190:191], 1, v[106:107]
	v_cvt_pk_bf16_f32 v82, v94, v95
	v_cvt_pk_bf16_f32 v83, v96, v97
	v_cvt_pk_bf16_f32 v84, v84, v85
	v_cvt_pk_bf16_f32 v85, v92, v93
	global_store_dwordx4 v[90:91], v[82:85], off sc1
	ds_bpermute_b32 v82, v225, v98
	s_waitcnt lgkmcnt(0)
	v_add_f32_e32 v82, v98, v82
	ds_bpermute_b32 v83, v226, v82
	s_and_saveexec_b64 s[20:21], s[4:5]
	s_cbranch_execz .LBB0_1178
	s_waitcnt lgkmcnt(0)
	v_add_f32_e32 v82, v82, v83
	v_fma_f32 v82, v82, s36, 0.5
	v_trunc_f32_e32 v82, v82
	v_mul_f32_e32 v83, 0x2f800000, v82
	v_floor_f32_e32 v83, v83
	v_fmac_f32_e32 v82, 0xcf800000, v83
	v_cvt_u32_f32_e32 v82, v82
	v_cvt_u32_f32_e32 v83, v83
	v_lshl_add_u64 v[84:85], v[198:199], 3, s[26:27]
	global_atomic_add_x2 v[84:85], v[82:83], off
.LBB0_1178:
	s_or_b64 exec, exec, s[20:21]
	v_pk_add_f32 v[60:61], v[60:61], v[80:81]
	v_pk_add_f32 v[58:59], v[58:59], v[78:79]
	v_pk_add_f32 v[52:53], v[52:53], v[72:73]
	v_pk_add_f32 v[50:51], v[50:51], v[70:71]
	v_pk_mul_f32 v[60:61], v[60:61], s[64:65] op_sel_hi:[1,0]
	v_pk_mul_f32 v[58:59], v[58:59], s[64:65] op_sel_hi:[1,0]
	v_pk_mul_f32 v[52:53], v[52:53], s[64:65] op_sel_hi:[1,0]
	v_pk_mul_f32 v[50:51], v[50:51], s[64:65] op_sel_hi:[1,0]
	v_exp_f32_e32 v58, v58
	v_exp_f32_e32 v59, v59
	v_exp_f32_e32 v60, v60
	v_exp_f32_e32 v61, v61
	v_exp_f32_e32 v50, v50
	v_exp_f32_e32 v51, v51
	v_exp_f32_e32 v52, v52
	v_exp_f32_e32 v53, v53
	v_pk_add_f32 v[60:61], v[60:61], 1.0 op_sel_hi:[1,0]
	v_pk_add_f32 v[58:59], v[58:59], 1.0 op_sel_hi:[1,0]
	v_pk_add_f32 v[50:51], v[50:51], 1.0 op_sel_hi:[1,0]
	v_pk_add_f32 v[52:53], v[52:53], 1.0 op_sel_hi:[1,0]
	v_rcp_f32_e32 v58, v58
	v_rcp_f32_e32 v59, v59
	v_rcp_f32_e32 v60, v60
	v_rcp_f32_e32 v61, v61
	v_rcp_f32_e32 v50, v50
	v_rcp_f32_e32 v51, v51
	v_rcp_f32_e32 v52, v52
	v_rcp_f32_e32 v53, v53
	v_lshlrev_b32_e32 v84, 16, v130
	v_and_b32_e32 v85, 0xffff0000, v130
	v_lshlrev_b32_e32 v90, 16, v131
	v_and_b32_e32 v91, 0xffff0000, v131
	v_lshlrev_b32_e32 v92, 16, v132
	v_and_b32_e32 v93, 0xffff0000, v132
	v_lshlrev_b32_e32 v94, 16, v133
	v_and_b32_e32 v95, 0xffff0000, v133
	v_pk_add_f32 v[64:65], v[64:65], v[76:77]
	v_pk_add_f32 v[62:63], v[62:63], v[74:75]
	v_pk_add_f32 v[56:57], v[56:57], v[68:69]
	v_pk_add_f32 v[54:55], v[54:55], v[66:67]
	v_pk_fma_f32 v[60:61], v[64:65], v[60:61], v[90:91]
	v_pk_fma_f32 v[58:59], v[62:63], v[58:59], v[84:85]
	v_pk_fma_f32 v[56:57], v[56:57], v[52:53], v[94:95]
	v_pk_fma_f32 v[52:53], v[54:55], v[50:51], v[92:93]
	v_mul_f32_e32 v62, v59, v59
	v_mul_f32_e32 v63, v61, v61
	v_mul_f32_e32 v50, v53, v53
	v_mul_f32_e32 v51, v57, v57
	v_fmac_f32_e32 v62, v58, v58
	v_fmac_f32_e32 v63, v60, v60
	v_fmac_f32_e32 v50, v52, v52
	v_fmac_f32_e32 v51, v56, v56
	s_waitcnt lgkmcnt(0)
	v_lshl_add_u64 v[82:83], s[44:45], 0, v[196:197]
	v_add_f32_e32 v62, v62, v63
	v_add_f32_e32 v50, v50, v51
	v_add_f32_e32 v62, v62, v50
	v_lshl_add_u64 v[54:55], v[190:191], 1, v[82:83]
	v_cvt_pk_bf16_f32 v50, v58, v59
	v_cvt_pk_bf16_f32 v51, v60, v61
	v_cvt_pk_bf16_f32 v52, v52, v53
	v_cvt_pk_bf16_f32 v53, v56, v57
	global_store_dwordx4 v[54:55], v[50:53], off sc1
	ds_bpermute_b32 v50, v225, v62
	s_waitcnt lgkmcnt(0)
	v_add_f32_e32 v50, v62, v50
	ds_bpermute_b32 v51, v226, v50
	s_and_saveexec_b64 s[20:21], s[4:5]
	s_cbranch_execz .LBB0_1180
	s_waitcnt lgkmcnt(0)
	v_add_f32_e32 v50, v50, v51
	v_fma_f32 v50, v50, s36, 0.5
	v_trunc_f32_e32 v50, v50
	v_mul_f32_e32 v51, 0x2f800000, v50
	v_floor_f32_e32 v51, v51
	v_fmac_f32_e32 v50, 0xcf800000, v51
	v_cvt_u32_f32_e32 v50, v50
	v_cvt_u32_f32_e32 v51, v51
	v_lshl_add_u64 v[52:53], v[194:195], 3, s[26:27]
	global_atomic_add_x2 v[52:53], v[50:51], off
.LBB0_1180:
	s_or_b64 exec, exec, s[20:21]
	v_pk_add_f32 v[44:45], v[44:45], v[80:81]
	v_pk_add_f32 v[42:43], v[42:43], v[78:79]
	v_pk_add_f32 v[36:37], v[36:37], v[72:73]
	v_pk_add_f32 v[34:35], v[34:35], v[70:71]
	v_pk_mul_f32 v[44:45], v[44:45], s[64:65] op_sel_hi:[1,0]
	v_pk_mul_f32 v[42:43], v[42:43], s[64:65] op_sel_hi:[1,0]
	v_pk_mul_f32 v[36:37], v[36:37], s[64:65] op_sel_hi:[1,0]
	v_pk_mul_f32 v[34:35], v[34:35], s[64:65] op_sel_hi:[1,0]
	v_exp_f32_e32 v42, v42
	v_exp_f32_e32 v44, v44
	v_exp_f32_e32 v45, v45
	v_exp_f32_e32 v43, v43
	v_exp_f32_e32 v34, v34
	v_exp_f32_e32 v36, v36
	v_exp_f32_e32 v37, v37
	v_exp_f32_e32 v35, v35
	v_pk_add_f32 v[44:45], v[44:45], 1.0 op_sel_hi:[1,0]
	v_pk_add_f32 v[42:43], v[42:43], 1.0 op_sel_hi:[1,0]
	v_pk_add_f32 v[36:37], v[36:37], 1.0 op_sel_hi:[1,0]
	v_pk_add_f32 v[34:35], v[34:35], 1.0 op_sel_hi:[1,0]
	v_rcp_f32_e32 v42, v42
	v_rcp_f32_e32 v44, v44
	v_rcp_f32_e32 v45, v45
	v_rcp_f32_e32 v43, v43
	v_rcp_f32_e32 v34, v34
	v_rcp_f32_e32 v36, v36
	v_rcp_f32_e32 v37, v37
	v_rcp_f32_e32 v35, v35
	v_lshlrev_b32_e32 v52, 16, v110
	v_and_b32_e32 v53, 0xffff0000, v110
	v_lshlrev_b32_e32 v54, 16, v111
	v_and_b32_e32 v55, 0xffff0000, v111
	v_lshlrev_b32_e32 v56, 16, v112
	v_and_b32_e32 v57, 0xffff0000, v112
	v_lshlrev_b32_e32 v58, 16, v113
	v_and_b32_e32 v59, 0xffff0000, v113
	v_pk_add_f32 v[48:49], v[48:49], v[76:77]
	v_pk_add_f32 v[46:47], v[46:47], v[74:75]
	v_pk_add_f32 v[40:41], v[40:41], v[68:69]
	v_pk_add_f32 v[38:39], v[38:39], v[66:67]
	v_pk_fma_f32 v[44:45], v[48:49], v[44:45], v[54:55]
	v_pk_fma_f32 v[42:43], v[46:47], v[42:43], v[52:53]
	v_pk_fma_f32 v[40:41], v[40:41], v[36:37], v[58:59]
	v_pk_fma_f32 v[38:39], v[38:39], v[34:35], v[56:57]
	v_mul_f32_e32 v46, v43, v43
	v_mul_f32_e32 v47, v45, v45
	v_mul_f32_e32 v34, v39, v39
	v_mul_f32_e32 v35, v41, v41
	v_fmac_f32_e32 v46, v42, v42
	v_fmac_f32_e32 v47, v44, v44
	v_fmac_f32_e32 v34, v38, v38
	v_fmac_f32_e32 v35, v40, v40
	v_add_f32_e32 v46, v46, v47
	v_add_f32_e32 v34, v34, v35
	v_add_f32_e32 v37, v46, v34
	ds_bpermute_b32 v48, v225, v37
	v_add_u32_e32 v50, 0x90, v192
	s_waitcnt lgkmcnt(1)
	v_ashrrev_i32_e32 v51, 31, v50
	v_lshlrev_b64 v[34:35], 11, v[50:51]
	v_lshl_add_u64 v[34:35], s[44:45], 0, v[34:35]
	v_lshl_add_u64 v[46:47], v[190:191], 1, v[34:35]
	s_waitcnt lgkmcnt(0)
	v_add_f32_e32 v34, v37, v48
	ds_bpermute_b32 v35, v226, v34
	v_cvt_pk_bf16_f32 v36, v42, v43
	v_cvt_pk_bf16_f32 v37, v44, v45
	v_cvt_pk_bf16_f32 v38, v38, v39
	v_cvt_pk_bf16_f32 v39, v40, v41
	global_store_dwordx4 v[46:47], v[36:39], off sc1
	s_and_saveexec_b64 s[20:21], s[4:5]
	s_cbranch_execz .LBB0_1182
	s_waitcnt lgkmcnt(0)
	v_add_f32_e32 v34, v34, v35
	v_fma_f32 v34, v34, s36, 0.5
	v_trunc_f32_e32 v34, v34
	v_mul_f32_e32 v35, 0x2f800000, v34
	v_floor_f32_e32 v35, v35
	v_fmac_f32_e32 v34, 0xcf800000, v35
	v_cvt_u32_f32_e32 v34, v34
	v_cvt_u32_f32_e32 v35, v35
	v_lshl_add_u64 v[36:37], v[50:51], 3, s[26:27]
	global_atomic_add_x2 v[36:37], v[34:35], off
.LBB0_1182:
	s_or_b64 exec, exec, s[20:21]
	v_pk_add_f32 v[28:29], v[28:29], v[80:81]
	v_pk_add_f32 v[26:27], v[26:27], v[78:79]
	v_pk_add_f32 v[20:21], v[20:21], v[72:73]
	v_pk_add_f32 v[18:19], v[18:19], v[70:71]
	v_pk_mul_f32 v[28:29], v[28:29], s[64:65] op_sel_hi:[1,0]
	v_pk_mul_f32 v[26:27], v[26:27], s[64:65] op_sel_hi:[1,0]
	v_pk_mul_f32 v[20:21], v[20:21], s[64:65] op_sel_hi:[1,0]
	v_pk_mul_f32 v[18:19], v[18:19], s[64:65] op_sel_hi:[1,0]
	v_exp_f32_e32 v26, v26
	v_exp_f32_e32 v28, v28
	v_exp_f32_e32 v29, v29
	v_exp_f32_e32 v27, v27
	v_exp_f32_e32 v18, v18
	v_exp_f32_e32 v20, v20
	v_exp_f32_e32 v21, v21
	v_exp_f32_e32 v19, v19
	v_pk_add_f32 v[28:29], v[28:29], 1.0 op_sel_hi:[1,0]
	v_pk_add_f32 v[26:27], v[26:27], 1.0 op_sel_hi:[1,0]
	v_pk_add_f32 v[20:21], v[20:21], 1.0 op_sel_hi:[1,0]
	v_pk_add_f32 v[18:19], v[18:19], 1.0 op_sel_hi:[1,0]
	v_rcp_f32_e32 v26, v26
	v_rcp_f32_e32 v28, v28
	v_rcp_f32_e32 v29, v29
	v_rcp_f32_e32 v27, v27
	v_rcp_f32_e32 v18, v18
	v_rcp_f32_e32 v20, v20
	v_rcp_f32_e32 v21, v21
	v_rcp_f32_e32 v19, v19
	v_lshlrev_b32_e32 v36, 16, v102
	v_and_b32_e32 v37, 0xffff0000, v102
	v_lshlrev_b32_e32 v38, 16, v103
	v_and_b32_e32 v39, 0xffff0000, v103
	v_lshlrev_b32_e32 v40, 16, v104
	v_and_b32_e32 v41, 0xffff0000, v104
	v_lshlrev_b32_e32 v42, 16, v105
	v_and_b32_e32 v43, 0xffff0000, v105
	v_pk_add_f32 v[32:33], v[32:33], v[76:77]
	v_pk_add_f32 v[30:31], v[30:31], v[74:75]
	v_pk_add_f32 v[24:25], v[24:25], v[68:69]
	v_pk_add_f32 v[22:23], v[22:23], v[66:67]
	v_pk_fma_f32 v[28:29], v[32:33], v[28:29], v[38:39]
	v_pk_fma_f32 v[26:27], v[30:31], v[26:27], v[36:37]
	v_pk_fma_f32 v[24:25], v[24:25], v[20:21], v[42:43]
	v_pk_fma_f32 v[22:23], v[22:23], v[18:19], v[40:41]
	v_mul_f32_e32 v30, v27, v27
	v_mul_f32_e32 v31, v29, v29
	v_mul_f32_e32 v18, v23, v23
	v_mul_f32_e32 v19, v25, v25
	v_fmac_f32_e32 v30, v26, v26
	v_fmac_f32_e32 v31, v28, v28
	v_fmac_f32_e32 v18, v22, v22
	v_fmac_f32_e32 v19, v24, v24
	v_add_f32_e32 v30, v30, v31
	v_add_f32_e32 v18, v18, v19
	v_add_f32_e32 v21, v30, v18
	ds_bpermute_b32 v32, v225, v21
	v_add_u32_e32 v34, 0xa0, v192
	s_waitcnt lgkmcnt(1)
	v_ashrrev_i32_e32 v35, 31, v34
	v_lshlrev_b64 v[18:19], 11, v[34:35]
	v_lshl_add_u64 v[18:19], s[44:45], 0, v[18:19]
	v_lshl_add_u64 v[30:31], v[190:191], 1, v[18:19]
	s_waitcnt lgkmcnt(0)
	v_add_f32_e32 v18, v21, v32
	ds_bpermute_b32 v19, v226, v18
	v_cvt_pk_bf16_f32 v20, v26, v27
	v_cvt_pk_bf16_f32 v21, v28, v29
	v_cvt_pk_bf16_f32 v22, v22, v23
	v_cvt_pk_bf16_f32 v23, v24, v25
	global_store_dwordx4 v[30:31], v[20:23], off sc1
	s_and_saveexec_b64 s[20:21], s[4:5]
	s_cbranch_execz .LBB0_1184
	s_waitcnt lgkmcnt(0)
	v_add_f32_e32 v18, v18, v19
	v_fma_f32 v18, v18, s36, 0.5
	v_trunc_f32_e32 v18, v18
	v_mul_f32_e32 v19, 0x2f800000, v18
	v_floor_f32_e32 v19, v19
	v_fmac_f32_e32 v18, 0xcf800000, v19
	v_cvt_u32_f32_e32 v18, v18
	v_cvt_u32_f32_e32 v19, v19
	v_lshl_add_u64 v[20:21], v[34:35], 3, s[26:27]
	global_atomic_add_x2 v[20:21], v[18:19], off
.LBB0_1184:
	s_or_b64 exec, exec, s[20:21]
	v_pk_add_f32 v[12:13], v[12:13], v[80:81]
	v_pk_add_f32 v[10:11], v[10:11], v[78:79]
	v_pk_add_f32 v[4:5], v[4:5], v[72:73]
	v_pk_add_f32 v[2:3], v[2:3], v[70:71]
	v_pk_mul_f32 v[12:13], v[12:13], s[64:65] op_sel_hi:[1,0]
	v_pk_mul_f32 v[10:11], v[10:11], s[64:65] op_sel_hi:[1,0]
	v_pk_mul_f32 v[4:5], v[4:5], s[64:65] op_sel_hi:[1,0]
	v_pk_mul_f32 v[2:3], v[2:3], s[64:65] op_sel_hi:[1,0]
	v_exp_f32_e32 v10, v10
	v_exp_f32_e32 v12, v12
	v_exp_f32_e32 v13, v13
	v_exp_f32_e32 v11, v11
	v_exp_f32_e32 v2, v2
	v_exp_f32_e32 v4, v4
	v_exp_f32_e32 v5, v5
	v_exp_f32_e32 v3, v3
	v_pk_add_f32 v[12:13], v[12:13], 1.0 op_sel_hi:[1,0]
	v_pk_add_f32 v[10:11], v[10:11], 1.0 op_sel_hi:[1,0]
	v_pk_add_f32 v[4:5], v[4:5], 1.0 op_sel_hi:[1,0]
	v_pk_add_f32 v[2:3], v[2:3], 1.0 op_sel_hi:[1,0]
	v_rcp_f32_e32 v10, v10
	v_rcp_f32_e32 v12, v12
	v_rcp_f32_e32 v13, v13
	v_rcp_f32_e32 v11, v11
	v_rcp_f32_e32 v2, v2
	v_rcp_f32_e32 v4, v4
	v_rcp_f32_e32 v5, v5
	v_rcp_f32_e32 v3, v3
	v_lshlrev_b32_e32 v20, 16, v86
	v_and_b32_e32 v21, 0xffff0000, v86
	v_lshlrev_b32_e32 v22, 16, v87
	v_and_b32_e32 v23, 0xffff0000, v87
	v_lshlrev_b32_e32 v24, 16, v88
	v_and_b32_e32 v25, 0xffff0000, v88
	v_lshlrev_b32_e32 v26, 16, v89
	v_and_b32_e32 v27, 0xffff0000, v89
	v_pk_add_f32 v[16:17], v[16:17], v[76:77]
	v_pk_add_f32 v[14:15], v[14:15], v[74:75]
	v_pk_add_f32 v[8:9], v[8:9], v[68:69]
	v_pk_add_f32 v[6:7], v[6:7], v[66:67]
	v_pk_fma_f32 v[12:13], v[16:17], v[12:13], v[22:23]
	v_pk_fma_f32 v[10:11], v[14:15], v[10:11], v[20:21]
	v_pk_fma_f32 v[8:9], v[8:9], v[4:5], v[26:27]
	v_pk_fma_f32 v[6:7], v[6:7], v[2:3], v[24:25]
	v_mul_f32_e32 v14, v11, v11
	v_mul_f32_e32 v15, v13, v13
	v_mul_f32_e32 v2, v7, v7
	v_mul_f32_e32 v3, v9, v9
	v_fmac_f32_e32 v14, v10, v10
	v_fmac_f32_e32 v15, v12, v12
	v_fmac_f32_e32 v2, v6, v6
	v_fmac_f32_e32 v3, v8, v8
	v_add_f32_e32 v14, v14, v15
	v_add_f32_e32 v2, v2, v3
	v_add_f32_e32 v5, v14, v2
	ds_bpermute_b32 v16, v225, v5
	v_add_u32_e32 v18, 0xb0, v192
	s_waitcnt lgkmcnt(1)
	v_ashrrev_i32_e32 v19, 31, v18
	v_lshlrev_b64 v[2:3], 11, v[18:19]
	v_lshl_add_u64 v[2:3], s[44:45], 0, v[2:3]
	v_lshl_add_u64 v[14:15], v[190:191], 1, v[2:3]
	s_waitcnt lgkmcnt(0)
	v_add_f32_e32 v2, v5, v16
	ds_bpermute_b32 v3, v226, v2
	v_cvt_pk_bf16_f32 v4, v10, v11
	v_cvt_pk_bf16_f32 v5, v12, v13
	v_cvt_pk_bf16_f32 v6, v6, v7
	v_cvt_pk_bf16_f32 v7, v8, v9
	global_store_dwordx4 v[14:15], v[4:7], off sc1
	s_and_saveexec_b64 s[20:21], s[4:5]
	s_cbranch_execz .LBB0_1186
	s_waitcnt lgkmcnt(0)
	v_add_f32_e32 v2, v2, v3
	v_fma_f32 v2, v2, s36, 0.5
	v_trunc_f32_e32 v2, v2
	v_mul_f32_e32 v3, 0x2f800000, v2
	v_floor_f32_e32 v3, v3
	v_fmac_f32_e32 v2, 0xcf800000, v3
	v_cvt_u32_f32_e32 v2, v2
	v_cvt_u32_f32_e32 v3, v3
	v_lshl_add_u64 v[4:5], v[18:19], 3, s[26:27]
	global_atomic_add_x2 v[4:5], v[2:3], off

.LBB0_1261:
	v_lshl_add_u32 v146, s46, 8, v160
	v_ashrrev_i32_e32 v147, 31, v146
	v_lshl_add_u64 v[148:149], v[146:147], 3, s[26:27]
	global_load_dwordx2 v[168:169], v[148:149], off nt
	global_load_dwordx2 v[170:171], v[148:149], off offset:128 nt
	global_load_dwordx2 v[158:159], v[148:149], off offset:256 nt
	global_load_dwordx2 v[156:157], v[148:149], off offset:384 nt
	global_load_dwordx2 v[154:155], v[148:149], off offset:1024 nt
	global_load_dwordx2 v[152:153], v[148:149], off offset:1152 nt
	global_load_dwordx2 v[150:151], v[148:149], off offset:1280 nt
	s_nop 0
	global_load_dwordx2 v[148:149], v[148:149], off offset:1408 nt
	v_lshl_or_b32 v172, s55, 7, v162
	v_pk_mul_f32 v[174:175], v[114:115], v[122:123]
	v_mov_b64_e32 v[122:123], s[18:19]
	v_ashrrev_i32_e32 v173, 31, v172
	v_pk_mul_f32 v[176:177], v[106:107], v[110:111]
	v_mad_i64_i32 v[178:179], s[20:21], v146, s54, v[122:123]
	v_lshlrev_b64 v[110:111], 1, v[172:173]
	v_pk_mul_f32 v[128:129], v[120:121], v[128:129]
	v_pk_mul_f32 v[126:127], v[118:119], v[126:127]
	v_pk_mul_f32 v[124:125], v[116:117], v[124:125]
	v_pk_mul_f32 v[112:113], v[108:109], v[112:113]
	v_pk_mul_f32 v[100:101], v[104:105], v[100:101]
	v_pk_mul_f32 v[98:99], v[102:103], v[98:99]
	v_pk_mul_f32 v[88:89], v[96:97], v[88:89]
	v_pk_mul_f32 v[86:87], v[94:95], v[86:87]
	v_pk_mul_f32 v[84:85], v[92:93], v[84:85]
	v_pk_mul_f32 v[82:83], v[90:91], v[82:83]
	v_pk_mul_f32 v[72:73], v[80:81], v[72:73]
	v_pk_mul_f32 v[70:71], v[78:79], v[70:71]
	v_pk_mul_f32 v[68:69], v[76:77], v[68:69]
	v_pk_mul_f32 v[66:67], v[74:75], v[66:67]
	v_pk_mul_f32 v[56:57], v[64:65], v[56:57]
	v_pk_mul_f32 v[54:55], v[62:63], v[54:55]
	v_pk_mul_f32 v[52:53], v[60:61], v[52:53]
	v_pk_mul_f32 v[50:51], v[58:59], v[50:51]
	v_pk_mul_f32 v[40:41], v[48:49], v[40:41]
	v_pk_mul_f32 v[38:39], v[46:47], v[38:39]
	v_pk_mul_f32 v[36:37], v[44:45], v[36:37]
	v_pk_mul_f32 v[34:35], v[42:43], v[34:35]
	v_pk_mul_f32 v[24:25], v[32:33], v[24:25]
	v_pk_mul_f32 v[22:23], v[30:31], v[22:23]
	v_pk_mul_f32 v[20:21], v[28:29], v[20:21]
	v_pk_mul_f32 v[18:19], v[26:27], v[18:19]
	v_pk_mul_f32 v[8:9], v[16:17], v[8:9]
	v_pk_mul_f32 v[6:7], v[14:15], v[6:7]
	v_pk_mul_f32 v[4:5], v[12:13], v[4:5]
	v_pk_mul_f32 v[2:3], v[10:11], v[2:3]
	s_andn2_b64 vcc, exec, s[4:5]
	s_mov_b64 s[4:5], -1
	s_waitcnt vmcnt(0)
	s_nop 0
	v_ffbh_u32_e32 v147, v169
	v_ffbh_u32_e32 v167, v171
	v_min_u32_e32 v147, 32, v147
	v_min_u32_e32 v167, 32, v167
	v_lshlrev_b64 v[168:169], v147, v[168:169]
	v_lshlrev_b64 v[170:171], v167, v[170:171]
	v_min_u32_e32 v168, 1, v168
	v_min_u32_e32 v170, 1, v170
	v_or_b32_e32 v168, v169, v168
	v_or_b32_e32 v169, v171, v170
	v_cvt_f32_u32_e32 v168, v168
	v_cvt_f32_u32_e32 v169, v169
	v_sub_u32_e32 v147, 32, v147
	v_sub_u32_e32 v167, 32, v167
	v_ldexp_f32 v147, v168, v147
	v_ldexp_f32 v167, v169, v167
	v_fmamk_f32 v147, v147, 0x30800000, v166
	v_fmamk_f32 v167, v167, 0x30800000, v166
	v_rsq_f32_e32 v147, v147
	v_rsq_f32_e32 v167, v167
	v_lshl_add_u64 v[168:169], v[178:179], 0, v[110:111]
	v_mul_f32_e32 v170, 0xbfb8aa3b, v147
	v_mul_f32_e32 v178, 0xbfb8aa3b, v167
	v_pk_mul_f32 v[120:121], v[120:121], v[170:171] op_sel_hi:[1,0]
	v_pk_mul_f32 v[118:119], v[118:119], v[170:171] op_sel_hi:[1,0]
	v_pk_mul_f32 v[116:117], v[116:117], v[170:171] op_sel_hi:[1,0]
	v_pk_mul_f32 v[114:115], v[114:115], v[170:171] op_sel_hi:[1,0]
	v_pk_mul_f32 v[108:109], v[108:109], v[178:179] op_sel_hi:[1,0]
	v_pk_mul_f32 v[106:107], v[106:107], v[178:179] op_sel_hi:[1,0]
	v_pk_mul_f32 v[170:171], v[104:105], v[178:179] op_sel_hi:[1,0]
	v_pk_mul_f32 v[178:179], v[102:103], v[178:179] op_sel_hi:[1,0]
	v_exp_f32_e32 v118, v118
	v_exp_f32_e32 v119, v119
	v_exp_f32_e32 v120, v120
	v_exp_f32_e32 v121, v121
	v_exp_f32_e32 v116, v116
	v_exp_f32_e32 v117, v117
	v_exp_f32_e32 v106, v106
	v_exp_f32_e32 v107, v107
	v_exp_f32_e32 v178, v178
	v_exp_f32_e32 v179, v179
	v_exp_f32_e32 v170, v170
	v_exp_f32_e32 v171, v171
	v_exp_f32_e32 v114, v114
	v_exp_f32_e32 v115, v115
	v_exp_f32_e32 v108, v108
	v_exp_f32_e32 v109, v109
	v_pk_add_f32 v[120:121], v[120:121], 1.0 op_sel_hi:[1,0]
	v_pk_add_f32 v[118:119], v[118:119], 1.0 op_sel_hi:[1,0]
	v_pk_add_f32 v[116:117], v[116:117], 1.0 op_sel_hi:[1,0]
	v_pk_add_f32 v[106:107], v[106:107], 1.0 op_sel_hi:[1,0]
	v_pk_add_f32 v[170:171], v[170:171], 1.0 op_sel_hi:[1,0]
	v_pk_add_f32 v[178:179], v[178:179], 1.0 op_sel_hi:[1,0]
	v_pk_add_f32 v[114:115], v[114:115], 1.0 op_sel_hi:[1,0]
	v_pk_add_f32 v[108:109], v[108:109], 1.0 op_sel_hi:[1,0]
	v_rcp_f32_e32 v118, v118
	v_rcp_f32_e32 v119, v119
	v_rcp_f32_e32 v120, v120
	v_rcp_f32_e32 v121, v121
	v_rcp_f32_e32 v116, v116
	v_rcp_f32_e32 v117, v117
	v_rcp_f32_e32 v106, v106
	v_rcp_f32_e32 v107, v107
	v_rcp_f32_e32 v178, v178
	v_rcp_f32_e32 v179, v179
	v_rcp_f32_e32 v170, v170
	v_rcp_f32_e32 v171, v171
	v_rcp_f32_e32 v114, v114
	v_rcp_f32_e32 v115, v115
	v_rcp_f32_e32 v108, v108
	v_rcp_f32_e32 v109, v109
	v_mul_f32_e32 v172, v147, v147
	v_mul_f32_e32 v180, v167, v167
	v_pk_mul_f32 v[118:119], v[172:173], v[118:119] op_sel_hi:[0,1]
	v_pk_mul_f32 v[120:121], v[172:173], v[120:121] op_sel_hi:[0,1]
	v_pk_mul_f32 v[116:117], v[172:173], v[116:117] op_sel_hi:[0,1]
	v_pk_mul_f32 v[106:107], v[180:181], v[106:107] op_sel_hi:[0,1]
	v_pk_mul_f32 v[102:103], v[180:181], v[178:179] op_sel_hi:[0,1]
	v_pk_mul_f32 v[104:105], v[180:181], v[170:171] op_sel_hi:[0,1]
	v_pk_mul_f32 v[114:115], v[172:173], v[114:115] op_sel_hi:[0,1]
	v_pk_mul_f32 v[108:109], v[180:181], v[108:109] op_sel_hi:[0,1]
	v_pk_mul_f32 v[120:121], v[128:129], v[120:121]
	v_pk_mul_f32 v[118:119], v[126:127], v[118:119]
	v_pk_mul_f32 v[116:117], v[124:125], v[116:117]
	v_pk_mul_f32 v[124:125], v[176:177], v[106:107]
	v_cvt_pk_bf16_f32 v106, v118, v119
	v_cvt_pk_bf16_f32 v107, v120, v121
	v_pk_mul_f32 v[104:105], v[100:101], v[104:105]
	v_pk_mul_f32 v[100:101], v[98:99], v[102:103]
	v_ffbh_u32_e32 v102, v159
	v_pk_mul_f32 v[114:115], v[174:175], v[114:115]
	v_pk_mul_f32 v[112:113], v[112:113], v[108:109]
	v_cvt_pk_bf16_f32 v108, v114, v115
	v_cvt_pk_bf16_f32 v109, v116, v117
	global_store_dwordx4 v[168:169], v[106:109], off sc1
	v_cvt_pk_bf16_f32 v98, v124, v125
	v_cvt_pk_bf16_f32 v99, v112, v113
	v_cvt_pk_bf16_f32 v100, v100, v101
	v_cvt_pk_bf16_f32 v101, v104, v105
	s_nop 1
	v_min_u32_e32 v107, 32, v102
	v_lshlrev_b64 v[102:103], v107, v[158:159]
	v_min_u32_e32 v102, 1, v102
	v_or_b32_e32 v102, v103, v102
	v_cvt_f32_u32_e32 v102, v102
	v_sub_u32_e32 v103, 32, v107
	v_or_b32_e32 v106, 16, v146
	v_ldexp_f32 v102, v102, v103
	v_fmamk_f32 v102, v102, 0x30800000, v166
	v_rsq_f32_e32 v107, v102
	v_mad_i64_i32 v[102:103], s[20:21], v106, s54, v[122:123]
	v_lshl_add_u64 v[102:103], v[102:103], 0, v[110:111]
	global_store_dwordx4 v[102:103], v[98:101], off sc1
	v_mul_f32_e32 v106, v107, v107
	s_nop 0
	v_mul_f32_e32 v98, 0xbfb8aa3b, v107
	v_pk_mul_f32 v[100:101], v[96:97], v[98:99] op_sel_hi:[1,0]
	v_pk_mul_f32 v[102:103], v[94:95], v[98:99] op_sel_hi:[1,0]
	v_exp_f32_e32 v100, v100
	v_exp_f32_e32 v102, v102
	v_exp_f32_e32 v103, v103
	v_exp_f32_e32 v101, v101
	v_pk_mul_f32 v[104:105], v[92:93], v[98:99] op_sel_hi:[1,0]
	v_pk_mul_f32 v[98:99], v[90:91], v[98:99] op_sel_hi:[1,0]
	v_pk_add_f32 v[102:103], v[102:103], 1.0 op_sel_hi:[1,0]
	v_pk_add_f32 v[100:101], v[100:101], 1.0 op_sel_hi:[1,0]
	v_rcp_f32_e32 v102, v102
	v_rcp_f32_e32 v103, v103
	v_rcp_f32_e32 v100, v100
	v_rcp_f32_e32 v101, v101
	v_exp_f32_e32 v98, v98
	v_exp_f32_e32 v99, v99
	v_exp_f32_e32 v104, v104
	v_exp_f32_e32 v105, v105
	v_pk_mul_f32 v[94:95], v[106:107], v[102:103] op_sel_hi:[0,1]
	v_pk_mul_f32 v[96:97], v[106:107], v[100:101] op_sel_hi:[0,1]
	v_pk_mul_f32 v[88:89], v[88:89], v[96:97]
	v_pk_mul_f32 v[86:87], v[86:87], v[94:95]
	v_pk_add_f32 v[94:95], v[104:105], 1.0 op_sel_hi:[1,0]
	v_pk_add_f32 v[96:97], v[98:99], 1.0 op_sel_hi:[1,0]
	v_rcp_f32_e32 v94, v94
	v_rcp_f32_e32 v96, v96
	v_rcp_f32_e32 v97, v97
	v_rcp_f32_e32 v95, v95
	v_pk_mul_f32 v[90:91], v[106:107], v[96:97] op_sel_hi:[0,1]
	v_pk_mul_f32 v[92:93], v[106:107], v[94:95] op_sel_hi:[0,1]
	v_pk_mul_f32 v[92:93], v[84:85], v[92:93]
	v_pk_mul_f32 v[84:85], v[82:83], v[90:91]
	v_cvt_pk_bf16_f32 v82, v86, v87
	v_ffbh_u32_e32 v86, v157
	v_cvt_pk_bf16_f32 v83, v88, v89
	v_min_u32_e32 v88, 32, v86
	v_lshlrev_b64 v[86:87], v88, v[156:157]
	v_min_u32_e32 v86, 1, v86
	v_or_b32_e32 v86, v87, v86
	v_cvt_f32_u32_e32 v86, v86
	v_sub_u32_e32 v87, 32, v88
	v_or_b32_e32 v90, 32, v146
	v_cvt_pk_bf16_f32 v84, v84, v85
	v_ldexp_f32 v86, v86, v87
	v_fmamk_f32 v86, v86, 0x30800000, v166
	v_rsq_f32_e32 v91, v86
	v_mad_i64_i32 v[86:87], s[20:21], v90, s54, v[122:123]
	v_lshl_add_u64 v[86:87], v[86:87], 0, v[110:111]
	v_cvt_pk_bf16_f32 v85, v92, v93
	global_store_dwordx4 v[86:87], v[82:85], off sc1
	v_mul_f32_e32 v90, v91, v91
	s_nop 0
	v_mul_f32_e32 v82, 0xbfb8aa3b, v91
	v_pk_mul_f32 v[84:85], v[80:81], v[82:83] op_sel_hi:[1,0]
	v_pk_mul_f32 v[86:87], v[78:79], v[82:83] op_sel_hi:[1,0]
	v_exp_f32_e32 v84, v84
	v_exp_f32_e32 v86, v86
	v_exp_f32_e32 v87, v87
	v_exp_f32_e32 v85, v85
	v_pk_mul_f32 v[88:89], v[76:77], v[82:83] op_sel_hi:[1,0]
	v_pk_mul_f32 v[82:83], v[74:75], v[82:83] op_sel_hi:[1,0]
	v_pk_add_f32 v[86:87], v[86:87], 1.0 op_sel_hi:[1,0]
	v_pk_add_f32 v[84:85], v[84:85], 1.0 op_sel_hi:[1,0]
	v_rcp_f32_e32 v86, v86
	v_rcp_f32_e32 v87, v87
	v_rcp_f32_e32 v84, v84
	v_rcp_f32_e32 v85, v85
	v_exp_f32_e32 v82, v82
	v_exp_f32_e32 v83, v83
	v_exp_f32_e32 v88, v88
	v_exp_f32_e32 v89, v89
	v_pk_mul_f32 v[78:79], v[90:91], v[86:87] op_sel_hi:[0,1]
	v_pk_mul_f32 v[80:81], v[90:91], v[84:85] op_sel_hi:[0,1]
	v_pk_mul_f32 v[72:73], v[72:73], v[80:81]
	v_pk_mul_f32 v[70:71], v[70:71], v[78:79]
	v_pk_add_f32 v[78:79], v[88:89], 1.0 op_sel_hi:[1,0]
	v_pk_add_f32 v[80:81], v[82:83], 1.0 op_sel_hi:[1,0]
	v_rcp_f32_e32 v78, v78
	v_rcp_f32_e32 v80, v80
	v_rcp_f32_e32 v81, v81
	v_rcp_f32_e32 v79, v79
	v_pk_mul_f32 v[74:75], v[90:91], v[80:81] op_sel_hi:[0,1]
	v_pk_mul_f32 v[76:77], v[90:91], v[78:79] op_sel_hi:[0,1]
	v_pk_mul_f32 v[76:77], v[68:69], v[76:77]
	v_pk_mul_f32 v[68:69], v[66:67], v[74:75]
	v_cvt_pk_bf16_f32 v66, v70, v71
	v_ffbh_u32_e32 v70, v155
	v_cvt_pk_bf16_f32 v67, v72, v73
	v_min_u32_e32 v72, 32, v70
	v_lshlrev_b64 v[70:71], v72, v[154:155]
	v_min_u32_e32 v70, 1, v70
	v_or_b32_e32 v70, v71, v70
	v_cvt_f32_u32_e32 v73, v70
	v_sub_u32_e32 v72, 32, v72
	v_or_b32_e32 v74, 48, v146
	v_mad_i64_i32 v[70:71], s[20:21], v74, s54, v[122:123]
	v_ldexp_f32 v72, v73, v72
	v_fmamk_f32 v72, v72, 0x30800000, v166
	v_rsq_f32_e32 v74, v72
	v_lshl_add_u64 v[70:71], v[70:71], 0, v[110:111]
	v_cvt_pk_bf16_f32 v68, v68, v69
	v_cvt_pk_bf16_f32 v69, v76, v77
	global_store_dwordx4 v[70:71], v[66:69], off sc1
	v_add_u32_e32 v75, 0x80, v146
	s_nop 0
	v_mul_f32_e32 v66, 0xbfb8aa3b, v74
	v_pk_mul_f32 v[68:69], v[64:65], v[66:67] op_sel_hi:[1,0]
	v_pk_mul_f32 v[70:71], v[62:63], v[66:67] op_sel_hi:[1,0]
	v_exp_f32_e32 v68, v68
	v_exp_f32_e32 v70, v70
	v_exp_f32_e32 v71, v71
	v_exp_f32_e32 v69, v69
	v_pk_mul_f32 v[72:73], v[60:61], v[66:67] op_sel_hi:[1,0]
	v_pk_mul_f32 v[66:67], v[58:59], v[66:67] op_sel_hi:[1,0]
	v_pk_add_f32 v[70:71], v[70:71], 1.0 op_sel_hi:[1,0]
	v_pk_add_f32 v[68:69], v[68:69], 1.0 op_sel_hi:[1,0]
	v_rcp_f32_e32 v70, v70
	v_rcp_f32_e32 v71, v71
	v_rcp_f32_e32 v68, v68
	v_rcp_f32_e32 v69, v69
	v_exp_f32_e32 v66, v66
	v_exp_f32_e32 v67, v67
	v_exp_f32_e32 v72, v72
	v_exp_f32_e32 v73, v73
	v_mul_f32_e32 v74, v74, v74
	v_pk_mul_f32 v[62:63], v[74:75], v[70:71] op_sel_hi:[0,1]
	v_pk_mul_f32 v[64:65], v[74:75], v[68:69] op_sel_hi:[0,1]
	v_pk_mul_f32 v[56:57], v[56:57], v[64:65]
	v_pk_mul_f32 v[54:55], v[54:55], v[62:63]
	v_pk_add_f32 v[62:63], v[72:73], 1.0 op_sel_hi:[1,0]
	v_pk_add_f32 v[64:65], v[66:67], 1.0 op_sel_hi:[1,0]
	v_rcp_f32_e32 v62, v62
	v_rcp_f32_e32 v64, v64
	v_rcp_f32_e32 v65, v65
	v_rcp_f32_e32 v63, v63
	v_pk_mul_f32 v[58:59], v[74:75], v[64:65] op_sel_hi:[0,1]
	v_pk_mul_f32 v[60:61], v[74:75], v[62:63] op_sel_hi:[0,1]
	v_pk_mul_f32 v[60:61], v[52:53], v[60:61]
	v_pk_mul_f32 v[52:53], v[50:51], v[58:59]
	v_cvt_pk_bf16_f32 v50, v54, v55
	v_ffbh_u32_e32 v54, v153
	v_cvt_pk_bf16_f32 v51, v56, v57
	v_min_u32_e32 v56, 32, v54
	v_lshlrev_b64 v[54:55], v56, v[152:153]
	v_min_u32_e32 v54, 1, v54
	v_or_b32_e32 v54, v55, v54
	v_cvt_f32_u32_e32 v54, v54
	v_sub_u32_e32 v55, 32, v56
	v_cvt_pk_bf16_f32 v52, v52, v53
	v_cvt_pk_bf16_f32 v53, v60, v61
	v_ldexp_f32 v54, v54, v55
	v_fmamk_f32 v54, v54, 0x30800000, v166
	v_rsq_f32_e32 v58, v54
	v_mad_i64_i32 v[54:55], s[20:21], v75, s54, v[122:123]
	v_lshl_add_u64 v[54:55], v[54:55], 0, v[110:111]
	global_store_dwordx4 v[54:55], v[50:53], off sc1
	s_nop 1
	v_mul_f32_e32 v50, 0xbfb8aa3b, v58
	v_pk_mul_f32 v[52:53], v[48:49], v[50:51] op_sel_hi:[1,0]
	v_pk_mul_f32 v[54:55], v[46:47], v[50:51] op_sel_hi:[1,0]
	v_exp_f32_e32 v52, v52
	v_exp_f32_e32 v54, v54
	v_exp_f32_e32 v55, v55
	v_exp_f32_e32 v53, v53
	v_pk_mul_f32 v[56:57], v[44:45], v[50:51] op_sel_hi:[1,0]
	v_pk_mul_f32 v[50:51], v[42:43], v[50:51] op_sel_hi:[1,0]
	v_pk_add_f32 v[54:55], v[54:55], 1.0 op_sel_hi:[1,0]
	v_pk_add_f32 v[52:53], v[52:53], 1.0 op_sel_hi:[1,0]
	v_rcp_f32_e32 v54, v54
	v_rcp_f32_e32 v55, v55
	v_rcp_f32_e32 v52, v52
	v_rcp_f32_e32 v53, v53
	v_exp_f32_e32 v50, v50
	v_exp_f32_e32 v51, v51
	v_exp_f32_e32 v56, v56
	v_exp_f32_e32 v57, v57
	v_mul_f32_e32 v58, v58, v58
	v_pk_mul_f32 v[46:47], v[58:59], v[54:55] op_sel_hi:[0,1]
	v_pk_mul_f32 v[48:49], v[58:59], v[52:53] op_sel_hi:[0,1]
	v_pk_mul_f32 v[40:41], v[40:41], v[48:49]
	v_pk_mul_f32 v[38:39], v[38:39], v[46:47]
	v_pk_add_f32 v[46:47], v[56:57], 1.0 op_sel_hi:[1,0]
	v_pk_add_f32 v[48:49], v[50:51], 1.0 op_sel_hi:[1,0]
	v_rcp_f32_e32 v46, v46
	v_rcp_f32_e32 v48, v48
	v_rcp_f32_e32 v49, v49
	v_rcp_f32_e32 v47, v47
	v_pk_mul_f32 v[42:43], v[58:59], v[48:49] op_sel_hi:[0,1]
	v_pk_mul_f32 v[44:45], v[58:59], v[46:47] op_sel_hi:[0,1]
	v_pk_mul_f32 v[44:45], v[36:37], v[44:45]
	v_pk_mul_f32 v[36:37], v[34:35], v[42:43]
	v_cvt_pk_bf16_f32 v34, v38, v39
	v_ffbh_u32_e32 v38, v151
	v_cvt_pk_bf16_f32 v35, v40, v41
	v_min_u32_e32 v40, 32, v38
	v_lshlrev_b64 v[38:39], v40, v[150:151]
	v_min_u32_e32 v38, 1, v38
	v_or_b32_e32 v38, v39, v38
	v_cvt_f32_u32_e32 v38, v38
	v_sub_u32_e32 v39, 32, v40
	v_add_u32_e32 v42, 0x90, v146
	v_cvt_pk_bf16_f32 v36, v36, v37
	v_ldexp_f32 v38, v38, v39
	v_fmamk_f32 v38, v38, 0x30800000, v166
	v_rsq_f32_e32 v43, v38
	v_mad_i64_i32 v[38:39], s[20:21], v42, s54, v[122:123]
	v_lshl_add_u64 v[38:39], v[38:39], 0, v[110:111]
	v_cvt_pk_bf16_f32 v37, v44, v45
	global_store_dwordx4 v[38:39], v[34:37], off sc1
	v_mul_f32_e32 v42, v43, v43
	s_nop 0
	v_mul_f32_e32 v34, 0xbfb8aa3b, v43
	v_pk_mul_f32 v[36:37], v[32:33], v[34:35] op_sel_hi:[1,0]
	v_pk_mul_f32 v[38:39], v[30:31], v[34:35] op_sel_hi:[1,0]
	v_exp_f32_e32 v36, v36
	v_exp_f32_e32 v38, v38
	v_exp_f32_e32 v39, v39
	v_exp_f32_e32 v37, v37
	v_pk_mul_f32 v[40:41], v[28:29], v[34:35] op_sel_hi:[1,0]
	v_pk_mul_f32 v[34:35], v[26:27], v[34:35] op_sel_hi:[1,0]
	v_pk_add_f32 v[38:39], v[38:39], 1.0 op_sel_hi:[1,0]
	v_pk_add_f32 v[36:37], v[36:37], 1.0 op_sel_hi:[1,0]
	v_rcp_f32_e32 v38, v38
	v_rcp_f32_e32 v39, v39
	v_rcp_f32_e32 v36, v36
	v_rcp_f32_e32 v37, v37
	v_exp_f32_e32 v34, v34
	v_exp_f32_e32 v35, v35
	v_exp_f32_e32 v40, v40
	v_exp_f32_e32 v41, v41
	v_pk_mul_f32 v[30:31], v[42:43], v[38:39] op_sel_hi:[0,1]
	v_pk_mul_f32 v[32:33], v[42:43], v[36:37] op_sel_hi:[0,1]
	v_pk_mul_f32 v[24:25], v[24:25], v[32:33]
	v_pk_mul_f32 v[22:23], v[22:23], v[30:31]
	v_pk_add_f32 v[30:31], v[40:41], 1.0 op_sel_hi:[1,0]
	v_pk_add_f32 v[32:33], v[34:35], 1.0 op_sel_hi:[1,0]
	v_rcp_f32_e32 v30, v30
	v_rcp_f32_e32 v32, v32
	v_rcp_f32_e32 v33, v33
	v_rcp_f32_e32 v31, v31
	v_pk_mul_f32 v[26:27], v[42:43], v[32:33] op_sel_hi:[0,1]
	v_pk_mul_f32 v[28:29], v[42:43], v[30:31] op_sel_hi:[0,1]
	v_pk_mul_f32 v[28:29], v[20:21], v[28:29]
	v_pk_mul_f32 v[20:21], v[18:19], v[26:27]
	v_cvt_pk_bf16_f32 v18, v22, v23
	v_ffbh_u32_e32 v22, v149
	v_cvt_pk_bf16_f32 v19, v24, v25
	v_min_u32_e32 v24, 32, v22
	v_lshlrev_b64 v[22:23], v24, v[148:149]
	v_min_u32_e32 v22, 1, v22
	v_or_b32_e32 v22, v23, v22
	v_cvt_f32_u32_e32 v22, v22
	v_sub_u32_e32 v23, 32, v24
	v_add_u32_e32 v26, 0xa0, v146
	v_cvt_pk_bf16_f32 v20, v20, v21
	v_ldexp_f32 v22, v22, v23
	v_fmamk_f32 v22, v22, 0x30800000, v166
	v_rsq_f32_e32 v27, v22
	v_mad_i64_i32 v[22:23], s[20:21], v26, s54, v[122:123]
	v_lshl_add_u64 v[22:23], v[22:23], 0, v[110:111]
	v_cvt_pk_bf16_f32 v21, v28, v29
	global_store_dwordx4 v[22:23], v[18:21], off sc1
	v_mul_f32_e32 v26, v27, v27
	s_nop 0
	v_mul_f32_e32 v18, 0xbfb8aa3b, v27
	v_pk_mul_f32 v[20:21], v[16:17], v[18:19] op_sel_hi:[1,0]
	v_pk_mul_f32 v[22:23], v[14:15], v[18:19] op_sel_hi:[1,0]
	v_exp_f32_e32 v20, v20
	v_exp_f32_e32 v22, v22
	v_exp_f32_e32 v23, v23
	v_exp_f32_e32 v21, v21
	v_pk_mul_f32 v[24:25], v[12:13], v[18:19] op_sel_hi:[1,0]
	v_pk_mul_f32 v[18:19], v[10:11], v[18:19] op_sel_hi:[1,0]
	v_pk_add_f32 v[22:23], v[22:23], 1.0 op_sel_hi:[1,0]
	v_pk_add_f32 v[20:21], v[20:21], 1.0 op_sel_hi:[1,0]
	v_rcp_f32_e32 v22, v22
	v_rcp_f32_e32 v23, v23
	v_rcp_f32_e32 v20, v20
	v_rcp_f32_e32 v21, v21
	v_exp_f32_e32 v18, v18
	v_exp_f32_e32 v19, v19
	v_exp_f32_e32 v24, v24
	v_exp_f32_e32 v25, v25
	v_pk_mul_f32 v[14:15], v[26:27], v[22:23] op_sel_hi:[0,1]
	v_pk_mul_f32 v[16:17], v[26:27], v[20:21] op_sel_hi:[0,1]
	v_pk_mul_f32 v[8:9], v[8:9], v[16:17]
	v_pk_mul_f32 v[6:7], v[6:7], v[14:15]
	v_pk_add_f32 v[14:15], v[24:25], 1.0 op_sel_hi:[1,0]
	v_pk_add_f32 v[16:17], v[18:19], 1.0 op_sel_hi:[1,0]
	v_rcp_f32_e32 v14, v14
	v_rcp_f32_e32 v16, v16
	v_rcp_f32_e32 v17, v17
	v_rcp_f32_e32 v15, v15
	v_pk_mul_f32 v[10:11], v[26:27], v[16:17] op_sel_hi:[0,1]
	v_pk_mul_f32 v[12:13], v[26:27], v[14:15] op_sel_hi:[0,1]
	v_pk_mul_f32 v[12:13], v[4:5], v[12:13]
	v_pk_mul_f32 v[4:5], v[2:3], v[10:11]
	v_add_u32_e32 v10, 0xb0, v146
	v_cvt_pk_bf16_f32 v2, v6, v7
	v_mad_i64_i32 v[6:7], s[20:21], v10, s54, v[122:123]
	v_lshl_add_u64 v[6:7], v[6:7], 0, v[110:111]
	v_cvt_pk_bf16_f32 v3, v8, v9
	v_cvt_pk_bf16_f32 v4, v4, v5
	v_cvt_pk_bf16_f32 v5, v12, v13
	global_store_dwordx4 v[6:7], v[2:5], off sc1
	s_cbranch_vccnz .LBB0_1250
	s_andn2_b64 vcc, exec, s[0:1]
	s_cbranch_vccnz .LBB0_1249
	s_barrier
	s_branch .LBB0_1249

.LBB0_1268:
	s_ashr_i32 s7, s0, 31
	s_lshr_b32 s7, s7, 28
	s_add_i32 s7, s0, s7
	s_ashr_i32 s7, s7, 4
	s_lshl_b32 s8, s7, 6
	s_lshl_b32 s9, s7, 10
	s_mul_i32 s7, s7, 0xffd40000
	v_or_b32_e32 v42, s8, v6
	s_sub_i32 s10, s5, s9
	v_add_u32_e32 v44, s7, v8
	v_or_b32_e32 v46, 4, v42
	v_or_b32_e32 v48, 8, v42
	v_or_b32_e32 v50, 12, v42
	v_or_b32_e32 v52, 16, v42
	v_or_b32_e32 v54, 20, v42
	v_or_b32_e32 v56, 24, v42
	v_or_b32_e32 v58, 28, v42
	v_or_b32_e32 v60, 32, v42
	v_or_b32_e32 v62, 36, v42
	v_or_b32_e32 v64, 40, v42
	v_or_b32_e32 v66, 44, v42
	v_or_b32_e32 v68, 48, v42
	v_or_b32_e32 v70, 52, v42
	s_ashr_i32 s9, s8, 31
	s_ashr_i32 s11, s10, 31
	v_ashrrev_i32_e32 v43, 31, v42
	v_or_b32_e32 v72, 56, v42
	v_or_b32_e32 v74, 60, v42
	v_add_u32_e32 v78, 0x5800, v44
	v_add_u32_e32 v80, 0xb000, v44
	v_add_u32_e32 v82, 0x10800, v44
	v_add_u32_e32 v84, 0x16000, v44
	v_add_u32_e32 v86, 0x1b800, v44
	v_add_u32_e32 v88, 0x21000, v44
	v_add_u32_e32 v90, 0x26800, v44
	v_ashrrev_i32_e32 v47, 31, v46
	v_ashrrev_i32_e32 v49, 31, v48
	v_ashrrev_i32_e32 v51, 31, v50
	v_ashrrev_i32_e32 v53, 31, v52
	v_ashrrev_i32_e32 v55, 31, v54
	v_ashrrev_i32_e32 v57, 31, v56
	v_ashrrev_i32_e32 v59, 31, v58
	v_ashrrev_i32_e32 v61, 31, v60
	v_ashrrev_i32_e32 v63, 31, v62
	v_ashrrev_i32_e32 v65, 31, v64
	v_ashrrev_i32_e32 v67, 31, v66
	v_ashrrev_i32_e32 v69, 31, v68
	v_ashrrev_i32_e32 v71, 31, v70
	v_lshl_add_u64 v[76:77], s[8:9], 1, v[4:5]
	v_lshl_add_u64 v[92:93], s[10:11], 2, v[2:3]
	v_lshlrev_b64 v[42:43], 12, v[42:43]
	v_ashrrev_i32_e32 v73, 31, v72
	v_ashrrev_i32_e32 v75, 31, v74
	v_ashrrev_i32_e32 v79, 31, v78
	v_ashrrev_i32_e32 v81, 31, v80
	v_ashrrev_i32_e32 v83, 31, v82
	v_ashrrev_i32_e32 v85, 31, v84
	v_ashrrev_i32_e32 v87, 31, v86
	v_ashrrev_i32_e32 v89, 31, v88
	v_ashrrev_i32_e32 v91, 31, v90
	v_lshlrev_b64 v[46:47], 12, v[46:47]
	v_lshlrev_b64 v[48:49], 12, v[48:49]
	v_lshlrev_b64 v[50:51], 12, v[50:51]
	v_lshlrev_b64 v[52:53], 12, v[52:53]
	v_lshlrev_b64 v[54:55], 12, v[54:55]
	v_lshlrev_b64 v[56:57], 12, v[56:57]
	v_lshlrev_b64 v[58:59], 12, v[58:59]
	v_lshlrev_b64 v[60:61], 12, v[60:61]
	v_lshlrev_b64 v[62:63], 12, v[62:63]
	v_lshlrev_b64 v[64:65], 12, v[64:65]
	v_lshlrev_b64 v[66:67], 12, v[66:67]
	v_lshlrev_b64 v[68:69], 12, v[68:69]
	v_lshlrev_b64 v[70:71], 12, v[70:71]
	v_ashrrev_i32_e32 v45, 31, v44
	v_lshl_add_u64 v[42:43], v[92:93], 0, v[42:43]
	v_lshlrev_b64 v[72:73], 12, v[72:73]
	v_lshlrev_b64 v[74:75], 12, v[74:75]
	v_lshl_add_u64 v[108:109], v[78:79], 1, v[76:77]
	v_lshl_add_u64 v[110:111], v[80:81], 1, v[76:77]
	v_lshl_add_u64 v[112:113], v[82:83], 1, v[76:77]
	v_lshl_add_u64 v[114:115], v[84:85], 1, v[76:77]
	v_lshl_add_u64 v[116:117], v[86:87], 1, v[76:77]
	v_lshl_add_u64 v[118:119], v[88:89], 1, v[76:77]
	v_lshl_add_u64 v[120:121], v[90:91], 1, v[76:77]
	v_lshl_add_u64 v[78:79], v[92:93], 0, v[46:47]
	v_lshl_add_u64 v[80:81], v[92:93], 0, v[48:49]
	v_lshl_add_u64 v[82:83], v[92:93], 0, v[50:51]
	v_lshl_add_u64 v[84:85], v[92:93], 0, v[52:53]
	v_lshl_add_u64 v[86:87], v[92:93], 0, v[54:55]
	v_lshl_add_u64 v[88:89], v[92:93], 0, v[56:57]
	v_lshl_add_u64 v[90:91], v[92:93], 0, v[58:59]
	v_lshl_add_u64 v[94:95], v[92:93], 0, v[60:61]
	v_lshl_add_u64 v[96:97], v[92:93], 0, v[62:63]
	v_lshl_add_u64 v[98:99], v[92:93], 0, v[64:65]
	v_lshl_add_u64 v[100:101], v[92:93], 0, v[66:67]
	v_lshl_add_u64 v[102:103], v[92:93], 0, v[68:69]
	v_lshl_add_u64 v[104:105], v[92:93], 0, v[70:71]
	v_lshl_add_u64 v[106:107], v[44:45], 1, v[76:77]
	global_load_dwordx4 v[42:45], v[42:43], off nt
	v_lshl_add_u64 v[122:123], v[92:93], 0, v[72:73]
	v_lshl_add_u64 v[124:125], v[92:93], 0, v[74:75]
	global_load_dwordx4 v[46:49], v[78:79], off nt
	global_load_dwordx4 v[50:53], v[80:81], off nt
	global_load_dwordx4 v[54:57], v[82:83], off nt
	global_load_dwordx4 v[58:61], v[84:85], off nt
	global_load_dwordx4 v[62:65], v[86:87], off nt
	global_load_dwordx4 v[66:69], v[88:89], off nt
	global_load_dwordx4 v[70:73], v[90:91], off nt
	global_load_dwordx4 v[74:77], v[94:95], off nt
	global_load_dwordx4 v[78:81], v[96:97], off nt
	global_load_dwordx4 v[82:85], v[98:99], off nt
	s_nop 0
	global_load_dwordx4 v[86:89], v[100:101], off nt
	global_load_dwordx4 v[90:93], v[102:103], off nt
	global_load_dwordx4 v[94:97], v[104:105], off nt
	s_nop 0
	global_load_dwordx4 v[98:101], v[122:123], off nt
	global_load_dwordx4 v[102:105], v[124:125], off nt
	s_waitcnt vmcnt(15)
	ds_write2_b32 v9, v42, v43 offset1:1
	ds_write2_b32 v9, v44, v45 offset0:2 offset1:3
	s_waitcnt vmcnt(14)
	ds_write2_b32 v10, v46, v47 offset1:1
	ds_write2_b32 v11, v48, v49 offset1:1
	s_waitcnt vmcnt(13)
	ds_write2_b32 v12, v50, v51 offset1:1
	ds_write2_b32 v13, v52, v53 offset1:1
	s_waitcnt vmcnt(12)
	ds_write2_b32 v14, v54, v55 offset1:1
	ds_write2_b32 v15, v56, v57 offset1:1
	s_waitcnt vmcnt(11)
	ds_write2_b32 v16, v58, v59 offset1:1
	ds_write2_b32 v17, v60, v61 offset1:1
	s_waitcnt vmcnt(10)
	ds_write2_b32 v18, v62, v63 offset1:1
	ds_write2_b32 v19, v64, v65 offset1:1
	s_waitcnt vmcnt(9)
	ds_write2_b32 v20, v66, v67 offset1:1
	ds_write2_b32 v21, v68, v69 offset1:1
	s_waitcnt vmcnt(8)
	ds_write2_b32 v22, v70, v71 offset1:1
	ds_write2_b32 v23, v72, v73 offset1:1
	s_waitcnt vmcnt(7)
	ds_write2_b32 v24, v74, v75 offset1:1
	ds_write2_b32 v25, v76, v77 offset1:1
	s_waitcnt vmcnt(6)
	ds_write2_b32 v26, v78, v79 offset1:1
	ds_write2_b32 v27, v80, v81 offset1:1
	s_waitcnt vmcnt(5)
	ds_write2_b32 v28, v82, v83 offset1:1
	ds_write2_b32 v29, v84, v85 offset1:1
	s_waitcnt vmcnt(4)
	ds_write2_b32 v30, v86, v87 offset1:1
	ds_write2_b32 v31, v88, v89 offset1:1
	s_waitcnt vmcnt(3)
	ds_write2_b32 v32, v90, v91 offset1:1
	ds_write2_b32 v33, v92, v93 offset1:1
	s_waitcnt vmcnt(2)
	ds_write2_b32 v34, v94, v95 offset1:1
	ds_write2_b32 v35, v96, v97 offset1:1
	s_waitcnt vmcnt(1)
	ds_write2_b32 v36, v98, v99 offset1:1
	ds_write2_b32 v37, v100, v101 offset1:1
	s_waitcnt vmcnt(0)
	ds_write2_b32 v38, v102, v103 offset1:1
	ds_write2_b32 v39, v104, v105 offset1:1
	s_waitcnt lgkmcnt(0)
	ds_read2_b32 v[46:47], v7 offset0:65 offset1:73
	ds_read2_b32 v[48:49], v7 offset1:8
	ds_read2_b32 v[50:51], v7 offset0:130 offset1:138
	ds_read2_b32 v[52:53], v7 offset0:195 offset1:203
	ds_read2_b32 v[54:55], v40 offset0:4 offset1:12
	ds_read2_b32 v[56:57], v40 offset0:69 offset1:77
	ds_read2_b32 v[58:59], v40 offset0:134 offset1:142
	ds_read2_b32 v[60:61], v40 offset0:199 offset1:207
	ds_read2_b32 v[62:63], v7 offset0:81 offset1:89
	ds_read2_b32 v[64:65], v7 offset0:16 offset1:24
	ds_read2_b32 v[66:67], v7 offset0:146 offset1:154
	ds_read2_b32 v[68:69], v7 offset0:211 offset1:219
	ds_read2_b32 v[70:71], v40 offset0:20 offset1:28
	ds_read2_b32 v[72:73], v40 offset0:85 offset1:93
	ds_read2_b32 v[74:75], v40 offset0:150 offset1:158
	ds_read2_b32 v[76:77], v40 offset0:215 offset1:223
	ds_read2_b32 v[78:79], v7 offset0:32 offset1:40
	ds_read2_b32 v[80:81], v7 offset0:97 offset1:105
	ds_read2_b32 v[82:83], v7 offset0:162 offset1:170
	ds_read2_b32 v[84:85], v7 offset0:227 offset1:235
	ds_read2_b32 v[86:87], v40 offset0:36 offset1:44
	ds_read2_b32 v[88:89], v40 offset0:101 offset1:109
	ds_read2_b32 v[90:91], v40 offset0:166 offset1:174
	ds_read2_b32 v[92:93], v40 offset0:231 offset1:239
	ds_read2_b32 v[94:95], v7 offset0:48 offset1:56
	ds_read2_b32 v[96:97], v7 offset0:113 offset1:121
	ds_read2_b32 v[98:99], v7 offset0:178 offset1:186
	ds_read2_b32 v[100:101], v7 offset0:243 offset1:251
	ds_read2_b32 v[102:103], v40 offset0:52 offset1:60
	ds_read2_b32 v[104:105], v40 offset0:117 offset1:125
	ds_read2_b32 v[122:123], v40 offset0:182 offset1:190
	ds_read2_b32 v[124:125], v40 offset0:247 offset1:255
	s_waitcnt lgkmcnt(14)
	v_cvt_pk_bf16_f32 v42, v48, v46
	v_cvt_pk_bf16_f32 v43, v50, v52
	v_cvt_pk_bf16_f32 v44, v54, v56
	v_cvt_pk_bf16_f32 v45, v58, v60
	v_cvt_pk_bf16_f32 v46, v49, v47
	v_cvt_pk_bf16_f32 v47, v51, v53
	v_cvt_pk_bf16_f32 v48, v55, v57
	v_cvt_pk_bf16_f32 v49, v59, v61
	v_cvt_pk_bf16_f32 v50, v64, v62
	v_cvt_pk_bf16_f32 v51, v66, v68
	v_cvt_pk_bf16_f32 v52, v70, v72
	v_cvt_pk_bf16_f32 v53, v74, v76
	v_cvt_pk_bf16_f32 v54, v65, v63
	v_cvt_pk_bf16_f32 v55, v67, v69
	v_cvt_pk_bf16_f32 v56, v71, v73
	v_cvt_pk_bf16_f32 v57, v75, v77
	v_cvt_pk_bf16_f32 v58, v78, v80
	s_waitcnt lgkmcnt(12)
	v_cvt_pk_bf16_f32 v59, v82, v84
	s_waitcnt lgkmcnt(10)
	v_cvt_pk_bf16_f32 v60, v86, v88
	s_waitcnt lgkmcnt(8)
	v_cvt_pk_bf16_f32 v61, v90, v92
	v_cvt_pk_bf16_f32 v62, v79, v81
	v_cvt_pk_bf16_f32 v63, v83, v85
	v_cvt_pk_bf16_f32 v64, v87, v89
	v_cvt_pk_bf16_f32 v65, v91, v93
	s_waitcnt lgkmcnt(6)
	v_cvt_pk_bf16_f32 v66, v94, v96
	s_waitcnt lgkmcnt(4)
	v_cvt_pk_bf16_f32 v67, v98, v100
	s_waitcnt lgkmcnt(2)
	v_cvt_pk_bf16_f32 v68, v102, v104
	s_waitcnt lgkmcnt(0)
	v_cvt_pk_bf16_f32 v69, v122, v124
	v_cvt_pk_bf16_f32 v70, v95, v97
	v_cvt_pk_bf16_f32 v71, v99, v101
	v_cvt_pk_bf16_f32 v72, v103, v105
	v_cvt_pk_bf16_f32 v73, v123, v125
	global_store_dwordx4 v[106:107], v[42:45], off sc1
	global_store_dwordx4 v[108:109], v[46:49], off sc1
	global_store_dwordx4 v[110:111], v[50:53], off sc1
	global_store_dwordx4 v[112:113], v[54:57], off sc1
	global_store_dwordx4 v[114:115], v[58:61], off sc1
	global_store_dwordx4 v[116:117], v[62:65], off sc1
	global_store_dwordx4 v[118:119], v[66:69], off sc1
	global_store_dwordx4 v[120:121], v[70:73], off sc1
	s_waitcnt lgkmcnt(0)
	s_add_i32 s0, s0, s1
	s_add_i32 s5, s5, s6
	s_cmpk_lt_i32 s0, 0x2c0
	v_add_u32_e32 v8, s4, v8
	s_cbranch_scc1 .LBB0_1268

.LBB0_1344:
	v_lshl_add_u32 v204, s21, 8, v214
	v_lshl_or_b32 v202, s20, 8, v216
	v_ashrrev_i32_e32 v203, 31, v202
	v_ashrrev_i32_e32 v205, 31, v204
	v_lshl_add_u64 v[106:107], v[202:203], 1, s[44:45]
	v_lshlrev_b64 v[108:109], 11, v[204:205]
	v_or_b32_e32 v212, 16, v204
	v_lshl_add_u64 v[108:109], v[106:107], 0, v[108:109]
	v_ashrrev_i32_e32 v213, 31, v212
	global_load_dwordx4 v[228:231], v[108:109], off
	global_load_dwordx4 v[232:235], v[108:109], off offset:256
	v_lshlrev_b64 v[108:109], 11, v[212:213]
	v_or_b32_e32 v210, 32, v204
	v_lshl_add_u64 v[108:109], v[106:107], 0, v[108:109]
	v_ashrrev_i32_e32 v211, 31, v210
	global_load_dwordx4 v[182:185], v[108:109], off
	global_load_dwordx4 v[178:181], v[108:109], off offset:256
	v_lshlrev_b64 v[108:109], 11, v[210:211]
	v_or_b32_e32 v208, 48, v204
	v_lshl_add_u64 v[108:109], v[106:107], 0, v[108:109]
	v_ashrrev_i32_e32 v209, 31, v208
	global_load_dwordx4 v[174:177], v[108:109], off
	global_load_dwordx4 v[170:173], v[108:109], off offset:256
	v_lshlrev_b64 v[108:109], 11, v[208:209]
	v_lshl_add_u64 v[108:109], v[106:107], 0, v[108:109]
	global_load_dwordx4 v[166:169], v[108:109], off
	global_load_dwordx4 v[162:165], v[108:109], off offset:256
	v_add_u32_e32 v206, 0x80, v204
	v_add_u32_e32 v108, 0x90, v204
	v_add_u32_e32 v110, 0xa0, v204
	v_add_u32_e32 v112, 0xb0, v204
	v_ashrrev_i32_e32 v207, 31, v206
	v_ashrrev_i32_e32 v109, 31, v108
	v_ashrrev_i32_e32 v111, 31, v110
	v_ashrrev_i32_e32 v113, 31, v112
	v_lshlrev_b64 v[126:127], 11, v[206:207]
	v_lshlrev_b64 v[108:109], 11, v[108:109]
	v_lshlrev_b64 v[110:111], 11, v[110:111]
	v_lshlrev_b64 v[112:113], 11, v[112:113]
	v_lshl_add_u64 v[126:127], v[106:107], 0, v[126:127]
	v_lshl_add_u64 v[108:109], v[106:107], 0, v[108:109]
	v_lshl_add_u64 v[110:111], v[106:107], 0, v[110:111]
	v_lshl_add_u64 v[106:107], v[106:107], 0, v[112:113]
	global_load_dwordx4 v[158:161], v[126:127], off
	global_load_dwordx4 v[154:157], v[126:127], off offset:256
	global_load_dwordx4 v[150:153], v[108:109], off
	global_load_dwordx4 v[146:149], v[108:109], off offset:256
	global_load_dwordx4 v[138:141], v[110:111], off
	s_nop 0
	global_load_dwordx4 v[126:129], v[110:111], off offset:256
	s_nop 0
	global_load_dwordx4 v[110:113], v[106:107], off
	s_nop 0
	global_load_dwordx4 v[106:109], v[106:107], off offset:256
	s_waitcnt vmcnt(0)
	s_nop 0
	v_lshlrev_b32_e32 v220, 16, v228
	v_and_b32_e32 v221, 0xffff0000, v228
	v_lshlrev_b32_e32 v228, 16, v229
	v_and_b32_e32 v229, 0xffff0000, v229
	v_lshlrev_b32_e32 v236, 16, v230
	v_and_b32_e32 v237, 0xffff0000, v230
	v_lshlrev_b32_e32 v238, 16, v232
	v_and_b32_e32 v239, 0xffff0000, v232
	v_lshlrev_b32_e32 v232, 16, v233
	v_and_b32_e32 v233, 0xffff0000, v233
	v_lshlrev_b32_e32 v240, 16, v234
	v_and_b32_e32 v241, 0xffff0000, v234
	v_pk_add_f32 v[144:145], v[144:145], v[228:229]
	v_pk_add_f32 v[142:143], v[142:143], v[220:221]
	v_lshlrev_b32_e32 v230, 16, v231
	v_and_b32_e32 v231, 0xffff0000, v231
	v_lshlrev_b32_e32 v234, 16, v235
	v_and_b32_e32 v235, 0xffff0000, v235
	v_pk_add_f32 v[134:135], v[134:135], v[236:237]
	v_pk_add_f32 v[132:133], v[132:133], v[232:233]
	v_pk_add_f32 v[130:131], v[130:131], v[238:239]
	v_pk_add_f32 v[228:229], v[122:123], v[240:241]
	v_mul_f32_e32 v122, v143, v143
	v_mul_f32_e32 v123, v144, v144
	v_pk_add_f32 v[136:137], v[136:137], v[230:231]
	v_pk_add_f32 v[230:231], v[124:125], v[234:235]
	v_mul_f32_e32 v124, v134, v134
	v_mul_f32_e32 v220, v131, v131
	v_mul_f32_e32 v221, v132, v132
	v_fmac_f32_e32 v122, v142, v142
	v_fmac_f32_e32 v123, v145, v145
	v_mul_f32_e32 v227, v228, v228
	v_fmac_f32_e32 v124, v135, v135
	v_fmac_f32_e32 v220, v130, v130
	v_fmac_f32_e32 v221, v133, v133
	v_add_f32_e32 v122, v122, v123
	v_mul_f32_e32 v125, v136, v136
	v_add_f32_e32 v123, v220, v221
	v_add_f32_e32 v122, v124, v122
	v_fmac_f32_e32 v227, v229, v229
	v_mul_f32_e32 v124, v230, v230
	v_fmac_f32_e32 v125, v137, v137
	v_add_f32_e32 v123, v227, v123
	v_fmac_f32_e32 v124, v231, v231
	v_add_f32_e32 v122, v125, v122
	v_add_f32_e32 v123, v124, v123
	v_add_f32_e32 v220, v122, v123
	ds_bpermute_b32 v221, v225, v220
	v_lshlrev_b64 v[122:123], 12, v[204:205]
	v_lshl_add_u64 v[122:123], s[26:27], 0, v[122:123]
	v_lshl_add_u64 v[124:125], v[202:203], 2, v[122:123]
	s_waitcnt lgkmcnt(0)
	v_add_f32_e32 v122, v220, v221
	ds_bpermute_b32 v123, v226, v122
	global_store_dwordx4 v[124:125], v[142:145], off sc1
	global_store_dwordx4 v[124:125], v[134:137], off offset:16 sc1
	global_store_dwordx4 v[124:125], v[130:133], off offset:512 sc1
	global_store_dwordx4 v[124:125], v[228:231], off offset:528 sc1
	s_and_saveexec_b64 s[20:21], s[6:7]
	s_cbranch_execz .LBB0_1346
	s_waitcnt lgkmcnt(0)
	v_add_f32_e32 v122, v122, v123
	v_fma_f32 v122, v122, s59, 0.5
	v_trunc_f32_e32 v122, v122
	v_mul_f32_e32 v123, 0x2f800000, v122
	v_floor_f32_e32 v123, v123
	v_fmac_f32_e32 v122, 0xcf800000, v123
	v_cvt_u32_f32_e32 v122, v122
	v_cvt_u32_f32_e32 v123, v123
	v_lshl_add_u64 v[124:125], v[204:205], 3, s[34:35]
	global_atomic_add_x2 v[124:125], v[122:123], off
.LBB0_1346:
	s_or_b64 exec, exec, s[20:21]
	v_lshlrev_b32_e32 v122, 16, v182
	s_waitcnt lgkmcnt(0)
	v_and_b32_e32 v123, 0xffff0000, v182
	v_lshlrev_b32_e32 v124, 16, v183
	v_and_b32_e32 v125, 0xffff0000, v183
	v_pk_add_f32 v[120:121], v[120:121], v[124:125]
	v_pk_add_f32 v[118:119], v[118:119], v[122:123]
	v_lshlrev_b32_e32 v130, 16, v184
	v_and_b32_e32 v131, 0xffff0000, v184
	v_mul_f32_e32 v122, v119, v119
	v_mul_f32_e32 v123, v120, v120
	v_pk_add_f32 v[114:115], v[114:115], v[130:131]
	v_fmac_f32_e32 v122, v118, v118
	v_fmac_f32_e32 v123, v121, v121
	v_lshlrev_b32_e32 v132, 16, v185
	v_and_b32_e32 v133, 0xffff0000, v185
	v_add_f32_e32 v122, v122, v123
	v_mul_f32_e32 v123, v114, v114
	v_pk_add_f32 v[116:117], v[116:117], v[132:133]
	v_fmac_f32_e32 v123, v115, v115
	v_add_f32_e32 v122, v123, v122
	v_mul_f32_e32 v123, v116, v116
	v_fmac_f32_e32 v123, v117, v117
	v_add_f32_e32 v134, v123, v122
	v_lshlrev_b32_e32 v122, 16, v178
	v_and_b32_e32 v123, 0xffff0000, v178
	v_lshlrev_b32_e32 v124, 16, v179
	v_and_b32_e32 v125, 0xffff0000, v179
	v_lshlrev_b32_e32 v130, 16, v180
	v_and_b32_e32 v131, 0xffff0000, v180
	v_pk_add_f32 v[104:105], v[104:105], v[124:125]
	v_pk_add_f32 v[102:103], v[102:103], v[122:123]
	v_pk_add_f32 v[122:123], v[98:99], v[130:131]
	v_mul_f32_e32 v98, v103, v103
	v_mul_f32_e32 v99, v104, v104
	v_fmac_f32_e32 v98, v102, v102
	v_fmac_f32_e32 v99, v105, v105
	v_lshlrev_b32_e32 v132, 16, v181
	v_and_b32_e32 v133, 0xffff0000, v181
	v_add_f32_e32 v98, v98, v99
	v_mul_f32_e32 v99, v122, v122
	v_pk_add_f32 v[124:125], v[100:101], v[132:133]
	v_fmac_f32_e32 v99, v123, v123
	v_add_f32_e32 v98, v99, v98
	v_mul_f32_e32 v99, v124, v124
	v_fmac_f32_e32 v99, v125, v125
	v_add_f32_e32 v98, v99, v98
	v_add_f32_e32 v130, v134, v98
	ds_bpermute_b32 v131, v225, v130
	v_lshlrev_b64 v[98:99], 12, v[212:213]
	v_lshl_add_u64 v[98:99], s[26:27], 0, v[98:99]
	v_lshl_add_u64 v[100:101], v[202:203], 2, v[98:99]
	global_store_dwordx4 v[100:101], v[118:121], off sc1
	global_store_dwordx4 v[100:101], v[114:117], off offset:16 sc1
	global_store_dwordx4 v[100:101], v[102:105], off offset:512 sc1
	global_store_dwordx4 v[100:101], v[122:125], off offset:528 sc1
	s_waitcnt lgkmcnt(0)
	v_add_f32_e32 v98, v130, v131
	ds_bpermute_b32 v99, v226, v98
	s_and_saveexec_b64 s[20:21], s[6:7]
	s_cbranch_execz .LBB0_1348
	s_waitcnt lgkmcnt(0)
	v_add_f32_e32 v98, v98, v99
	v_fma_f32 v98, v98, s59, 0.5
	v_trunc_f32_e32 v98, v98
	v_mul_f32_e32 v99, 0x2f800000, v98
	v_floor_f32_e32 v99, v99
	v_fmac_f32_e32 v98, 0xcf800000, v99
	v_cvt_u32_f32_e32 v98, v98
	v_cvt_u32_f32_e32 v99, v99
	v_lshl_add_u64 v[100:101], v[212:213], 3, s[34:35]
	global_atomic_add_x2 v[100:101], v[98:99], off
.LBB0_1348:
	s_or_b64 exec, exec, s[20:21]
	v_lshlrev_b32_e32 v98, 16, v174
	s_waitcnt lgkmcnt(0)
	v_and_b32_e32 v99, 0xffff0000, v174
	v_lshlrev_b32_e32 v100, 16, v175
	v_and_b32_e32 v101, 0xffff0000, v175
	v_pk_add_f32 v[96:97], v[96:97], v[100:101]
	v_pk_add_f32 v[94:95], v[94:95], v[98:99]
	v_lshlrev_b32_e32 v102, 16, v176
	v_and_b32_e32 v103, 0xffff0000, v176
	v_mul_f32_e32 v98, v95, v95
	v_mul_f32_e32 v99, v96, v96
	v_pk_add_f32 v[90:91], v[90:91], v[102:103]
	v_fmac_f32_e32 v98, v94, v94
	v_fmac_f32_e32 v99, v97, v97
	v_lshlrev_b32_e32 v104, 16, v177
	v_and_b32_e32 v105, 0xffff0000, v177
	v_add_f32_e32 v98, v98, v99
	v_mul_f32_e32 v99, v90, v90
	v_pk_add_f32 v[92:93], v[92:93], v[104:105]
	v_fmac_f32_e32 v99, v91, v91
	v_add_f32_e32 v98, v99, v98
	v_mul_f32_e32 v99, v92, v92
	v_fmac_f32_e32 v99, v93, v93
	v_add_f32_e32 v114, v99, v98
	v_lshlrev_b32_e32 v98, 16, v170
	v_and_b32_e32 v99, 0xffff0000, v170
	v_lshlrev_b32_e32 v100, 16, v171
	v_and_b32_e32 v101, 0xffff0000, v171
	v_lshlrev_b32_e32 v102, 16, v172
	v_and_b32_e32 v103, 0xffff0000, v172
	v_pk_add_f32 v[88:89], v[88:89], v[100:101]
	v_pk_add_f32 v[86:87], v[86:87], v[98:99]
	v_pk_add_f32 v[98:99], v[82:83], v[102:103]
	v_mul_f32_e32 v82, v87, v87
	v_mul_f32_e32 v83, v88, v88
	v_fmac_f32_e32 v82, v86, v86
	v_fmac_f32_e32 v83, v89, v89
	v_lshlrev_b32_e32 v104, 16, v173
	v_and_b32_e32 v105, 0xffff0000, v173
	v_add_f32_e32 v82, v82, v83
	v_mul_f32_e32 v83, v98, v98
	v_pk_add_f32 v[100:101], v[84:85], v[104:105]
	v_fmac_f32_e32 v83, v99, v99
	v_add_f32_e32 v82, v83, v82
	v_mul_f32_e32 v83, v100, v100
	v_fmac_f32_e32 v83, v101, v101
	v_add_f32_e32 v82, v83, v82
	v_add_f32_e32 v102, v114, v82
	ds_bpermute_b32 v103, v225, v102
	v_lshlrev_b64 v[82:83], 12, v[210:211]
	v_lshl_add_u64 v[82:83], s[26:27], 0, v[82:83]
	v_lshl_add_u64 v[84:85], v[202:203], 2, v[82:83]
	global_store_dwordx4 v[84:85], v[94:97], off sc1
	global_store_dwordx4 v[84:85], v[90:93], off offset:16 sc1
	global_store_dwordx4 v[84:85], v[86:89], off offset:512 sc1
	global_store_dwordx4 v[84:85], v[98:101], off offset:528 sc1
	s_waitcnt lgkmcnt(0)
	v_add_f32_e32 v82, v102, v103
	ds_bpermute_b32 v83, v226, v82
	s_and_saveexec_b64 s[20:21], s[6:7]
	s_cbranch_execz .LBB0_1350
	s_waitcnt lgkmcnt(0)
	v_add_f32_e32 v82, v82, v83
	v_fma_f32 v82, v82, s59, 0.5
	v_trunc_f32_e32 v82, v82
	v_mul_f32_e32 v83, 0x2f800000, v82
	v_floor_f32_e32 v83, v83
	v_fmac_f32_e32 v82, 0xcf800000, v83
	v_cvt_u32_f32_e32 v82, v82
	v_cvt_u32_f32_e32 v83, v83
	v_lshl_add_u64 v[84:85], v[210:211], 3, s[34:35]
	global_atomic_add_x2 v[84:85], v[82:83], off
.LBB0_1350:
	s_or_b64 exec, exec, s[20:21]
	v_lshlrev_b32_e32 v82, 16, v166
	s_waitcnt lgkmcnt(0)
	v_and_b32_e32 v83, 0xffff0000, v166
	v_lshlrev_b32_e32 v84, 16, v167
	v_and_b32_e32 v85, 0xffff0000, v167
	v_pk_add_f32 v[80:81], v[80:81], v[84:85]
	v_pk_add_f32 v[78:79], v[78:79], v[82:83]
	v_lshlrev_b32_e32 v86, 16, v168
	v_and_b32_e32 v87, 0xffff0000, v168
	v_mul_f32_e32 v82, v79, v79
	v_mul_f32_e32 v83, v80, v80
	v_pk_add_f32 v[74:75], v[74:75], v[86:87]
	v_fmac_f32_e32 v82, v78, v78
	v_fmac_f32_e32 v83, v81, v81
	v_lshlrev_b32_e32 v88, 16, v169
	v_and_b32_e32 v89, 0xffff0000, v169
	v_add_f32_e32 v82, v82, v83
	v_mul_f32_e32 v83, v74, v74
	v_pk_add_f32 v[76:77], v[76:77], v[88:89]
	v_fmac_f32_e32 v83, v75, v75
	v_add_f32_e32 v82, v83, v82
	v_mul_f32_e32 v83, v76, v76
	v_fmac_f32_e32 v83, v77, v77
	v_add_f32_e32 v90, v83, v82
	v_lshlrev_b32_e32 v82, 16, v162
	v_and_b32_e32 v83, 0xffff0000, v162
	v_lshlrev_b32_e32 v84, 16, v163
	v_and_b32_e32 v85, 0xffff0000, v163
	v_lshlrev_b32_e32 v86, 16, v164
	v_and_b32_e32 v87, 0xffff0000, v164
	v_pk_add_f32 v[72:73], v[72:73], v[84:85]
	v_pk_add_f32 v[70:71], v[70:71], v[82:83]
	v_pk_add_f32 v[82:83], v[66:67], v[86:87]
	v_mul_f32_e32 v66, v71, v71
	v_mul_f32_e32 v67, v72, v72
	v_fmac_f32_e32 v66, v70, v70
	v_fmac_f32_e32 v67, v73, v73
	v_lshlrev_b32_e32 v88, 16, v165
	v_and_b32_e32 v89, 0xffff0000, v165
	v_add_f32_e32 v66, v66, v67
	v_mul_f32_e32 v67, v82, v82
	v_pk_add_f32 v[84:85], v[68:69], v[88:89]
	v_fmac_f32_e32 v67, v83, v83
	v_add_f32_e32 v66, v67, v66
	v_mul_f32_e32 v67, v84, v84
	v_fmac_f32_e32 v67, v85, v85
	v_add_f32_e32 v66, v67, v66
	v_add_f32_e32 v86, v90, v66
	ds_bpermute_b32 v87, v225, v86
	v_lshlrev_b64 v[66:67], 12, v[208:209]
	v_lshl_add_u64 v[66:67], s[26:27], 0, v[66:67]
	v_lshl_add_u64 v[68:69], v[202:203], 2, v[66:67]
	global_store_dwordx4 v[68:69], v[78:81], off sc1
	global_store_dwordx4 v[68:69], v[74:77], off offset:16 sc1
	global_store_dwordx4 v[68:69], v[70:73], off offset:512 sc1
	global_store_dwordx4 v[68:69], v[82:85], off offset:528 sc1
	s_waitcnt lgkmcnt(0)
	v_add_f32_e32 v66, v86, v87
	ds_bpermute_b32 v67, v226, v66
	s_and_saveexec_b64 s[20:21], s[6:7]
	s_cbranch_execz .LBB0_1352
	s_waitcnt lgkmcnt(0)
	v_add_f32_e32 v66, v66, v67
	v_fma_f32 v66, v66, s59, 0.5
	v_trunc_f32_e32 v66, v66
	v_mul_f32_e32 v67, 0x2f800000, v66
	v_floor_f32_e32 v67, v67
	v_fmac_f32_e32 v66, 0xcf800000, v67
	v_cvt_u32_f32_e32 v66, v66
	v_cvt_u32_f32_e32 v67, v67
	v_lshl_add_u64 v[68:69], v[208:209], 3, s[34:35]
	global_atomic_add_x2 v[68:69], v[66:67], off
.LBB0_1352:
	s_or_b64 exec, exec, s[20:21]
	v_lshlrev_b32_e32 v66, 16, v158
	s_waitcnt lgkmcnt(0)
	v_and_b32_e32 v67, 0xffff0000, v158
	v_lshlrev_b32_e32 v68, 16, v159
	v_and_b32_e32 v69, 0xffff0000, v159
	v_pk_add_f32 v[64:65], v[64:65], v[68:69]
	v_pk_add_f32 v[62:63], v[62:63], v[66:67]
	v_lshlrev_b32_e32 v70, 16, v160
	v_and_b32_e32 v71, 0xffff0000, v160
	v_mul_f32_e32 v66, v63, v63
	v_mul_f32_e32 v67, v64, v64
	v_pk_add_f32 v[58:59], v[58:59], v[70:71]
	v_fmac_f32_e32 v66, v62, v62
	v_fmac_f32_e32 v67, v65, v65
	v_lshlrev_b32_e32 v72, 16, v161
	v_and_b32_e32 v73, 0xffff0000, v161
	v_add_f32_e32 v66, v66, v67
	v_mul_f32_e32 v67, v58, v58
	v_pk_add_f32 v[60:61], v[60:61], v[72:73]
	v_fmac_f32_e32 v67, v59, v59
	v_add_f32_e32 v66, v67, v66
	v_mul_f32_e32 v67, v60, v60
	v_fmac_f32_e32 v67, v61, v61
	v_add_f32_e32 v74, v67, v66
	v_lshlrev_b32_e32 v66, 16, v154
	v_and_b32_e32 v67, 0xffff0000, v154
	v_lshlrev_b32_e32 v68, 16, v155
	v_and_b32_e32 v69, 0xffff0000, v155
	v_lshlrev_b32_e32 v70, 16, v156
	v_and_b32_e32 v71, 0xffff0000, v156
	v_pk_add_f32 v[56:57], v[56:57], v[68:69]
	v_pk_add_f32 v[54:55], v[54:55], v[66:67]
	v_pk_add_f32 v[66:67], v[50:51], v[70:71]
	v_mul_f32_e32 v50, v55, v55
	v_mul_f32_e32 v51, v56, v56
	v_fmac_f32_e32 v50, v54, v54
	v_fmac_f32_e32 v51, v57, v57
	v_lshlrev_b32_e32 v72, 16, v157
	v_and_b32_e32 v73, 0xffff0000, v157
	v_add_f32_e32 v50, v50, v51
	v_mul_f32_e32 v51, v66, v66
	v_pk_add_f32 v[68:69], v[52:53], v[72:73]
	v_fmac_f32_e32 v51, v67, v67
	v_add_f32_e32 v50, v51, v50
	v_mul_f32_e32 v51, v68, v68
	v_fmac_f32_e32 v51, v69, v69
	v_add_f32_e32 v50, v51, v50
	v_add_f32_e32 v70, v74, v50
	ds_bpermute_b32 v71, v225, v70
	v_lshlrev_b64 v[50:51], 12, v[206:207]
	v_lshl_add_u64 v[50:51], s[26:27], 0, v[50:51]
	v_lshl_add_u64 v[52:53], v[202:203], 2, v[50:51]
	global_store_dwordx4 v[52:53], v[62:65], off sc1
	global_store_dwordx4 v[52:53], v[58:61], off offset:16 sc1
	global_store_dwordx4 v[52:53], v[54:57], off offset:512 sc1
	global_store_dwordx4 v[52:53], v[66:69], off offset:528 sc1
	s_waitcnt lgkmcnt(0)
	v_add_f32_e32 v50, v70, v71
	ds_bpermute_b32 v51, v226, v50
	s_and_saveexec_b64 s[20:21], s[6:7]
	s_cbranch_execz .LBB0_1354
	s_waitcnt lgkmcnt(0)
	v_add_f32_e32 v50, v50, v51
	v_fma_f32 v50, v50, s59, 0.5
	v_trunc_f32_e32 v50, v50
	v_mul_f32_e32 v51, 0x2f800000, v50
	v_floor_f32_e32 v51, v51
	v_fmac_f32_e32 v50, 0xcf800000, v51
	v_cvt_u32_f32_e32 v50, v50
	v_cvt_u32_f32_e32 v51, v51
	v_lshl_add_u64 v[52:53], v[206:207], 3, s[34:35]
	global_atomic_add_x2 v[52:53], v[50:51], off
.LBB0_1354:
	s_or_b64 exec, exec, s[20:21]
	v_lshlrev_b32_e32 v52, 16, v150
	v_and_b32_e32 v53, 0xffff0000, v150
	v_lshlrev_b32_e32 v54, 16, v151
	v_and_b32_e32 v55, 0xffff0000, v151
	v_pk_add_f32 v[48:49], v[48:49], v[54:55]
	v_pk_add_f32 v[46:47], v[46:47], v[52:53]
	v_lshlrev_b32_e32 v56, 16, v152
	v_and_b32_e32 v57, 0xffff0000, v152
	s_waitcnt lgkmcnt(0)
	v_mul_f32_e32 v51, v47, v47
	v_mul_f32_e32 v52, v48, v48
	v_pk_add_f32 v[42:43], v[42:43], v[56:57]
	v_fmac_f32_e32 v51, v46, v46
	v_fmac_f32_e32 v52, v49, v49
	v_lshlrev_b32_e32 v58, 16, v153
	v_and_b32_e32 v59, 0xffff0000, v153
	v_add_f32_e32 v51, v51, v52
	v_mul_f32_e32 v52, v42, v42
	v_pk_add_f32 v[44:45], v[44:45], v[58:59]
	v_fmac_f32_e32 v52, v43, v43
	v_add_f32_e32 v51, v52, v51
	v_mul_f32_e32 v52, v44, v44
	v_fmac_f32_e32 v52, v45, v45
	v_add_f32_e32 v51, v52, v51
	v_lshlrev_b32_e32 v52, 16, v146
	v_and_b32_e32 v53, 0xffff0000, v146
	v_lshlrev_b32_e32 v54, 16, v147
	v_and_b32_e32 v55, 0xffff0000, v147
	v_lshlrev_b32_e32 v56, 16, v148
	v_and_b32_e32 v57, 0xffff0000, v148
	v_pk_add_f32 v[40:41], v[40:41], v[54:55]
	v_pk_add_f32 v[38:39], v[38:39], v[52:53]
	v_pk_add_f32 v[52:53], v[34:35], v[56:57]
	v_mul_f32_e32 v34, v39, v39
	v_mul_f32_e32 v35, v40, v40
	v_fmac_f32_e32 v34, v38, v38
	v_fmac_f32_e32 v35, v41, v41
	v_lshlrev_b32_e32 v58, 16, v149
	v_and_b32_e32 v59, 0xffff0000, v149
	v_add_f32_e32 v34, v34, v35
	v_mul_f32_e32 v35, v52, v52
	v_pk_add_f32 v[54:55], v[36:37], v[58:59]
	v_fmac_f32_e32 v35, v53, v53
	v_add_f32_e32 v34, v35, v34
	v_mul_f32_e32 v35, v54, v54
	v_fmac_f32_e32 v35, v55, v55
	v_add_f32_e32 v34, v35, v34
	v_add_f32_e32 v56, v51, v34
	ds_bpermute_b32 v57, v225, v56
	v_add_u32_e32 v50, 0x90, v204
	v_ashrrev_i32_e32 v51, 31, v50
	v_lshlrev_b64 v[34:35], 12, v[50:51]
	v_lshl_add_u64 v[34:35], s[26:27], 0, v[34:35]
	v_lshl_add_u64 v[36:37], v[202:203], 2, v[34:35]
	s_waitcnt lgkmcnt(0)
	v_add_f32_e32 v34, v56, v57
	ds_bpermute_b32 v35, v226, v34
	global_store_dwordx4 v[36:37], v[46:49], off sc1
	global_store_dwordx4 v[36:37], v[42:45], off offset:16 sc1
	global_store_dwordx4 v[36:37], v[38:41], off offset:512 sc1
	global_store_dwordx4 v[36:37], v[52:55], off offset:528 sc1
	s_and_saveexec_b64 s[20:21], s[6:7]
	s_cbranch_execz .LBB0_1356
	s_waitcnt lgkmcnt(0)
	v_add_f32_e32 v34, v34, v35
	v_fma_f32 v34, v34, s59, 0.5
	v_trunc_f32_e32 v34, v34
	v_mul_f32_e32 v35, 0x2f800000, v34
	v_floor_f32_e32 v35, v35
	v_fmac_f32_e32 v34, 0xcf800000, v35
	v_cvt_u32_f32_e32 v34, v34
	v_cvt_u32_f32_e32 v35, v35
	v_lshl_add_u64 v[36:37], v[50:51], 3, s[34:35]
	global_atomic_add_x2 v[36:37], v[34:35], off
.LBB0_1356:
	s_or_b64 exec, exec, s[20:21]
	v_lshlrev_b32_e32 v36, 16, v138
	v_and_b32_e32 v37, 0xffff0000, v138
	v_lshlrev_b32_e32 v38, 16, v139
	v_and_b32_e32 v39, 0xffff0000, v139
	v_pk_add_f32 v[32:33], v[32:33], v[38:39]
	v_pk_add_f32 v[30:31], v[30:31], v[36:37]
	v_lshlrev_b32_e32 v40, 16, v140
	v_and_b32_e32 v41, 0xffff0000, v140
	s_waitcnt lgkmcnt(0)
	v_mul_f32_e32 v35, v31, v31
	v_mul_f32_e32 v36, v32, v32
	v_pk_add_f32 v[26:27], v[26:27], v[40:41]
	v_fmac_f32_e32 v35, v30, v30
	v_fmac_f32_e32 v36, v33, v33
	v_lshlrev_b32_e32 v42, 16, v141
	v_and_b32_e32 v43, 0xffff0000, v141
	v_add_f32_e32 v35, v35, v36
	v_mul_f32_e32 v36, v26, v26
	v_pk_add_f32 v[28:29], v[28:29], v[42:43]
	v_fmac_f32_e32 v36, v27, v27
	v_add_f32_e32 v35, v36, v35
	v_mul_f32_e32 v36, v28, v28
	v_fmac_f32_e32 v36, v29, v29
	v_add_f32_e32 v35, v36, v35
	v_lshlrev_b32_e32 v36, 16, v126
	v_and_b32_e32 v37, 0xffff0000, v126
	v_lshlrev_b32_e32 v38, 16, v127
	v_and_b32_e32 v39, 0xffff0000, v127
	v_lshlrev_b32_e32 v40, 16, v128
	v_and_b32_e32 v41, 0xffff0000, v128
	v_pk_add_f32 v[24:25], v[24:25], v[38:39]
	v_pk_add_f32 v[22:23], v[22:23], v[36:37]
	v_pk_add_f32 v[36:37], v[18:19], v[40:41]
	v_mul_f32_e32 v18, v23, v23
	v_mul_f32_e32 v19, v24, v24
	v_fmac_f32_e32 v18, v22, v22
	v_fmac_f32_e32 v19, v25, v25
	v_lshlrev_b32_e32 v42, 16, v129
	v_and_b32_e32 v43, 0xffff0000, v129
	v_add_f32_e32 v18, v18, v19
	v_mul_f32_e32 v19, v36, v36
	v_pk_add_f32 v[38:39], v[20:21], v[42:43]
	v_fmac_f32_e32 v19, v37, v37
	v_add_f32_e32 v18, v19, v18
	v_mul_f32_e32 v19, v38, v38
	v_fmac_f32_e32 v19, v39, v39
	v_add_f32_e32 v18, v19, v18
	v_add_f32_e32 v40, v35, v18
	ds_bpermute_b32 v41, v225, v40
	v_add_u32_e32 v34, 0xa0, v204
	v_ashrrev_i32_e32 v35, 31, v34
	v_lshlrev_b64 v[18:19], 12, v[34:35]
	v_lshl_add_u64 v[18:19], s[26:27], 0, v[18:19]
	v_lshl_add_u64 v[20:21], v[202:203], 2, v[18:19]
	s_waitcnt lgkmcnt(0)
	v_add_f32_e32 v18, v40, v41
	ds_bpermute_b32 v19, v226, v18
	global_store_dwordx4 v[20:21], v[30:33], off sc1
	global_store_dwordx4 v[20:21], v[26:29], off offset:16 sc1
	global_store_dwordx4 v[20:21], v[22:25], off offset:512 sc1
	global_store_dwordx4 v[20:21], v[36:39], off offset:528 sc1
	s_and_saveexec_b64 s[20:21], s[6:7]
	s_cbranch_execz .LBB0_1358
	s_waitcnt lgkmcnt(0)
	v_add_f32_e32 v18, v18, v19
	v_fma_f32 v18, v18, s59, 0.5
	v_trunc_f32_e32 v18, v18
	v_mul_f32_e32 v19, 0x2f800000, v18
	v_floor_f32_e32 v19, v19
	v_fmac_f32_e32 v18, 0xcf800000, v19
	v_cvt_u32_f32_e32 v18, v18
	v_cvt_u32_f32_e32 v19, v19
	v_lshl_add_u64 v[20:21], v[34:35], 3, s[34:35]
	global_atomic_add_x2 v[20:21], v[18:19], off
.LBB0_1358:
	s_or_b64 exec, exec, s[20:21]
	v_lshlrev_b32_e32 v20, 16, v110
	v_and_b32_e32 v21, 0xffff0000, v110
	v_lshlrev_b32_e32 v22, 16, v111
	v_and_b32_e32 v23, 0xffff0000, v111
	v_pk_add_f32 v[16:17], v[16:17], v[22:23]
	v_pk_add_f32 v[14:15], v[14:15], v[20:21]
	v_lshlrev_b32_e32 v24, 16, v112
	v_and_b32_e32 v25, 0xffff0000, v112
	s_waitcnt lgkmcnt(0)
	v_mul_f32_e32 v19, v15, v15
	v_mul_f32_e32 v20, v16, v16
	v_pk_add_f32 v[10:11], v[10:11], v[24:25]
	v_fmac_f32_e32 v19, v14, v14
	v_fmac_f32_e32 v20, v17, v17
	v_lshlrev_b32_e32 v26, 16, v113
	v_and_b32_e32 v27, 0xffff0000, v113
	v_add_f32_e32 v19, v19, v20
	v_mul_f32_e32 v20, v10, v10
	v_pk_add_f32 v[12:13], v[12:13], v[26:27]
	v_fmac_f32_e32 v20, v11, v11
	v_add_f32_e32 v19, v20, v19
	v_mul_f32_e32 v20, v12, v12
	v_fmac_f32_e32 v20, v13, v13
	v_add_f32_e32 v19, v20, v19
	v_lshlrev_b32_e32 v20, 16, v106
	v_and_b32_e32 v21, 0xffff0000, v106
	v_lshlrev_b32_e32 v22, 16, v107
	v_and_b32_e32 v23, 0xffff0000, v107
	v_lshlrev_b32_e32 v24, 16, v108
	v_and_b32_e32 v25, 0xffff0000, v108
	v_pk_add_f32 v[8:9], v[8:9], v[22:23]
	v_pk_add_f32 v[6:7], v[6:7], v[20:21]
	v_pk_add_f32 v[20:21], v[2:3], v[24:25]
	v_mul_f32_e32 v2, v7, v7
	v_mul_f32_e32 v3, v8, v8
	v_fmac_f32_e32 v2, v6, v6
	v_fmac_f32_e32 v3, v9, v9
	v_lshlrev_b32_e32 v26, 16, v109
	v_and_b32_e32 v27, 0xffff0000, v109
	v_add_f32_e32 v2, v2, v3
	v_mul_f32_e32 v3, v20, v20
	v_pk_add_f32 v[22:23], v[4:5], v[26:27]
	v_fmac_f32_e32 v3, v21, v21
	v_add_f32_e32 v2, v3, v2
	v_mul_f32_e32 v3, v22, v22
	v_fmac_f32_e32 v3, v23, v23
	v_add_f32_e32 v2, v3, v2
	v_add_f32_e32 v24, v19, v2
	ds_bpermute_b32 v25, v225, v24
	v_add_u32_e32 v18, 0xb0, v204
	v_ashrrev_i32_e32 v19, 31, v18
	v_lshlrev_b64 v[2:3], 12, v[18:19]
	v_lshl_add_u64 v[2:3], s[26:27], 0, v[2:3]
	v_lshl_add_u64 v[4:5], v[202:203], 2, v[2:3]
	s_waitcnt lgkmcnt(0)
	v_add_f32_e32 v2, v24, v25
	ds_bpermute_b32 v3, v226, v2
	global_store_dwordx4 v[4:5], v[14:17], off sc1
	global_store_dwordx4 v[4:5], v[10:13], off offset:16 sc1
	global_store_dwordx4 v[4:5], v[6:9], off offset:512 sc1
	global_store_dwordx4 v[4:5], v[20:23], off offset:528 sc1
	s_and_saveexec_b64 s[20:21], s[6:7]
	s_cbranch_execz .LBB0_1360
	s_waitcnt lgkmcnt(0)
	v_add_f32_e32 v2, v2, v3
	v_fma_f32 v2, v2, s59, 0.5
	v_trunc_f32_e32 v2, v2
	v_mul_f32_e32 v3, 0x2f800000, v2
	v_floor_f32_e32 v3, v3
	v_fmac_f32_e32 v2, 0xcf800000, v3
	v_cvt_u32_f32_e32 v2, v2
	v_cvt_u32_f32_e32 v3, v3
	v_lshl_add_u64 v[4:5], v[18:19], 3, s[34:35]
	global_atomic_add_x2 v[4:5], v[2:3], off
